# attn loop resched (K reads batched, DMA in PV, max3 tree) + pooling pass rewritten: all rows loaded up front per 16-token run
# speedup vs baseline: 1.0158x; 1.0081x over previous
; __global__ void __launch_bounds__(512, 2) fwd_mega(Args a) {
;     ...
;         for (int item = bx * 512 + tid; item < NBATCH * 64 * 64; item += G * 512) {
;             const int c8 = item & 63, seg = (item >> 6) & 63, bb = item >> 12;
;             const int ch = c8 * 8, hw = 1 << (ch >> 7);
;             const bf16* base = UB + (size_t)bb * SEQ * 512 + ch;
;             bf16* obase = XB + (size_t)bb * SEQ * 1024 + 512 + ch;
;             const int s0 = seg * 32;
;             f32x4 w0 = {0.f, 0.f, 0.f, 0.f}, w1 = {0.f, 0.f, 0.f, 0.f};
;             { const int jlo = (s0 - hw) > 0 ? (s0 - hw) : 0, jhi = (s0 + hw) < SEQ ? (s0 + hw) : SEQ;
;               for (int j = jlo; j < jhi; ++j) { f32x4 a0, a1; pg8::unpack8(*(const u32x4*)(base + (size_t)j * 512), a0, a1); w0 += a0; w1 += a1; } }
;     ...
;                 if (s + hw < SEQ) { f32x4 a0, a1; pg8::unpack8(*(const u32x4*)(base + (size_t)(s + hw) * 512), a0, a1); w0 += a0; w1 += a1; }
;                 if (s - hw >= 0) { f32x4 a0, a1; pg8::unpack8(*(const u32x4*)(base + (size_t)(s - hw) * 512), a0, a1); w0 -= a0; w1 -= a1; }
.LBB0_502:
	s_cmp_lt_i32 s68, 6
	s_cselect_b64 s[20:21], -1, 0
	s_and_b64 s[0:1], s[20:21], s[0:1]
	s_andn2_b64 vcc, exec, s[0:1]
	s_cbranch_vccnz .LBB0_579
	v_readfirstlane_b32 s44, v156
	s_mov_b64 s[22:23], exec
	s_movk_i32 s56, 0x800
	s_lshr_b32 s44, s44, 6
	s_lshl_b32 s45, s2, 3
	s_add_i32 s44, s44, s45
	s_mov_b32 s46, s44
	v_lshrrev_b32_e32 v170, 4, v203
	v_and_b32_e32 v171, 15, v203
	v_lshlrev_b32_e32 v172, 4, v171
	v_lshl_add_u32 v160, v170, 14, v172
	v_add_u32_e32 v161, 0x1000, v160
	v_add_u32_e32 v162, 0x2000, v160
	v_add_u32_e32 v163, 0x3000, v160
	v_add_u32_e32 v164, 0x4000, v160
	v_add_u32_e32 v165, 0x5000, v160
	v_add_u32_e32 v166, 0x6000, v160
	v_add_u32_e32 v167, 0x7000, v160
	v_lshl_add_u32 v176, v170, 15, v172
	v_lshlrev_b32_e32 v177, 4, v170
.Lpool_item:
	s_lshr_b32 s48, s46, 11
	s_lshl_b32 s48, s48, 1
	s_add_i32 s47, s46, s48
	s_and_b32 s47, s47, 3
	s_lshr_b32 s48, s46, 2
	s_lshl_b32 s49, s48, 6
	s_and_b32 s50, s49, 0x7ff
	v_mov_b32_e32 v168, v176
	v_add_u32_e32 v169, s50, v177
	s_cmp_eq_u32 s47, 0
	s_cbranch_scc1 .Lpool_g0
	s_cmp_eq_u32 s47, 1
	s_cbranch_scc1 .Lpool_g1
	s_cmp_eq_u32 s47, 2
	s_cbranch_scc1 .Lpool_g2
	s_branch .Lpool_g3
.Lpool_g0:
	s_sub_i32 s52, s49, 1
	s_ashr_i32 s53, s52, 31
	s_lshl_b64 s[52:53], s[52:53], 10
	s_add_u32 s52, s52, s8
	s_addc_u32 s53, s53, s9
	s_add_u32 s52, s52, 0
	s_addc_u32 s53, s53, 0
	s_lshl_b32 s54, s49, 11
	s_add_u32 s54, s54, 0x3000400
	s_add_u32 s54, s30, s54
	s_addc_u32 s55, s31, 0
	global_load_dwordx4 v[0:3], v160, s[52:53] offset:0
	global_load_dwordx4 v[4:7], v160, s[52:53] offset:1024
	global_load_dwordx4 v[8:11], v160, s[52:53] offset:2048
	global_load_dwordx4 v[12:15], v160, s[52:53] offset:3072
	global_load_dwordx4 v[16:19], v161, s[52:53] offset:0
	global_load_dwordx4 v[20:23], v161, s[52:53] offset:1024
	global_load_dwordx4 v[24:27], v161, s[52:53] offset:2048
	global_load_dwordx4 v[28:31], v161, s[52:53] offset:3072
	global_load_dwordx4 v[32:35], v162, s[52:53] offset:0
	global_load_dwordx4 v[36:39], v162, s[52:53] offset:1024
	global_load_dwordx4 v[40:43], v162, s[52:53] offset:2048
	global_load_dwordx4 v[44:47], v162, s[52:53] offset:3072
	global_load_dwordx4 v[48:51], v163, s[52:53] offset:0
	global_load_dwordx4 v[52:55], v163, s[52:53] offset:1024
	global_load_dwordx4 v[56:59], v163, s[52:53] offset:2048
	global_load_dwordx4 v[60:63], v163, s[52:53] offset:3072
	global_load_dwordx4 v[64:67], v164, s[52:53] offset:0
	s_waitcnt vmcnt(0)
	s_cmp_eq_u32 s50, 0
	s_cbranch_scc1 .Lpool_g0_mask
	s_cmpk_eq_i32 s50, 0x7c0
	s_cbranch_scc0 .Lpool_g0_nomask
.Lpool_g0_mask:
	v_add_u32_e32 v170, -1, v169
	v_cmp_gt_u32_e32 vcc, s56, v170
	s_nop 1
	v_cndmask_b32_e32 v0, 0, v0, vcc
	v_cndmask_b32_e32 v1, 0, v1, vcc
	v_cndmask_b32_e32 v2, 0, v2, vcc
	v_cndmask_b32_e32 v3, 0, v3, vcc
	v_add_u32_e32 v170, 0, v169
	v_cmp_gt_u32_e32 vcc, s56, v170
	s_nop 1
	v_cndmask_b32_e32 v4, 0, v4, vcc
	v_cndmask_b32_e32 v5, 0, v5, vcc
	v_cndmask_b32_e32 v6, 0, v6, vcc
	v_cndmask_b32_e32 v7, 0, v7, vcc
	v_add_u32_e32 v170, 1, v169
	v_cmp_gt_u32_e32 vcc, s56, v170
	s_nop 1
	v_cndmask_b32_e32 v8, 0, v8, vcc
	v_cndmask_b32_e32 v9, 0, v9, vcc
	v_cndmask_b32_e32 v10, 0, v10, vcc
	v_cndmask_b32_e32 v11, 0, v11, vcc
	v_add_u32_e32 v170, 2, v169
	v_cmp_gt_u32_e32 vcc, s56, v170
	s_nop 1
	v_cndmask_b32_e32 v12, 0, v12, vcc
	v_cndmask_b32_e32 v13, 0, v13, vcc
	v_cndmask_b32_e32 v14, 0, v14, vcc
	v_cndmask_b32_e32 v15, 0, v15, vcc
	v_add_u32_e32 v170, 3, v169
	v_cmp_gt_u32_e32 vcc, s56, v170
	s_nop 1
	v_cndmask_b32_e32 v16, 0, v16, vcc
	v_cndmask_b32_e32 v17, 0, v17, vcc
	v_cndmask_b32_e32 v18, 0, v18, vcc
	v_cndmask_b32_e32 v19, 0, v19, vcc
	v_add_u32_e32 v170, 4, v169
	v_cmp_gt_u32_e32 vcc, s56, v170
	s_nop 1
	v_cndmask_b32_e32 v20, 0, v20, vcc
	v_cndmask_b32_e32 v21, 0, v21, vcc
	v_cndmask_b32_e32 v22, 0, v22, vcc
	v_cndmask_b32_e32 v23, 0, v23, vcc
	v_add_u32_e32 v170, 5, v169
	v_cmp_gt_u32_e32 vcc, s56, v170
	s_nop 1
	v_cndmask_b32_e32 v24, 0, v24, vcc
	v_cndmask_b32_e32 v25, 0, v25, vcc
	v_cndmask_b32_e32 v26, 0, v26, vcc
	v_cndmask_b32_e32 v27, 0, v27, vcc
	v_add_u32_e32 v170, 6, v169
	v_cmp_gt_u32_e32 vcc, s56, v170
	s_nop 1
	v_cndmask_b32_e32 v28, 0, v28, vcc
	v_cndmask_b32_e32 v29, 0, v29, vcc
	v_cndmask_b32_e32 v30, 0, v30, vcc
	v_cndmask_b32_e32 v31, 0, v31, vcc
	v_add_u32_e32 v170, 7, v169
	v_cmp_gt_u32_e32 vcc, s56, v170
	s_nop 1
	v_cndmask_b32_e32 v32, 0, v32, vcc
	v_cndmask_b32_e32 v33, 0, v33, vcc
	v_cndmask_b32_e32 v34, 0, v34, vcc
	v_cndmask_b32_e32 v35, 0, v35, vcc
	v_add_u32_e32 v170, 8, v169
	v_cmp_gt_u32_e32 vcc, s56, v170
	s_nop 1
	v_cndmask_b32_e32 v36, 0, v36, vcc
	v_cndmask_b32_e32 v37, 0, v37, vcc
	v_cndmask_b32_e32 v38, 0, v38, vcc
	v_cndmask_b32_e32 v39, 0, v39, vcc
	v_add_u32_e32 v170, 9, v169
	v_cmp_gt_u32_e32 vcc, s56, v170
	s_nop 1
	v_cndmask_b32_e32 v40, 0, v40, vcc
	v_cndmask_b32_e32 v41, 0, v41, vcc
	v_cndmask_b32_e32 v42, 0, v42, vcc
	v_cndmask_b32_e32 v43, 0, v43, vcc
	v_add_u32_e32 v170, 10, v169
	v_cmp_gt_u32_e32 vcc, s56, v170
	s_nop 1
	v_cndmask_b32_e32 v44, 0, v44, vcc
	v_cndmask_b32_e32 v45, 0, v45, vcc
	v_cndmask_b32_e32 v46, 0, v46, vcc
	v_cndmask_b32_e32 v47, 0, v47, vcc
	v_add_u32_e32 v170, 11, v169
	v_cmp_gt_u32_e32 vcc, s56, v170
	s_nop 1
	v_cndmask_b32_e32 v48, 0, v48, vcc
	v_cndmask_b32_e32 v49, 0, v49, vcc
	v_cndmask_b32_e32 v50, 0, v50, vcc
	v_cndmask_b32_e32 v51, 0, v51, vcc
	v_add_u32_e32 v170, 12, v169
	v_cmp_gt_u32_e32 vcc, s56, v170
	s_nop 1
	v_cndmask_b32_e32 v52, 0, v52, vcc
	v_cndmask_b32_e32 v53, 0, v53, vcc
	v_cndmask_b32_e32 v54, 0, v54, vcc
	v_cndmask_b32_e32 v55, 0, v55, vcc
	v_add_u32_e32 v170, 13, v169
	v_cmp_gt_u32_e32 vcc, s56, v170
	s_nop 1
	v_cndmask_b32_e32 v56, 0, v56, vcc
	v_cndmask_b32_e32 v57, 0, v57, vcc
	v_cndmask_b32_e32 v58, 0, v58, vcc
	v_cndmask_b32_e32 v59, 0, v59, vcc
	v_add_u32_e32 v170, 14, v169
	v_cmp_gt_u32_e32 vcc, s56, v170
	s_nop 1
	v_cndmask_b32_e32 v60, 0, v60, vcc
	v_cndmask_b32_e32 v61, 0, v61, vcc
	v_cndmask_b32_e32 v62, 0, v62, vcc
	v_cndmask_b32_e32 v63, 0, v63, vcc
	v_add_u32_e32 v170, 15, v169
	v_cmp_gt_u32_e32 vcc, s56, v170
	s_nop 1
	v_cndmask_b32_e32 v64, 0, v64, vcc
	v_cndmask_b32_e32 v65, 0, v65, vcc
	v_cndmask_b32_e32 v66, 0, v66, vcc
	v_cndmask_b32_e32 v67, 0, v67, vcc
; __device__ __forceinline__ u32x4 pack8(const f32x4 a, const f32x4 b) { u32x4 w; w.x = cvt_pk_bf16(a[0], a[1]); w.y = cvt_pk_bf16(a[2], a[3]); w.z = cvt_pk_bf16(b[0], b[1]); w.w = cvt_pk_bf16(b[2], b[3]); return w; }
; __global__ void __launch_bounds__(512, 2) fwd_mega(Args a) {
;     ...
;             for (int s = s0; s < s0 + 32; ++s) {
;                 f32x4 u0, u1; pg8::unpack8(*(const u32x4*)(base + (size_t)s * 512), u0, u1);
;                 const int jlo = (s - hw) > 0 ? (s - hw) : 0, jhi = (s + hw) < SEQ ? (s + hw) : SEQ;
;                 const float rc = 1.0f / (float)(jhi - jlo);
;                 *(u32x4*)(obase + (size_t)s * 1024) = pg8::pack8(w0 * rc - u0, w1 * rc - u1);
;                 if (s + hw < SEQ) { f32x4 a0, a1; pg8::unpack8(*(const u32x4*)(base + (size_t)(s + hw) * 512), a0, a1); w0 += a0; w1 += a1; }
;                 if (s - hw >= 0) { f32x4 a0, a1; pg8::unpack8(*(const u32x4*)(base + (size_t)(s - hw) * 512), a0, a1); w0 -= a0; w1 -= a1; }
.Lpool_g0_nomask:
	v_lshlrev_b32_e32 v124, 16, v0
	v_and_b32_e32 v125, 0xffff0000, v0
	v_lshlrev_b32_e32 v126, 16, v1
	v_and_b32_e32 v127, 0xffff0000, v1
	v_lshlrev_b32_e32 v128, 16, v2
	v_and_b32_e32 v129, 0xffff0000, v2
	v_lshlrev_b32_e32 v130, 16, v3
	v_and_b32_e32 v131, 0xffff0000, v3
	v_lshlrev_b32_e32 v132, 16, v4
	v_and_b32_e32 v133, 0xffff0000, v4
	v_lshlrev_b32_e32 v134, 16, v5
	v_and_b32_e32 v135, 0xffff0000, v5
	v_lshlrev_b32_e32 v136, 16, v6
	v_and_b32_e32 v137, 0xffff0000, v6
	v_lshlrev_b32_e32 v138, 16, v7
	v_and_b32_e32 v139, 0xffff0000, v7
	v_pk_add_f32 v[124:125], v[124:125], v[132:133]
	v_pk_add_f32 v[126:127], v[126:127], v[134:135]
	v_pk_add_f32 v[128:129], v[128:129], v[136:137]
	v_pk_add_f32 v[130:131], v[130:131], v[138:139]
	v_add_u32_e32 v170, 1, v169
	v_min_u32_e32 v170, s56, v170
	v_add_u32_e32 v171, -1, v169
	v_max_i32_e32 v171, 0, v171
	v_sub_u32_e32 v170, v170, v171
	v_cvt_f32_u32_e32 v170, v170
	v_rcp_f32_e32 v174, v170
	v_lshlrev_b32_e32 v132, 16, v4
	v_and_b32_e32 v133, 0xffff0000, v4
	v_lshlrev_b32_e32 v134, 16, v5
	v_and_b32_e32 v135, 0xffff0000, v5
	v_lshlrev_b32_e32 v136, 16, v6
	v_and_b32_e32 v137, 0xffff0000, v6
	v_lshlrev_b32_e32 v138, 16, v7
	v_and_b32_e32 v139, 0xffff0000, v7
	v_pk_fma_f32 v[140:141], v[124:125], v[174:175], v[132:133] op_sel_hi:[1,0,1] neg_lo:[0,0,1] neg_hi:[0,0,1]
	v_pk_fma_f32 v[142:143], v[126:127], v[174:175], v[134:135] op_sel_hi:[1,0,1] neg_lo:[0,0,1] neg_hi:[0,0,1]
	v_pk_fma_f32 v[144:145], v[128:129], v[174:175], v[136:137] op_sel_hi:[1,0,1] neg_lo:[0,0,1] neg_hi:[0,0,1]
	v_pk_fma_f32 v[146:147], v[130:131], v[174:175], v[138:139] op_sel_hi:[1,0,1] neg_lo:[0,0,1] neg_hi:[0,0,1]
	v_cvt_pk_bf16_f32 v148, v140, v141
	v_cvt_pk_bf16_f32 v149, v142, v143
	v_cvt_pk_bf16_f32 v150, v144, v145
	v_cvt_pk_bf16_f32 v151, v146, v147
	global_store_dwordx4 v168, v[148:151], s[54:55]
	v_add_u32_e32 v168, 0x800, v168
	v_lshlrev_b32_e32 v132, 16, v8
	v_and_b32_e32 v133, 0xffff0000, v8
	v_lshlrev_b32_e32 v134, 16, v9
	v_and_b32_e32 v135, 0xffff0000, v9
	v_lshlrev_b32_e32 v136, 16, v10
	v_and_b32_e32 v137, 0xffff0000, v10
	v_lshlrev_b32_e32 v138, 16, v11
	v_and_b32_e32 v139, 0xffff0000, v11
	v_lshlrev_b32_e32 v140, 16, v0
	v_and_b32_e32 v141, 0xffff0000, v0
	v_lshlrev_b32_e32 v142, 16, v1
	v_and_b32_e32 v143, 0xffff0000, v1
	v_lshlrev_b32_e32 v144, 16, v2
	v_and_b32_e32 v145, 0xffff0000, v2
	v_lshlrev_b32_e32 v146, 16, v3
	v_and_b32_e32 v147, 0xffff0000, v3
	v_pk_add_f32 v[124:125], v[124:125], v[132:133]
	v_pk_add_f32 v[126:127], v[126:127], v[134:135]
	v_pk_add_f32 v[128:129], v[128:129], v[136:137]
	v_pk_add_f32 v[130:131], v[130:131], v[138:139]
	v_pk_add_f32 v[124:125], v[124:125], v[140:141] neg_lo:[0,1] neg_hi:[0,1]
	v_pk_add_f32 v[126:127], v[126:127], v[142:143] neg_lo:[0,1] neg_hi:[0,1]
	v_pk_add_f32 v[128:129], v[128:129], v[144:145] neg_lo:[0,1] neg_hi:[0,1]
	v_pk_add_f32 v[130:131], v[130:131], v[146:147] neg_lo:[0,1] neg_hi:[0,1]
	v_add_u32_e32 v170, 2, v169
	v_min_u32_e32 v170, s56, v170
	v_add_u32_e32 v171, 0, v169
	v_max_i32_e32 v171, 0, v171
	v_sub_u32_e32 v170, v170, v171
	v_cvt_f32_u32_e32 v170, v170
	v_rcp_f32_e32 v174, v170
	v_lshlrev_b32_e32 v132, 16, v8
	v_and_b32_e32 v133, 0xffff0000, v8
	v_lshlrev_b32_e32 v134, 16, v9
	v_and_b32_e32 v135, 0xffff0000, v9
	v_lshlrev_b32_e32 v136, 16, v10
	v_and_b32_e32 v137, 0xffff0000, v10
	v_lshlrev_b32_e32 v138, 16, v11
	v_and_b32_e32 v139, 0xffff0000, v11
	v_pk_fma_f32 v[140:141], v[124:125], v[174:175], v[132:133] op_sel_hi:[1,0,1] neg_lo:[0,0,1] neg_hi:[0,0,1]
	v_pk_fma_f32 v[142:143], v[126:127], v[174:175], v[134:135] op_sel_hi:[1,0,1] neg_lo:[0,0,1] neg_hi:[0,0,1]
	v_pk_fma_f32 v[144:145], v[128:129], v[174:175], v[136:137] op_sel_hi:[1,0,1] neg_lo:[0,0,1] neg_hi:[0,0,1]
	v_pk_fma_f32 v[146:147], v[130:131], v[174:175], v[138:139] op_sel_hi:[1,0,1] neg_lo:[0,0,1] neg_hi:[0,0,1]
	v_cvt_pk_bf16_f32 v148, v140, v141
	v_cvt_pk_bf16_f32 v149, v142, v143
	v_cvt_pk_bf16_f32 v150, v144, v145
	v_cvt_pk_bf16_f32 v151, v146, v147
	global_store_dwordx4 v168, v[148:151], s[54:55]
	v_add_u32_e32 v168, 0x800, v168
	v_lshlrev_b32_e32 v132, 16, v12
	v_and_b32_e32 v133, 0xffff0000, v12
	v_lshlrev_b32_e32 v134, 16, v13
	v_and_b32_e32 v135, 0xffff0000, v13
	v_lshlrev_b32_e32 v136, 16, v14
	v_and_b32_e32 v137, 0xffff0000, v14
	v_lshlrev_b32_e32 v138, 16, v15
	v_and_b32_e32 v139, 0xffff0000, v15
	v_lshlrev_b32_e32 v140, 16, v4
	v_and_b32_e32 v141, 0xffff0000, v4
	v_lshlrev_b32_e32 v142, 16, v5
	v_and_b32_e32 v143, 0xffff0000, v5
	v_lshlrev_b32_e32 v144, 16, v6
	v_and_b32_e32 v145, 0xffff0000, v6
	v_lshlrev_b32_e32 v146, 16, v7
	v_and_b32_e32 v147, 0xffff0000, v7
	v_pk_add_f32 v[124:125], v[124:125], v[132:133]
	v_pk_add_f32 v[126:127], v[126:127], v[134:135]
	v_pk_add_f32 v[128:129], v[128:129], v[136:137]
	v_pk_add_f32 v[130:131], v[130:131], v[138:139]
	v_pk_add_f32 v[124:125], v[124:125], v[140:141] neg_lo:[0,1] neg_hi:[0,1]
	v_pk_add_f32 v[126:127], v[126:127], v[142:143] neg_lo:[0,1] neg_hi:[0,1]
	v_pk_add_f32 v[128:129], v[128:129], v[144:145] neg_lo:[0,1] neg_hi:[0,1]
	v_pk_add_f32 v[130:131], v[130:131], v[146:147] neg_lo:[0,1] neg_hi:[0,1]
	v_add_u32_e32 v170, 3, v169
	v_min_u32_e32 v170, s56, v170
	v_add_u32_e32 v171, 1, v169
	v_max_i32_e32 v171, 0, v171
	v_sub_u32_e32 v170, v170, v171
	v_cvt_f32_u32_e32 v170, v170
	v_rcp_f32_e32 v174, v170
	v_lshlrev_b32_e32 v132, 16, v12
	v_and_b32_e32 v133, 0xffff0000, v12
	v_lshlrev_b32_e32 v134, 16, v13
	v_and_b32_e32 v135, 0xffff0000, v13
	v_lshlrev_b32_e32 v136, 16, v14
	v_and_b32_e32 v137, 0xffff0000, v14
	v_lshlrev_b32_e32 v138, 16, v15
	v_and_b32_e32 v139, 0xffff0000, v15
; __device__ __forceinline__ u32x4 pack8(const f32x4 a, const f32x4 b) { u32x4 w; w.x = cvt_pk_bf16(a[0], a[1]); w.y = cvt_pk_bf16(a[2], a[3]); w.z = cvt_pk_bf16(b[0], b[1]); w.w = cvt_pk_bf16(b[2], b[3]); return w; }
; __global__ void __launch_bounds__(512, 2) fwd_mega(Args a) {
;     ...
;             for (int s = s0; s < s0 + 32; ++s) {
;                 f32x4 u0, u1; pg8::unpack8(*(const u32x4*)(base + (size_t)s * 512), u0, u1);
;                 const int jlo = (s - hw) > 0 ? (s - hw) : 0, jhi = (s + hw) < SEQ ? (s + hw) : SEQ;
;                 const float rc = 1.0f / (float)(jhi - jlo);
;                 *(u32x4*)(obase + (size_t)s * 1024) = pg8::pack8(w0 * rc - u0, w1 * rc - u1);
;                 if (s + hw < SEQ) { f32x4 a0, a1; pg8::unpack8(*(const u32x4*)(base + (size_t)(s + hw) * 512), a0, a1); w0 += a0; w1 += a1; }
;                 if (s - hw >= 0) { f32x4 a0, a1; pg8::unpack8(*(const u32x4*)(base + (size_t)(s - hw) * 512), a0, a1); w0 -= a0; w1 -= a1; }
	v_pk_fma_f32 v[140:141], v[124:125], v[174:175], v[132:133] op_sel_hi:[1,0,1] neg_lo:[0,0,1] neg_hi:[0,0,1]
	v_pk_fma_f32 v[142:143], v[126:127], v[174:175], v[134:135] op_sel_hi:[1,0,1] neg_lo:[0,0,1] neg_hi:[0,0,1]
	v_pk_fma_f32 v[144:145], v[128:129], v[174:175], v[136:137] op_sel_hi:[1,0,1] neg_lo:[0,0,1] neg_hi:[0,0,1]
	v_pk_fma_f32 v[146:147], v[130:131], v[174:175], v[138:139] op_sel_hi:[1,0,1] neg_lo:[0,0,1] neg_hi:[0,0,1]
	v_cvt_pk_bf16_f32 v148, v140, v141
	v_cvt_pk_bf16_f32 v149, v142, v143
	v_cvt_pk_bf16_f32 v150, v144, v145
	v_cvt_pk_bf16_f32 v151, v146, v147
	global_store_dwordx4 v168, v[148:151], s[54:55]
	v_add_u32_e32 v168, 0x800, v168
	v_lshlrev_b32_e32 v132, 16, v16
	v_and_b32_e32 v133, 0xffff0000, v16
	v_lshlrev_b32_e32 v134, 16, v17
	v_and_b32_e32 v135, 0xffff0000, v17
	v_lshlrev_b32_e32 v136, 16, v18
	v_and_b32_e32 v137, 0xffff0000, v18
	v_lshlrev_b32_e32 v138, 16, v19
	v_and_b32_e32 v139, 0xffff0000, v19
	v_lshlrev_b32_e32 v140, 16, v8
	v_and_b32_e32 v141, 0xffff0000, v8
	v_lshlrev_b32_e32 v142, 16, v9
	v_and_b32_e32 v143, 0xffff0000, v9
	v_lshlrev_b32_e32 v144, 16, v10
	v_and_b32_e32 v145, 0xffff0000, v10
	v_lshlrev_b32_e32 v146, 16, v11
	v_and_b32_e32 v147, 0xffff0000, v11
	v_pk_add_f32 v[124:125], v[124:125], v[132:133]
	v_pk_add_f32 v[126:127], v[126:127], v[134:135]
	v_pk_add_f32 v[128:129], v[128:129], v[136:137]
	v_pk_add_f32 v[130:131], v[130:131], v[138:139]
	v_pk_add_f32 v[124:125], v[124:125], v[140:141] neg_lo:[0,1] neg_hi:[0,1]
	v_pk_add_f32 v[126:127], v[126:127], v[142:143] neg_lo:[0,1] neg_hi:[0,1]
	v_pk_add_f32 v[128:129], v[128:129], v[144:145] neg_lo:[0,1] neg_hi:[0,1]
	v_pk_add_f32 v[130:131], v[130:131], v[146:147] neg_lo:[0,1] neg_hi:[0,1]
	v_add_u32_e32 v170, 4, v169
	v_min_u32_e32 v170, s56, v170
	v_add_u32_e32 v171, 2, v169
	v_max_i32_e32 v171, 0, v171
	v_sub_u32_e32 v170, v170, v171
	v_cvt_f32_u32_e32 v170, v170
	v_rcp_f32_e32 v174, v170
	v_lshlrev_b32_e32 v132, 16, v16
	v_and_b32_e32 v133, 0xffff0000, v16
	v_lshlrev_b32_e32 v134, 16, v17
	v_and_b32_e32 v135, 0xffff0000, v17
	v_lshlrev_b32_e32 v136, 16, v18
	v_and_b32_e32 v137, 0xffff0000, v18
	v_lshlrev_b32_e32 v138, 16, v19
	v_and_b32_e32 v139, 0xffff0000, v19
	v_pk_fma_f32 v[140:141], v[124:125], v[174:175], v[132:133] op_sel_hi:[1,0,1] neg_lo:[0,0,1] neg_hi:[0,0,1]
	v_pk_fma_f32 v[142:143], v[126:127], v[174:175], v[134:135] op_sel_hi:[1,0,1] neg_lo:[0,0,1] neg_hi:[0,0,1]
	v_pk_fma_f32 v[144:145], v[128:129], v[174:175], v[136:137] op_sel_hi:[1,0,1] neg_lo:[0,0,1] neg_hi:[0,0,1]
	v_pk_fma_f32 v[146:147], v[130:131], v[174:175], v[138:139] op_sel_hi:[1,0,1] neg_lo:[0,0,1] neg_hi:[0,0,1]
	v_cvt_pk_bf16_f32 v148, v140, v141
	v_cvt_pk_bf16_f32 v149, v142, v143
	v_cvt_pk_bf16_f32 v150, v144, v145
	v_cvt_pk_bf16_f32 v151, v146, v147
	global_store_dwordx4 v168, v[148:151], s[54:55]
	v_add_u32_e32 v168, 0x800, v168
	v_lshlrev_b32_e32 v132, 16, v20
	v_and_b32_e32 v133, 0xffff0000, v20
	v_lshlrev_b32_e32 v134, 16, v21
	v_and_b32_e32 v135, 0xffff0000, v21
	v_lshlrev_b32_e32 v136, 16, v22
	v_and_b32_e32 v137, 0xffff0000, v22
	v_lshlrev_b32_e32 v138, 16, v23
	v_and_b32_e32 v139, 0xffff0000, v23
	v_lshlrev_b32_e32 v140, 16, v12
	v_and_b32_e32 v141, 0xffff0000, v12
	v_lshlrev_b32_e32 v142, 16, v13
	v_and_b32_e32 v143, 0xffff0000, v13
	v_lshlrev_b32_e32 v144, 16, v14
	v_and_b32_e32 v145, 0xffff0000, v14
	v_lshlrev_b32_e32 v146, 16, v15
	v_and_b32_e32 v147, 0xffff0000, v15
	v_pk_add_f32 v[124:125], v[124:125], v[132:133]
	v_pk_add_f32 v[126:127], v[126:127], v[134:135]
	v_pk_add_f32 v[128:129], v[128:129], v[136:137]
	v_pk_add_f32 v[130:131], v[130:131], v[138:139]
	v_pk_add_f32 v[124:125], v[124:125], v[140:141] neg_lo:[0,1] neg_hi:[0,1]
	v_pk_add_f32 v[126:127], v[126:127], v[142:143] neg_lo:[0,1] neg_hi:[0,1]
	v_pk_add_f32 v[128:129], v[128:129], v[144:145] neg_lo:[0,1] neg_hi:[0,1]
	v_pk_add_f32 v[130:131], v[130:131], v[146:147] neg_lo:[0,1] neg_hi:[0,1]
	v_add_u32_e32 v170, 5, v169
	v_min_u32_e32 v170, s56, v170
	v_add_u32_e32 v171, 3, v169
	v_max_i32_e32 v171, 0, v171
	v_sub_u32_e32 v170, v170, v171
	v_cvt_f32_u32_e32 v170, v170
	v_rcp_f32_e32 v174, v170
	v_lshlrev_b32_e32 v132, 16, v20
	v_and_b32_e32 v133, 0xffff0000, v20
	v_lshlrev_b32_e32 v134, 16, v21
	v_and_b32_e32 v135, 0xffff0000, v21
	v_lshlrev_b32_e32 v136, 16, v22
	v_and_b32_e32 v137, 0xffff0000, v22
	v_lshlrev_b32_e32 v138, 16, v23
	v_and_b32_e32 v139, 0xffff0000, v23
	v_pk_fma_f32 v[140:141], v[124:125], v[174:175], v[132:133] op_sel_hi:[1,0,1] neg_lo:[0,0,1] neg_hi:[0,0,1]
	v_pk_fma_f32 v[142:143], v[126:127], v[174:175], v[134:135] op_sel_hi:[1,0,1] neg_lo:[0,0,1] neg_hi:[0,0,1]
	v_pk_fma_f32 v[144:145], v[128:129], v[174:175], v[136:137] op_sel_hi:[1,0,1] neg_lo:[0,0,1] neg_hi:[0,0,1]
	v_pk_fma_f32 v[146:147], v[130:131], v[174:175], v[138:139] op_sel_hi:[1,0,1] neg_lo:[0,0,1] neg_hi:[0,0,1]
	v_cvt_pk_bf16_f32 v148, v140, v141
	v_cvt_pk_bf16_f32 v149, v142, v143
	v_cvt_pk_bf16_f32 v150, v144, v145
	v_cvt_pk_bf16_f32 v151, v146, v147
	global_store_dwordx4 v168, v[148:151], s[54:55]
	v_add_u32_e32 v168, 0x800, v168
	v_lshlrev_b32_e32 v132, 16, v24
	v_and_b32_e32 v133, 0xffff0000, v24
	v_lshlrev_b32_e32 v134, 16, v25
	v_and_b32_e32 v135, 0xffff0000, v25
	v_lshlrev_b32_e32 v136, 16, v26
	v_and_b32_e32 v137, 0xffff0000, v26
	v_lshlrev_b32_e32 v138, 16, v27
	v_and_b32_e32 v139, 0xffff0000, v27
	v_lshlrev_b32_e32 v140, 16, v16
	v_and_b32_e32 v141, 0xffff0000, v16
	v_lshlrev_b32_e32 v142, 16, v17
	v_and_b32_e32 v143, 0xffff0000, v17
	v_lshlrev_b32_e32 v144, 16, v18
	v_and_b32_e32 v145, 0xffff0000, v18
	v_lshlrev_b32_e32 v146, 16, v19
	v_and_b32_e32 v147, 0xffff0000, v19
; __device__ __forceinline__ u32x4 pack8(const f32x4 a, const f32x4 b) { u32x4 w; w.x = cvt_pk_bf16(a[0], a[1]); w.y = cvt_pk_bf16(a[2], a[3]); w.z = cvt_pk_bf16(b[0], b[1]); w.w = cvt_pk_bf16(b[2], b[3]); return w; }
; __global__ void __launch_bounds__(512, 2) fwd_mega(Args a) {
;     ...
;             for (int s = s0; s < s0 + 32; ++s) {
;                 f32x4 u0, u1; pg8::unpack8(*(const u32x4*)(base + (size_t)s * 512), u0, u1);
;                 const int jlo = (s - hw) > 0 ? (s - hw) : 0, jhi = (s + hw) < SEQ ? (s + hw) : SEQ;
;                 const float rc = 1.0f / (float)(jhi - jlo);
;                 *(u32x4*)(obase + (size_t)s * 1024) = pg8::pack8(w0 * rc - u0, w1 * rc - u1);
;                 if (s + hw < SEQ) { f32x4 a0, a1; pg8::unpack8(*(const u32x4*)(base + (size_t)(s + hw) * 512), a0, a1); w0 += a0; w1 += a1; }
;                 if (s - hw >= 0) { f32x4 a0, a1; pg8::unpack8(*(const u32x4*)(base + (size_t)(s - hw) * 512), a0, a1); w0 -= a0; w1 -= a1; }
	v_pk_add_f32 v[124:125], v[124:125], v[132:133]
	v_pk_add_f32 v[126:127], v[126:127], v[134:135]
	v_pk_add_f32 v[128:129], v[128:129], v[136:137]
	v_pk_add_f32 v[130:131], v[130:131], v[138:139]
	v_pk_add_f32 v[124:125], v[124:125], v[140:141] neg_lo:[0,1] neg_hi:[0,1]
	v_pk_add_f32 v[126:127], v[126:127], v[142:143] neg_lo:[0,1] neg_hi:[0,1]
	v_pk_add_f32 v[128:129], v[128:129], v[144:145] neg_lo:[0,1] neg_hi:[0,1]
	v_pk_add_f32 v[130:131], v[130:131], v[146:147] neg_lo:[0,1] neg_hi:[0,1]
	v_add_u32_e32 v170, 6, v169
	v_min_u32_e32 v170, s56, v170
	v_add_u32_e32 v171, 4, v169
	v_max_i32_e32 v171, 0, v171
	v_sub_u32_e32 v170, v170, v171
	v_cvt_f32_u32_e32 v170, v170
	v_rcp_f32_e32 v174, v170
	v_lshlrev_b32_e32 v132, 16, v24
	v_and_b32_e32 v133, 0xffff0000, v24
	v_lshlrev_b32_e32 v134, 16, v25
	v_and_b32_e32 v135, 0xffff0000, v25
	v_lshlrev_b32_e32 v136, 16, v26
	v_and_b32_e32 v137, 0xffff0000, v26
	v_lshlrev_b32_e32 v138, 16, v27
	v_and_b32_e32 v139, 0xffff0000, v27
	v_pk_fma_f32 v[140:141], v[124:125], v[174:175], v[132:133] op_sel_hi:[1,0,1] neg_lo:[0,0,1] neg_hi:[0,0,1]
	v_pk_fma_f32 v[142:143], v[126:127], v[174:175], v[134:135] op_sel_hi:[1,0,1] neg_lo:[0,0,1] neg_hi:[0,0,1]
	v_pk_fma_f32 v[144:145], v[128:129], v[174:175], v[136:137] op_sel_hi:[1,0,1] neg_lo:[0,0,1] neg_hi:[0,0,1]
	v_pk_fma_f32 v[146:147], v[130:131], v[174:175], v[138:139] op_sel_hi:[1,0,1] neg_lo:[0,0,1] neg_hi:[0,0,1]
	v_cvt_pk_bf16_f32 v148, v140, v141
	v_cvt_pk_bf16_f32 v149, v142, v143
	v_cvt_pk_bf16_f32 v150, v144, v145
	v_cvt_pk_bf16_f32 v151, v146, v147
	global_store_dwordx4 v168, v[148:151], s[54:55]
	v_add_u32_e32 v168, 0x800, v168
	v_lshlrev_b32_e32 v132, 16, v28
	v_and_b32_e32 v133, 0xffff0000, v28
	v_lshlrev_b32_e32 v134, 16, v29
	v_and_b32_e32 v135, 0xffff0000, v29
	v_lshlrev_b32_e32 v136, 16, v30
	v_and_b32_e32 v137, 0xffff0000, v30
	v_lshlrev_b32_e32 v138, 16, v31
	v_and_b32_e32 v139, 0xffff0000, v31
	v_lshlrev_b32_e32 v140, 16, v20
	v_and_b32_e32 v141, 0xffff0000, v20
	v_lshlrev_b32_e32 v142, 16, v21
	v_and_b32_e32 v143, 0xffff0000, v21
	v_lshlrev_b32_e32 v144, 16, v22
	v_and_b32_e32 v145, 0xffff0000, v22
	v_lshlrev_b32_e32 v146, 16, v23
	v_and_b32_e32 v147, 0xffff0000, v23
	v_pk_add_f32 v[124:125], v[124:125], v[132:133]
	v_pk_add_f32 v[126:127], v[126:127], v[134:135]
	v_pk_add_f32 v[128:129], v[128:129], v[136:137]
	v_pk_add_f32 v[130:131], v[130:131], v[138:139]
	v_pk_add_f32 v[124:125], v[124:125], v[140:141] neg_lo:[0,1] neg_hi:[0,1]
	v_pk_add_f32 v[126:127], v[126:127], v[142:143] neg_lo:[0,1] neg_hi:[0,1]
	v_pk_add_f32 v[128:129], v[128:129], v[144:145] neg_lo:[0,1] neg_hi:[0,1]
	v_pk_add_f32 v[130:131], v[130:131], v[146:147] neg_lo:[0,1] neg_hi:[0,1]
	v_add_u32_e32 v170, 7, v169
	v_min_u32_e32 v170, s56, v170
	v_add_u32_e32 v171, 5, v169
	v_max_i32_e32 v171, 0, v171
	v_sub_u32_e32 v170, v170, v171
	v_cvt_f32_u32_e32 v170, v170
	v_rcp_f32_e32 v174, v170
	v_lshlrev_b32_e32 v132, 16, v28
	v_and_b32_e32 v133, 0xffff0000, v28
	v_lshlrev_b32_e32 v134, 16, v29
	v_and_b32_e32 v135, 0xffff0000, v29
	v_lshlrev_b32_e32 v136, 16, v30
	v_and_b32_e32 v137, 0xffff0000, v30
	v_lshlrev_b32_e32 v138, 16, v31
	v_and_b32_e32 v139, 0xffff0000, v31
	v_pk_fma_f32 v[140:141], v[124:125], v[174:175], v[132:133] op_sel_hi:[1,0,1] neg_lo:[0,0,1] neg_hi:[0,0,1]
	v_pk_fma_f32 v[142:143], v[126:127], v[174:175], v[134:135] op_sel_hi:[1,0,1] neg_lo:[0,0,1] neg_hi:[0,0,1]
	v_pk_fma_f32 v[144:145], v[128:129], v[174:175], v[136:137] op_sel_hi:[1,0,1] neg_lo:[0,0,1] neg_hi:[0,0,1]
	v_pk_fma_f32 v[146:147], v[130:131], v[174:175], v[138:139] op_sel_hi:[1,0,1] neg_lo:[0,0,1] neg_hi:[0,0,1]
	v_cvt_pk_bf16_f32 v148, v140, v141
	v_cvt_pk_bf16_f32 v149, v142, v143
	v_cvt_pk_bf16_f32 v150, v144, v145
	v_cvt_pk_bf16_f32 v151, v146, v147
	global_store_dwordx4 v168, v[148:151], s[54:55]
	v_add_u32_e32 v168, 0x800, v168
	v_lshlrev_b32_e32 v132, 16, v32
	v_and_b32_e32 v133, 0xffff0000, v32
	v_lshlrev_b32_e32 v134, 16, v33
	v_and_b32_e32 v135, 0xffff0000, v33
	v_lshlrev_b32_e32 v136, 16, v34
	v_and_b32_e32 v137, 0xffff0000, v34
	v_lshlrev_b32_e32 v138, 16, v35
	v_and_b32_e32 v139, 0xffff0000, v35
	v_lshlrev_b32_e32 v140, 16, v24
	v_and_b32_e32 v141, 0xffff0000, v24
	v_lshlrev_b32_e32 v142, 16, v25
	v_and_b32_e32 v143, 0xffff0000, v25
	v_lshlrev_b32_e32 v144, 16, v26
	v_and_b32_e32 v145, 0xffff0000, v26
	v_lshlrev_b32_e32 v146, 16, v27
	v_and_b32_e32 v147, 0xffff0000, v27
	v_pk_add_f32 v[124:125], v[124:125], v[132:133]
	v_pk_add_f32 v[126:127], v[126:127], v[134:135]
	v_pk_add_f32 v[128:129], v[128:129], v[136:137]
	v_pk_add_f32 v[130:131], v[130:131], v[138:139]
	v_pk_add_f32 v[124:125], v[124:125], v[140:141] neg_lo:[0,1] neg_hi:[0,1]
	v_pk_add_f32 v[126:127], v[126:127], v[142:143] neg_lo:[0,1] neg_hi:[0,1]
	v_pk_add_f32 v[128:129], v[128:129], v[144:145] neg_lo:[0,1] neg_hi:[0,1]
	v_pk_add_f32 v[130:131], v[130:131], v[146:147] neg_lo:[0,1] neg_hi:[0,1]
	v_add_u32_e32 v170, 8, v169
	v_min_u32_e32 v170, s56, v170
	v_add_u32_e32 v171, 6, v169
	v_max_i32_e32 v171, 0, v171
	v_sub_u32_e32 v170, v170, v171
	v_cvt_f32_u32_e32 v170, v170
	v_rcp_f32_e32 v174, v170
	v_lshlrev_b32_e32 v132, 16, v32
	v_and_b32_e32 v133, 0xffff0000, v32
	v_lshlrev_b32_e32 v134, 16, v33
	v_and_b32_e32 v135, 0xffff0000, v33
	v_lshlrev_b32_e32 v136, 16, v34
	v_and_b32_e32 v137, 0xffff0000, v34
	v_lshlrev_b32_e32 v138, 16, v35
	v_and_b32_e32 v139, 0xffff0000, v35
	v_pk_fma_f32 v[140:141], v[124:125], v[174:175], v[132:133] op_sel_hi:[1,0,1] neg_lo:[0,0,1] neg_hi:[0,0,1]
	v_pk_fma_f32 v[142:143], v[126:127], v[174:175], v[134:135] op_sel_hi:[1,0,1] neg_lo:[0,0,1] neg_hi:[0,0,1]
; __device__ __forceinline__ u32x4 pack8(const f32x4 a, const f32x4 b) { u32x4 w; w.x = cvt_pk_bf16(a[0], a[1]); w.y = cvt_pk_bf16(a[2], a[3]); w.z = cvt_pk_bf16(b[0], b[1]); w.w = cvt_pk_bf16(b[2], b[3]); return w; }
; __global__ void __launch_bounds__(512, 2) fwd_mega(Args a) {
;     ...
;             for (int s = s0; s < s0 + 32; ++s) {
;                 f32x4 u0, u1; pg8::unpack8(*(const u32x4*)(base + (size_t)s * 512), u0, u1);
;                 const int jlo = (s - hw) > 0 ? (s - hw) : 0, jhi = (s + hw) < SEQ ? (s + hw) : SEQ;
;                 const float rc = 1.0f / (float)(jhi - jlo);
;                 *(u32x4*)(obase + (size_t)s * 1024) = pg8::pack8(w0 * rc - u0, w1 * rc - u1);
;                 if (s + hw < SEQ) { f32x4 a0, a1; pg8::unpack8(*(const u32x4*)(base + (size_t)(s + hw) * 512), a0, a1); w0 += a0; w1 += a1; }
;                 if (s - hw >= 0) { f32x4 a0, a1; pg8::unpack8(*(const u32x4*)(base + (size_t)(s - hw) * 512), a0, a1); w0 -= a0; w1 -= a1; }
	v_pk_fma_f32 v[144:145], v[128:129], v[174:175], v[136:137] op_sel_hi:[1,0,1] neg_lo:[0,0,1] neg_hi:[0,0,1]
	v_pk_fma_f32 v[146:147], v[130:131], v[174:175], v[138:139] op_sel_hi:[1,0,1] neg_lo:[0,0,1] neg_hi:[0,0,1]
	v_cvt_pk_bf16_f32 v148, v140, v141
	v_cvt_pk_bf16_f32 v149, v142, v143
	v_cvt_pk_bf16_f32 v150, v144, v145
	v_cvt_pk_bf16_f32 v151, v146, v147
	global_store_dwordx4 v168, v[148:151], s[54:55]
	v_add_u32_e32 v168, 0x800, v168
	v_lshlrev_b32_e32 v132, 16, v36
	v_and_b32_e32 v133, 0xffff0000, v36
	v_lshlrev_b32_e32 v134, 16, v37
	v_and_b32_e32 v135, 0xffff0000, v37
	v_lshlrev_b32_e32 v136, 16, v38
	v_and_b32_e32 v137, 0xffff0000, v38
	v_lshlrev_b32_e32 v138, 16, v39
	v_and_b32_e32 v139, 0xffff0000, v39
	v_lshlrev_b32_e32 v140, 16, v28
	v_and_b32_e32 v141, 0xffff0000, v28
	v_lshlrev_b32_e32 v142, 16, v29
	v_and_b32_e32 v143, 0xffff0000, v29
	v_lshlrev_b32_e32 v144, 16, v30
	v_and_b32_e32 v145, 0xffff0000, v30
	v_lshlrev_b32_e32 v146, 16, v31
	v_and_b32_e32 v147, 0xffff0000, v31
	v_pk_add_f32 v[124:125], v[124:125], v[132:133]
	v_pk_add_f32 v[126:127], v[126:127], v[134:135]
	v_pk_add_f32 v[128:129], v[128:129], v[136:137]
	v_pk_add_f32 v[130:131], v[130:131], v[138:139]
	v_pk_add_f32 v[124:125], v[124:125], v[140:141] neg_lo:[0,1] neg_hi:[0,1]
	v_pk_add_f32 v[126:127], v[126:127], v[142:143] neg_lo:[0,1] neg_hi:[0,1]
	v_pk_add_f32 v[128:129], v[128:129], v[144:145] neg_lo:[0,1] neg_hi:[0,1]
	v_pk_add_f32 v[130:131], v[130:131], v[146:147] neg_lo:[0,1] neg_hi:[0,1]
	v_add_u32_e32 v170, 9, v169
	v_min_u32_e32 v170, s56, v170
	v_add_u32_e32 v171, 7, v169
	v_max_i32_e32 v171, 0, v171
	v_sub_u32_e32 v170, v170, v171
	v_cvt_f32_u32_e32 v170, v170
	v_rcp_f32_e32 v174, v170
	v_lshlrev_b32_e32 v132, 16, v36
	v_and_b32_e32 v133, 0xffff0000, v36
	v_lshlrev_b32_e32 v134, 16, v37
	v_and_b32_e32 v135, 0xffff0000, v37
	v_lshlrev_b32_e32 v136, 16, v38
	v_and_b32_e32 v137, 0xffff0000, v38
	v_lshlrev_b32_e32 v138, 16, v39
	v_and_b32_e32 v139, 0xffff0000, v39
	v_pk_fma_f32 v[140:141], v[124:125], v[174:175], v[132:133] op_sel_hi:[1,0,1] neg_lo:[0,0,1] neg_hi:[0,0,1]
	v_pk_fma_f32 v[142:143], v[126:127], v[174:175], v[134:135] op_sel_hi:[1,0,1] neg_lo:[0,0,1] neg_hi:[0,0,1]
	v_pk_fma_f32 v[144:145], v[128:129], v[174:175], v[136:137] op_sel_hi:[1,0,1] neg_lo:[0,0,1] neg_hi:[0,0,1]
	v_pk_fma_f32 v[146:147], v[130:131], v[174:175], v[138:139] op_sel_hi:[1,0,1] neg_lo:[0,0,1] neg_hi:[0,0,1]
	v_cvt_pk_bf16_f32 v148, v140, v141
	v_cvt_pk_bf16_f32 v149, v142, v143
	v_cvt_pk_bf16_f32 v150, v144, v145
	v_cvt_pk_bf16_f32 v151, v146, v147
	global_store_dwordx4 v168, v[148:151], s[54:55]
	v_add_u32_e32 v168, 0x800, v168
	v_lshlrev_b32_e32 v132, 16, v40
	v_and_b32_e32 v133, 0xffff0000, v40
	v_lshlrev_b32_e32 v134, 16, v41
	v_and_b32_e32 v135, 0xffff0000, v41
	v_lshlrev_b32_e32 v136, 16, v42
	v_and_b32_e32 v137, 0xffff0000, v42
	v_lshlrev_b32_e32 v138, 16, v43
	v_and_b32_e32 v139, 0xffff0000, v43
	v_lshlrev_b32_e32 v140, 16, v32
	v_and_b32_e32 v141, 0xffff0000, v32
	v_lshlrev_b32_e32 v142, 16, v33
	v_and_b32_e32 v143, 0xffff0000, v33
	v_lshlrev_b32_e32 v144, 16, v34
	v_and_b32_e32 v145, 0xffff0000, v34
	v_lshlrev_b32_e32 v146, 16, v35
	v_and_b32_e32 v147, 0xffff0000, v35
	v_pk_add_f32 v[124:125], v[124:125], v[132:133]
	v_pk_add_f32 v[126:127], v[126:127], v[134:135]
	v_pk_add_f32 v[128:129], v[128:129], v[136:137]
	v_pk_add_f32 v[130:131], v[130:131], v[138:139]
	v_pk_add_f32 v[124:125], v[124:125], v[140:141] neg_lo:[0,1] neg_hi:[0,1]
	v_pk_add_f32 v[126:127], v[126:127], v[142:143] neg_lo:[0,1] neg_hi:[0,1]
	v_pk_add_f32 v[128:129], v[128:129], v[144:145] neg_lo:[0,1] neg_hi:[0,1]
	v_pk_add_f32 v[130:131], v[130:131], v[146:147] neg_lo:[0,1] neg_hi:[0,1]
	v_add_u32_e32 v170, 10, v169
	v_min_u32_e32 v170, s56, v170
	v_add_u32_e32 v171, 8, v169
	v_max_i32_e32 v171, 0, v171
	v_sub_u32_e32 v170, v170, v171
	v_cvt_f32_u32_e32 v170, v170
	v_rcp_f32_e32 v174, v170
	v_lshlrev_b32_e32 v132, 16, v40
	v_and_b32_e32 v133, 0xffff0000, v40
	v_lshlrev_b32_e32 v134, 16, v41
	v_and_b32_e32 v135, 0xffff0000, v41
	v_lshlrev_b32_e32 v136, 16, v42
	v_and_b32_e32 v137, 0xffff0000, v42
	v_lshlrev_b32_e32 v138, 16, v43
	v_and_b32_e32 v139, 0xffff0000, v43
	v_pk_fma_f32 v[140:141], v[124:125], v[174:175], v[132:133] op_sel_hi:[1,0,1] neg_lo:[0,0,1] neg_hi:[0,0,1]
	v_pk_fma_f32 v[142:143], v[126:127], v[174:175], v[134:135] op_sel_hi:[1,0,1] neg_lo:[0,0,1] neg_hi:[0,0,1]
	v_pk_fma_f32 v[144:145], v[128:129], v[174:175], v[136:137] op_sel_hi:[1,0,1] neg_lo:[0,0,1] neg_hi:[0,0,1]
	v_pk_fma_f32 v[146:147], v[130:131], v[174:175], v[138:139] op_sel_hi:[1,0,1] neg_lo:[0,0,1] neg_hi:[0,0,1]
	v_cvt_pk_bf16_f32 v148, v140, v141
	v_cvt_pk_bf16_f32 v149, v142, v143
	v_cvt_pk_bf16_f32 v150, v144, v145
	v_cvt_pk_bf16_f32 v151, v146, v147
	global_store_dwordx4 v168, v[148:151], s[54:55]
	v_add_u32_e32 v168, 0x800, v168
	v_lshlrev_b32_e32 v132, 16, v44
	v_and_b32_e32 v133, 0xffff0000, v44
	v_lshlrev_b32_e32 v134, 16, v45
	v_and_b32_e32 v135, 0xffff0000, v45
	v_lshlrev_b32_e32 v136, 16, v46
	v_and_b32_e32 v137, 0xffff0000, v46
	v_lshlrev_b32_e32 v138, 16, v47
	v_and_b32_e32 v139, 0xffff0000, v47
	v_lshlrev_b32_e32 v140, 16, v36
	v_and_b32_e32 v141, 0xffff0000, v36
	v_lshlrev_b32_e32 v142, 16, v37
	v_and_b32_e32 v143, 0xffff0000, v37
	v_lshlrev_b32_e32 v144, 16, v38
	v_and_b32_e32 v145, 0xffff0000, v38
	v_lshlrev_b32_e32 v146, 16, v39
	v_and_b32_e32 v147, 0xffff0000, v39
	v_pk_add_f32 v[124:125], v[124:125], v[132:133]
	v_pk_add_f32 v[126:127], v[126:127], v[134:135]
	v_pk_add_f32 v[128:129], v[128:129], v[136:137]
	v_pk_add_f32 v[130:131], v[130:131], v[138:139]
; __device__ __forceinline__ u32x4 pack8(const f32x4 a, const f32x4 b) { u32x4 w; w.x = cvt_pk_bf16(a[0], a[1]); w.y = cvt_pk_bf16(a[2], a[3]); w.z = cvt_pk_bf16(b[0], b[1]); w.w = cvt_pk_bf16(b[2], b[3]); return w; }
; __global__ void __launch_bounds__(512, 2) fwd_mega(Args a) {
;     ...
;             for (int s = s0; s < s0 + 32; ++s) {
;                 f32x4 u0, u1; pg8::unpack8(*(const u32x4*)(base + (size_t)s * 512), u0, u1);
;                 const int jlo = (s - hw) > 0 ? (s - hw) : 0, jhi = (s + hw) < SEQ ? (s + hw) : SEQ;
;                 const float rc = 1.0f / (float)(jhi - jlo);
;                 *(u32x4*)(obase + (size_t)s * 1024) = pg8::pack8(w0 * rc - u0, w1 * rc - u1);
;                 if (s + hw < SEQ) { f32x4 a0, a1; pg8::unpack8(*(const u32x4*)(base + (size_t)(s + hw) * 512), a0, a1); w0 += a0; w1 += a1; }
;                 if (s - hw >= 0) { f32x4 a0, a1; pg8::unpack8(*(const u32x4*)(base + (size_t)(s - hw) * 512), a0, a1); w0 -= a0; w1 -= a1; }
	v_pk_add_f32 v[124:125], v[124:125], v[140:141] neg_lo:[0,1] neg_hi:[0,1]
	v_pk_add_f32 v[126:127], v[126:127], v[142:143] neg_lo:[0,1] neg_hi:[0,1]
	v_pk_add_f32 v[128:129], v[128:129], v[144:145] neg_lo:[0,1] neg_hi:[0,1]
	v_pk_add_f32 v[130:131], v[130:131], v[146:147] neg_lo:[0,1] neg_hi:[0,1]
	v_add_u32_e32 v170, 11, v169
	v_min_u32_e32 v170, s56, v170
	v_add_u32_e32 v171, 9, v169
	v_max_i32_e32 v171, 0, v171
	v_sub_u32_e32 v170, v170, v171
	v_cvt_f32_u32_e32 v170, v170
	v_rcp_f32_e32 v174, v170
	v_lshlrev_b32_e32 v132, 16, v44
	v_and_b32_e32 v133, 0xffff0000, v44
	v_lshlrev_b32_e32 v134, 16, v45
	v_and_b32_e32 v135, 0xffff0000, v45
	v_lshlrev_b32_e32 v136, 16, v46
	v_and_b32_e32 v137, 0xffff0000, v46
	v_lshlrev_b32_e32 v138, 16, v47
	v_and_b32_e32 v139, 0xffff0000, v47
	v_pk_fma_f32 v[140:141], v[124:125], v[174:175], v[132:133] op_sel_hi:[1,0,1] neg_lo:[0,0,1] neg_hi:[0,0,1]
	v_pk_fma_f32 v[142:143], v[126:127], v[174:175], v[134:135] op_sel_hi:[1,0,1] neg_lo:[0,0,1] neg_hi:[0,0,1]
	v_pk_fma_f32 v[144:145], v[128:129], v[174:175], v[136:137] op_sel_hi:[1,0,1] neg_lo:[0,0,1] neg_hi:[0,0,1]
	v_pk_fma_f32 v[146:147], v[130:131], v[174:175], v[138:139] op_sel_hi:[1,0,1] neg_lo:[0,0,1] neg_hi:[0,0,1]
	v_cvt_pk_bf16_f32 v148, v140, v141
	v_cvt_pk_bf16_f32 v149, v142, v143
	v_cvt_pk_bf16_f32 v150, v144, v145
	v_cvt_pk_bf16_f32 v151, v146, v147
	global_store_dwordx4 v168, v[148:151], s[54:55]
	v_add_u32_e32 v168, 0x800, v168
	v_lshlrev_b32_e32 v132, 16, v48
	v_and_b32_e32 v133, 0xffff0000, v48
	v_lshlrev_b32_e32 v134, 16, v49
	v_and_b32_e32 v135, 0xffff0000, v49
	v_lshlrev_b32_e32 v136, 16, v50
	v_and_b32_e32 v137, 0xffff0000, v50
	v_lshlrev_b32_e32 v138, 16, v51
	v_and_b32_e32 v139, 0xffff0000, v51
	v_lshlrev_b32_e32 v140, 16, v40
	v_and_b32_e32 v141, 0xffff0000, v40
	v_lshlrev_b32_e32 v142, 16, v41
	v_and_b32_e32 v143, 0xffff0000, v41
	v_lshlrev_b32_e32 v144, 16, v42
	v_and_b32_e32 v145, 0xffff0000, v42
	v_lshlrev_b32_e32 v146, 16, v43
	v_and_b32_e32 v147, 0xffff0000, v43
	v_pk_add_f32 v[124:125], v[124:125], v[132:133]
	v_pk_add_f32 v[126:127], v[126:127], v[134:135]
	v_pk_add_f32 v[128:129], v[128:129], v[136:137]
	v_pk_add_f32 v[130:131], v[130:131], v[138:139]
	v_pk_add_f32 v[124:125], v[124:125], v[140:141] neg_lo:[0,1] neg_hi:[0,1]
	v_pk_add_f32 v[126:127], v[126:127], v[142:143] neg_lo:[0,1] neg_hi:[0,1]
	v_pk_add_f32 v[128:129], v[128:129], v[144:145] neg_lo:[0,1] neg_hi:[0,1]
	v_pk_add_f32 v[130:131], v[130:131], v[146:147] neg_lo:[0,1] neg_hi:[0,1]
	v_add_u32_e32 v170, 12, v169
	v_min_u32_e32 v170, s56, v170
	v_add_u32_e32 v171, 10, v169
	v_max_i32_e32 v171, 0, v171
	v_sub_u32_e32 v170, v170, v171
	v_cvt_f32_u32_e32 v170, v170
	v_rcp_f32_e32 v174, v170
	v_lshlrev_b32_e32 v132, 16, v48
	v_and_b32_e32 v133, 0xffff0000, v48
	v_lshlrev_b32_e32 v134, 16, v49
	v_and_b32_e32 v135, 0xffff0000, v49
	v_lshlrev_b32_e32 v136, 16, v50
	v_and_b32_e32 v137, 0xffff0000, v50
	v_lshlrev_b32_e32 v138, 16, v51
	v_and_b32_e32 v139, 0xffff0000, v51
	v_pk_fma_f32 v[140:141], v[124:125], v[174:175], v[132:133] op_sel_hi:[1,0,1] neg_lo:[0,0,1] neg_hi:[0,0,1]
	v_pk_fma_f32 v[142:143], v[126:127], v[174:175], v[134:135] op_sel_hi:[1,0,1] neg_lo:[0,0,1] neg_hi:[0,0,1]
	v_pk_fma_f32 v[144:145], v[128:129], v[174:175], v[136:137] op_sel_hi:[1,0,1] neg_lo:[0,0,1] neg_hi:[0,0,1]
	v_pk_fma_f32 v[146:147], v[130:131], v[174:175], v[138:139] op_sel_hi:[1,0,1] neg_lo:[0,0,1] neg_hi:[0,0,1]
	v_cvt_pk_bf16_f32 v148, v140, v141
	v_cvt_pk_bf16_f32 v149, v142, v143
	v_cvt_pk_bf16_f32 v150, v144, v145
	v_cvt_pk_bf16_f32 v151, v146, v147
	global_store_dwordx4 v168, v[148:151], s[54:55]
	v_add_u32_e32 v168, 0x800, v168
	v_lshlrev_b32_e32 v132, 16, v52
	v_and_b32_e32 v133, 0xffff0000, v52
	v_lshlrev_b32_e32 v134, 16, v53
	v_and_b32_e32 v135, 0xffff0000, v53
	v_lshlrev_b32_e32 v136, 16, v54
	v_and_b32_e32 v137, 0xffff0000, v54
	v_lshlrev_b32_e32 v138, 16, v55
	v_and_b32_e32 v139, 0xffff0000, v55
	v_lshlrev_b32_e32 v140, 16, v44
	v_and_b32_e32 v141, 0xffff0000, v44
	v_lshlrev_b32_e32 v142, 16, v45
	v_and_b32_e32 v143, 0xffff0000, v45
	v_lshlrev_b32_e32 v144, 16, v46
	v_and_b32_e32 v145, 0xffff0000, v46
	v_lshlrev_b32_e32 v146, 16, v47
	v_and_b32_e32 v147, 0xffff0000, v47
	v_pk_add_f32 v[124:125], v[124:125], v[132:133]
	v_pk_add_f32 v[126:127], v[126:127], v[134:135]
	v_pk_add_f32 v[128:129], v[128:129], v[136:137]
	v_pk_add_f32 v[130:131], v[130:131], v[138:139]
	v_pk_add_f32 v[124:125], v[124:125], v[140:141] neg_lo:[0,1] neg_hi:[0,1]
	v_pk_add_f32 v[126:127], v[126:127], v[142:143] neg_lo:[0,1] neg_hi:[0,1]
	v_pk_add_f32 v[128:129], v[128:129], v[144:145] neg_lo:[0,1] neg_hi:[0,1]
	v_pk_add_f32 v[130:131], v[130:131], v[146:147] neg_lo:[0,1] neg_hi:[0,1]
	v_add_u32_e32 v170, 13, v169
	v_min_u32_e32 v170, s56, v170
	v_add_u32_e32 v171, 11, v169
	v_max_i32_e32 v171, 0, v171
	v_sub_u32_e32 v170, v170, v171
	v_cvt_f32_u32_e32 v170, v170
	v_rcp_f32_e32 v174, v170
	v_lshlrev_b32_e32 v132, 16, v52
	v_and_b32_e32 v133, 0xffff0000, v52
	v_lshlrev_b32_e32 v134, 16, v53
	v_and_b32_e32 v135, 0xffff0000, v53
	v_lshlrev_b32_e32 v136, 16, v54
	v_and_b32_e32 v137, 0xffff0000, v54
	v_lshlrev_b32_e32 v138, 16, v55
	v_and_b32_e32 v139, 0xffff0000, v55
	v_pk_fma_f32 v[140:141], v[124:125], v[174:175], v[132:133] op_sel_hi:[1,0,1] neg_lo:[0,0,1] neg_hi:[0,0,1]
	v_pk_fma_f32 v[142:143], v[126:127], v[174:175], v[134:135] op_sel_hi:[1,0,1] neg_lo:[0,0,1] neg_hi:[0,0,1]
	v_pk_fma_f32 v[144:145], v[128:129], v[174:175], v[136:137] op_sel_hi:[1,0,1] neg_lo:[0,0,1] neg_hi:[0,0,1]
	v_pk_fma_f32 v[146:147], v[130:131], v[174:175], v[138:139] op_sel_hi:[1,0,1] neg_lo:[0,0,1] neg_hi:[0,0,1]
; __device__ __forceinline__ u32x4 pack8(const f32x4 a, const f32x4 b) { u32x4 w; w.x = cvt_pk_bf16(a[0], a[1]); w.y = cvt_pk_bf16(a[2], a[3]); w.z = cvt_pk_bf16(b[0], b[1]); w.w = cvt_pk_bf16(b[2], b[3]); return w; }
; __global__ void __launch_bounds__(512, 2) fwd_mega(Args a) {
;     ...
;             for (int s = s0; s < s0 + 32; ++s) {
;                 f32x4 u0, u1; pg8::unpack8(*(const u32x4*)(base + (size_t)s * 512), u0, u1);
;                 const int jlo = (s - hw) > 0 ? (s - hw) : 0, jhi = (s + hw) < SEQ ? (s + hw) : SEQ;
;                 const float rc = 1.0f / (float)(jhi - jlo);
;                 *(u32x4*)(obase + (size_t)s * 1024) = pg8::pack8(w0 * rc - u0, w1 * rc - u1);
;                 if (s + hw < SEQ) { f32x4 a0, a1; pg8::unpack8(*(const u32x4*)(base + (size_t)(s + hw) * 512), a0, a1); w0 += a0; w1 += a1; }
;                 if (s - hw >= 0) { f32x4 a0, a1; pg8::unpack8(*(const u32x4*)(base + (size_t)(s - hw) * 512), a0, a1); w0 -= a0; w1 -= a1; }
	v_cvt_pk_bf16_f32 v148, v140, v141
	v_cvt_pk_bf16_f32 v149, v142, v143
	v_cvt_pk_bf16_f32 v150, v144, v145
	v_cvt_pk_bf16_f32 v151, v146, v147
	global_store_dwordx4 v168, v[148:151], s[54:55]
	v_add_u32_e32 v168, 0x800, v168
	v_lshlrev_b32_e32 v132, 16, v56
	v_and_b32_e32 v133, 0xffff0000, v56
	v_lshlrev_b32_e32 v134, 16, v57
	v_and_b32_e32 v135, 0xffff0000, v57
	v_lshlrev_b32_e32 v136, 16, v58
	v_and_b32_e32 v137, 0xffff0000, v58
	v_lshlrev_b32_e32 v138, 16, v59
	v_and_b32_e32 v139, 0xffff0000, v59
	v_lshlrev_b32_e32 v140, 16, v48
	v_and_b32_e32 v141, 0xffff0000, v48
	v_lshlrev_b32_e32 v142, 16, v49
	v_and_b32_e32 v143, 0xffff0000, v49
	v_lshlrev_b32_e32 v144, 16, v50
	v_and_b32_e32 v145, 0xffff0000, v50
	v_lshlrev_b32_e32 v146, 16, v51
	v_and_b32_e32 v147, 0xffff0000, v51
	v_pk_add_f32 v[124:125], v[124:125], v[132:133]
	v_pk_add_f32 v[126:127], v[126:127], v[134:135]
	v_pk_add_f32 v[128:129], v[128:129], v[136:137]
	v_pk_add_f32 v[130:131], v[130:131], v[138:139]
	v_pk_add_f32 v[124:125], v[124:125], v[140:141] neg_lo:[0,1] neg_hi:[0,1]
	v_pk_add_f32 v[126:127], v[126:127], v[142:143] neg_lo:[0,1] neg_hi:[0,1]
	v_pk_add_f32 v[128:129], v[128:129], v[144:145] neg_lo:[0,1] neg_hi:[0,1]
	v_pk_add_f32 v[130:131], v[130:131], v[146:147] neg_lo:[0,1] neg_hi:[0,1]
	v_add_u32_e32 v170, 14, v169
	v_min_u32_e32 v170, s56, v170
	v_add_u32_e32 v171, 12, v169
	v_max_i32_e32 v171, 0, v171
	v_sub_u32_e32 v170, v170, v171
	v_cvt_f32_u32_e32 v170, v170
	v_rcp_f32_e32 v174, v170
	v_lshlrev_b32_e32 v132, 16, v56
	v_and_b32_e32 v133, 0xffff0000, v56
	v_lshlrev_b32_e32 v134, 16, v57
	v_and_b32_e32 v135, 0xffff0000, v57
	v_lshlrev_b32_e32 v136, 16, v58
	v_and_b32_e32 v137, 0xffff0000, v58
	v_lshlrev_b32_e32 v138, 16, v59
	v_and_b32_e32 v139, 0xffff0000, v59
	v_pk_fma_f32 v[140:141], v[124:125], v[174:175], v[132:133] op_sel_hi:[1,0,1] neg_lo:[0,0,1] neg_hi:[0,0,1]
	v_pk_fma_f32 v[142:143], v[126:127], v[174:175], v[134:135] op_sel_hi:[1,0,1] neg_lo:[0,0,1] neg_hi:[0,0,1]
	v_pk_fma_f32 v[144:145], v[128:129], v[174:175], v[136:137] op_sel_hi:[1,0,1] neg_lo:[0,0,1] neg_hi:[0,0,1]
	v_pk_fma_f32 v[146:147], v[130:131], v[174:175], v[138:139] op_sel_hi:[1,0,1] neg_lo:[0,0,1] neg_hi:[0,0,1]
	v_cvt_pk_bf16_f32 v148, v140, v141
	v_cvt_pk_bf16_f32 v149, v142, v143
	v_cvt_pk_bf16_f32 v150, v144, v145
	v_cvt_pk_bf16_f32 v151, v146, v147
	global_store_dwordx4 v168, v[148:151], s[54:55]
	v_add_u32_e32 v168, 0x800, v168
	v_lshlrev_b32_e32 v132, 16, v60
	v_and_b32_e32 v133, 0xffff0000, v60
	v_lshlrev_b32_e32 v134, 16, v61
	v_and_b32_e32 v135, 0xffff0000, v61
	v_lshlrev_b32_e32 v136, 16, v62
	v_and_b32_e32 v137, 0xffff0000, v62
	v_lshlrev_b32_e32 v138, 16, v63
	v_and_b32_e32 v139, 0xffff0000, v63
	v_lshlrev_b32_e32 v140, 16, v52
	v_and_b32_e32 v141, 0xffff0000, v52
	v_lshlrev_b32_e32 v142, 16, v53
	v_and_b32_e32 v143, 0xffff0000, v53
	v_lshlrev_b32_e32 v144, 16, v54
	v_and_b32_e32 v145, 0xffff0000, v54
	v_lshlrev_b32_e32 v146, 16, v55
	v_and_b32_e32 v147, 0xffff0000, v55
	v_pk_add_f32 v[124:125], v[124:125], v[132:133]
	v_pk_add_f32 v[126:127], v[126:127], v[134:135]
	v_pk_add_f32 v[128:129], v[128:129], v[136:137]
	v_pk_add_f32 v[130:131], v[130:131], v[138:139]
	v_pk_add_f32 v[124:125], v[124:125], v[140:141] neg_lo:[0,1] neg_hi:[0,1]
	v_pk_add_f32 v[126:127], v[126:127], v[142:143] neg_lo:[0,1] neg_hi:[0,1]
	v_pk_add_f32 v[128:129], v[128:129], v[144:145] neg_lo:[0,1] neg_hi:[0,1]
	v_pk_add_f32 v[130:131], v[130:131], v[146:147] neg_lo:[0,1] neg_hi:[0,1]
	v_add_u32_e32 v170, 15, v169
	v_min_u32_e32 v170, s56, v170
	v_add_u32_e32 v171, 13, v169
	v_max_i32_e32 v171, 0, v171
	v_sub_u32_e32 v170, v170, v171
	v_cvt_f32_u32_e32 v170, v170
	v_rcp_f32_e32 v174, v170
	v_lshlrev_b32_e32 v132, 16, v60
	v_and_b32_e32 v133, 0xffff0000, v60
	v_lshlrev_b32_e32 v134, 16, v61
	v_and_b32_e32 v135, 0xffff0000, v61
	v_lshlrev_b32_e32 v136, 16, v62
	v_and_b32_e32 v137, 0xffff0000, v62
	v_lshlrev_b32_e32 v138, 16, v63
	v_and_b32_e32 v139, 0xffff0000, v63
	v_pk_fma_f32 v[140:141], v[124:125], v[174:175], v[132:133] op_sel_hi:[1,0,1] neg_lo:[0,0,1] neg_hi:[0,0,1]
	v_pk_fma_f32 v[142:143], v[126:127], v[174:175], v[134:135] op_sel_hi:[1,0,1] neg_lo:[0,0,1] neg_hi:[0,0,1]
	v_pk_fma_f32 v[144:145], v[128:129], v[174:175], v[136:137] op_sel_hi:[1,0,1] neg_lo:[0,0,1] neg_hi:[0,0,1]
	v_pk_fma_f32 v[146:147], v[130:131], v[174:175], v[138:139] op_sel_hi:[1,0,1] neg_lo:[0,0,1] neg_hi:[0,0,1]
	v_cvt_pk_bf16_f32 v148, v140, v141
	v_cvt_pk_bf16_f32 v149, v142, v143
	v_cvt_pk_bf16_f32 v150, v144, v145
	v_cvt_pk_bf16_f32 v151, v146, v147
	global_store_dwordx4 v168, v[148:151], s[54:55]
	v_add_u32_e32 v168, 0x800, v168
	v_lshlrev_b32_e32 v132, 16, v64
	v_and_b32_e32 v133, 0xffff0000, v64
	v_lshlrev_b32_e32 v134, 16, v65
	v_and_b32_e32 v135, 0xffff0000, v65
	v_lshlrev_b32_e32 v136, 16, v66
	v_and_b32_e32 v137, 0xffff0000, v66
	v_lshlrev_b32_e32 v138, 16, v67
	v_and_b32_e32 v139, 0xffff0000, v67
	v_lshlrev_b32_e32 v140, 16, v56
	v_and_b32_e32 v141, 0xffff0000, v56
	v_lshlrev_b32_e32 v142, 16, v57
	v_and_b32_e32 v143, 0xffff0000, v57
	v_lshlrev_b32_e32 v144, 16, v58
	v_and_b32_e32 v145, 0xffff0000, v58
	v_lshlrev_b32_e32 v146, 16, v59
	v_and_b32_e32 v147, 0xffff0000, v59
	v_pk_add_f32 v[124:125], v[124:125], v[132:133]
	v_pk_add_f32 v[126:127], v[126:127], v[134:135]
	v_pk_add_f32 v[128:129], v[128:129], v[136:137]
	v_pk_add_f32 v[130:131], v[130:131], v[138:139]
	v_pk_add_f32 v[124:125], v[124:125], v[140:141] neg_lo:[0,1] neg_hi:[0,1]
	v_pk_add_f32 v[126:127], v[126:127], v[142:143] neg_lo:[0,1] neg_hi:[0,1]
	v_pk_add_f32 v[128:129], v[128:129], v[144:145] neg_lo:[0,1] neg_hi:[0,1]
	v_pk_add_f32 v[130:131], v[130:131], v[146:147] neg_lo:[0,1] neg_hi:[0,1]
	v_add_u32_e32 v170, 16, v169
	v_min_u32_e32 v170, s56, v170
	v_add_u32_e32 v171, 14, v169
	v_max_i32_e32 v171, 0, v171
	v_sub_u32_e32 v170, v170, v171
	v_cvt_f32_u32_e32 v170, v170
	v_rcp_f32_e32 v174, v170
	v_lshlrev_b32_e32 v132, 16, v64
	v_and_b32_e32 v133, 0xffff0000, v64
	v_lshlrev_b32_e32 v134, 16, v65
	v_and_b32_e32 v135, 0xffff0000, v65
	v_lshlrev_b32_e32 v136, 16, v66
	v_and_b32_e32 v137, 0xffff0000, v66
	v_lshlrev_b32_e32 v138, 16, v67
	v_and_b32_e32 v139, 0xffff0000, v67
	v_pk_fma_f32 v[140:141], v[124:125], v[174:175], v[132:133] op_sel_hi:[1,0,1] neg_lo:[0,0,1] neg_hi:[0,0,1]
	v_pk_fma_f32 v[142:143], v[126:127], v[174:175], v[134:135] op_sel_hi:[1,0,1] neg_lo:[0,0,1] neg_hi:[0,0,1]
	v_pk_fma_f32 v[144:145], v[128:129], v[174:175], v[136:137] op_sel_hi:[1,0,1] neg_lo:[0,0,1] neg_hi:[0,0,1]
	v_pk_fma_f32 v[146:147], v[130:131], v[174:175], v[138:139] op_sel_hi:[1,0,1] neg_lo:[0,0,1] neg_hi:[0,0,1]
	v_cvt_pk_bf16_f32 v148, v140, v141
	v_cvt_pk_bf16_f32 v149, v142, v143
	v_cvt_pk_bf16_f32 v150, v144, v145
	v_cvt_pk_bf16_f32 v151, v146, v147
	global_store_dwordx4 v168, v[148:151], s[54:55]
	s_branch .Lpool_next
; __device__ __forceinline__ u32x4 pack8(const f32x4 a, const f32x4 b) { u32x4 w; w.x = cvt_pk_bf16(a[0], a[1]); w.y = cvt_pk_bf16(a[2], a[3]); w.z = cvt_pk_bf16(b[0], b[1]); w.w = cvt_pk_bf16(b[2], b[3]); return w; }
; __global__ void __launch_bounds__(512, 2) fwd_mega(Args a) {
;     ...
;             { const int jlo = (s0 - hw) > 0 ? (s0 - hw) : 0, jhi = (s0 + hw) < SEQ ? (s0 + hw) : SEQ;
;               for (int j = jlo; j < jhi; ++j) { f32x4 a0, a1; pg8::unpack8(*(const u32x4*)(base + (size_t)j * 512), a0, a1); w0 += a0; w1 += a1; } }
;     ...
;             for (int s = s0; s < s0 + 32; ++s) {
;                 f32x4 u0, u1; pg8::unpack8(*(const u32x4*)(base + (size_t)s * 512), u0, u1);
;                 const int jlo = (s - hw) > 0 ? (s - hw) : 0, jhi = (s + hw) < SEQ ? (s + hw) : SEQ;
;                 const float rc = 1.0f / (float)(jhi - jlo);
;                 *(u32x4*)(obase + (size_t)s * 1024) = pg8::pack8(w0 * rc - u0, w1 * rc - u1);
;                 if (s + hw < SEQ) { f32x4 a0, a1; pg8::unpack8(*(const u32x4*)(base + (size_t)(s + hw) * 512), a0, a1); w0 += a0; w1 += a1; }
;                 if (s - hw >= 0) { f32x4 a0, a1; pg8::unpack8(*(const u32x4*)(base + (size_t)(s - hw) * 512), a0, a1); w0 -= a0; w1 -= a1; }
.Lpool_g1:
	s_sub_i32 s52, s49, 2
	s_ashr_i32 s53, s52, 31
	s_lshl_b64 s[52:53], s[52:53], 10
	s_add_u32 s52, s52, s8
	s_addc_u32 s53, s53, s9
	s_add_u32 s52, s52, 256
	s_addc_u32 s53, s53, 0
	s_lshl_b32 s54, s49, 11
	s_add_u32 s54, s54, 0x3000500
	s_add_u32 s54, s30, s54
	s_addc_u32 s55, s31, 0
	global_load_dwordx4 v[0:3], v160, s[52:53] offset:0
	global_load_dwordx4 v[4:7], v160, s[52:53] offset:1024
	global_load_dwordx4 v[8:11], v160, s[52:53] offset:2048
	global_load_dwordx4 v[12:15], v160, s[52:53] offset:3072
	global_load_dwordx4 v[16:19], v161, s[52:53] offset:0
	global_load_dwordx4 v[20:23], v161, s[52:53] offset:1024
	global_load_dwordx4 v[24:27], v161, s[52:53] offset:2048
	global_load_dwordx4 v[28:31], v161, s[52:53] offset:3072
	global_load_dwordx4 v[32:35], v162, s[52:53] offset:0
	global_load_dwordx4 v[36:39], v162, s[52:53] offset:1024
	global_load_dwordx4 v[40:43], v162, s[52:53] offset:2048
	global_load_dwordx4 v[44:47], v162, s[52:53] offset:3072
	global_load_dwordx4 v[48:51], v163, s[52:53] offset:0
	global_load_dwordx4 v[52:55], v163, s[52:53] offset:1024
	global_load_dwordx4 v[56:59], v163, s[52:53] offset:2048
	global_load_dwordx4 v[60:63], v163, s[52:53] offset:3072
	global_load_dwordx4 v[64:67], v164, s[52:53] offset:0
	global_load_dwordx4 v[68:71], v164, s[52:53] offset:1024
	global_load_dwordx4 v[72:75], v164, s[52:53] offset:2048
	s_waitcnt vmcnt(0)
	s_cmp_eq_u32 s50, 0
	s_cbranch_scc1 .Lpool_g1_mask
	s_cmpk_eq_i32 s50, 0x7c0
	s_cbranch_scc0 .Lpool_g1_nomask
.Lpool_g1_mask:
	v_add_u32_e32 v170, -2, v169
	v_cmp_gt_u32_e32 vcc, s56, v170
	s_nop 1
	v_cndmask_b32_e32 v0, 0, v0, vcc
	v_cndmask_b32_e32 v1, 0, v1, vcc
	v_cndmask_b32_e32 v2, 0, v2, vcc
	v_cndmask_b32_e32 v3, 0, v3, vcc
	v_add_u32_e32 v170, -1, v169
	v_cmp_gt_u32_e32 vcc, s56, v170
	s_nop 1
	v_cndmask_b32_e32 v4, 0, v4, vcc
	v_cndmask_b32_e32 v5, 0, v5, vcc
	v_cndmask_b32_e32 v6, 0, v6, vcc
	v_cndmask_b32_e32 v7, 0, v7, vcc
	v_add_u32_e32 v170, 0, v169
	v_cmp_gt_u32_e32 vcc, s56, v170
	s_nop 1
	v_cndmask_b32_e32 v8, 0, v8, vcc
	v_cndmask_b32_e32 v9, 0, v9, vcc
	v_cndmask_b32_e32 v10, 0, v10, vcc
	v_cndmask_b32_e32 v11, 0, v11, vcc
	v_add_u32_e32 v170, 1, v169
	v_cmp_gt_u32_e32 vcc, s56, v170
	s_nop 1
	v_cndmask_b32_e32 v12, 0, v12, vcc
	v_cndmask_b32_e32 v13, 0, v13, vcc
	v_cndmask_b32_e32 v14, 0, v14, vcc
	v_cndmask_b32_e32 v15, 0, v15, vcc
	v_add_u32_e32 v170, 2, v169
	v_cmp_gt_u32_e32 vcc, s56, v170
	s_nop 1
	v_cndmask_b32_e32 v16, 0, v16, vcc
	v_cndmask_b32_e32 v17, 0, v17, vcc
	v_cndmask_b32_e32 v18, 0, v18, vcc
	v_cndmask_b32_e32 v19, 0, v19, vcc
	v_add_u32_e32 v170, 3, v169
	v_cmp_gt_u32_e32 vcc, s56, v170
	s_nop 1
	v_cndmask_b32_e32 v20, 0, v20, vcc
	v_cndmask_b32_e32 v21, 0, v21, vcc
	v_cndmask_b32_e32 v22, 0, v22, vcc
	v_cndmask_b32_e32 v23, 0, v23, vcc
	v_add_u32_e32 v170, 4, v169
	v_cmp_gt_u32_e32 vcc, s56, v170
	s_nop 1
	v_cndmask_b32_e32 v24, 0, v24, vcc
	v_cndmask_b32_e32 v25, 0, v25, vcc
	v_cndmask_b32_e32 v26, 0, v26, vcc
	v_cndmask_b32_e32 v27, 0, v27, vcc
	v_add_u32_e32 v170, 5, v169
	v_cmp_gt_u32_e32 vcc, s56, v170
	s_nop 1
	v_cndmask_b32_e32 v28, 0, v28, vcc
	v_cndmask_b32_e32 v29, 0, v29, vcc
	v_cndmask_b32_e32 v30, 0, v30, vcc
	v_cndmask_b32_e32 v31, 0, v31, vcc
	v_add_u32_e32 v170, 6, v169
	v_cmp_gt_u32_e32 vcc, s56, v170
	s_nop 1
	v_cndmask_b32_e32 v32, 0, v32, vcc
	v_cndmask_b32_e32 v33, 0, v33, vcc
	v_cndmask_b32_e32 v34, 0, v34, vcc
	v_cndmask_b32_e32 v35, 0, v35, vcc
	v_add_u32_e32 v170, 7, v169
	v_cmp_gt_u32_e32 vcc, s56, v170
	s_nop 1
	v_cndmask_b32_e32 v36, 0, v36, vcc
	v_cndmask_b32_e32 v37, 0, v37, vcc
	v_cndmask_b32_e32 v38, 0, v38, vcc
	v_cndmask_b32_e32 v39, 0, v39, vcc
	v_add_u32_e32 v170, 8, v169
	v_cmp_gt_u32_e32 vcc, s56, v170
	s_nop 1
	v_cndmask_b32_e32 v40, 0, v40, vcc
	v_cndmask_b32_e32 v41, 0, v41, vcc
	v_cndmask_b32_e32 v42, 0, v42, vcc
	v_cndmask_b32_e32 v43, 0, v43, vcc
	v_add_u32_e32 v170, 9, v169
	v_cmp_gt_u32_e32 vcc, s56, v170
	s_nop 1
	v_cndmask_b32_e32 v44, 0, v44, vcc
	v_cndmask_b32_e32 v45, 0, v45, vcc
	v_cndmask_b32_e32 v46, 0, v46, vcc
	v_cndmask_b32_e32 v47, 0, v47, vcc
	v_add_u32_e32 v170, 10, v169
	v_cmp_gt_u32_e32 vcc, s56, v170
	s_nop 1
	v_cndmask_b32_e32 v48, 0, v48, vcc
	v_cndmask_b32_e32 v49, 0, v49, vcc
	v_cndmask_b32_e32 v50, 0, v50, vcc
	v_cndmask_b32_e32 v51, 0, v51, vcc
	v_add_u32_e32 v170, 11, v169
	v_cmp_gt_u32_e32 vcc, s56, v170
	s_nop 1
	v_cndmask_b32_e32 v52, 0, v52, vcc
	v_cndmask_b32_e32 v53, 0, v53, vcc
	v_cndmask_b32_e32 v54, 0, v54, vcc
	v_cndmask_b32_e32 v55, 0, v55, vcc
	v_add_u32_e32 v170, 12, v169
	v_cmp_gt_u32_e32 vcc, s56, v170
	s_nop 1
	v_cndmask_b32_e32 v56, 0, v56, vcc
	v_cndmask_b32_e32 v57, 0, v57, vcc
	v_cndmask_b32_e32 v58, 0, v58, vcc
	v_cndmask_b32_e32 v59, 0, v59, vcc
	v_add_u32_e32 v170, 13, v169
	v_cmp_gt_u32_e32 vcc, s56, v170
	s_nop 1
	v_cndmask_b32_e32 v60, 0, v60, vcc
	v_cndmask_b32_e32 v61, 0, v61, vcc
	v_cndmask_b32_e32 v62, 0, v62, vcc
	v_cndmask_b32_e32 v63, 0, v63, vcc
	v_add_u32_e32 v170, 14, v169
	v_cmp_gt_u32_e32 vcc, s56, v170
	s_nop 1
	v_cndmask_b32_e32 v64, 0, v64, vcc
	v_cndmask_b32_e32 v65, 0, v65, vcc
	v_cndmask_b32_e32 v66, 0, v66, vcc
	v_cndmask_b32_e32 v67, 0, v67, vcc
	v_add_u32_e32 v170, 15, v169
	v_cmp_gt_u32_e32 vcc, s56, v170
	s_nop 1
	v_cndmask_b32_e32 v68, 0, v68, vcc
	v_cndmask_b32_e32 v69, 0, v69, vcc
	v_cndmask_b32_e32 v70, 0, v70, vcc
	v_cndmask_b32_e32 v71, 0, v71, vcc
	v_add_u32_e32 v170, 16, v169
	v_cmp_gt_u32_e32 vcc, s56, v170
	s_nop 1
	v_cndmask_b32_e32 v72, 0, v72, vcc
	v_cndmask_b32_e32 v73, 0, v73, vcc
	v_cndmask_b32_e32 v74, 0, v74, vcc
	v_cndmask_b32_e32 v75, 0, v75, vcc
; __device__ __forceinline__ u32x4 pack8(const f32x4 a, const f32x4 b) { u32x4 w; w.x = cvt_pk_bf16(a[0], a[1]); w.y = cvt_pk_bf16(a[2], a[3]); w.z = cvt_pk_bf16(b[0], b[1]); w.w = cvt_pk_bf16(b[2], b[3]); return w; }
; __global__ void __launch_bounds__(512, 2) fwd_mega(Args a) {
;     ...
;             { const int jlo = (s0 - hw) > 0 ? (s0 - hw) : 0, jhi = (s0 + hw) < SEQ ? (s0 + hw) : SEQ;
;               for (int j = jlo; j < jhi; ++j) { f32x4 a0, a1; pg8::unpack8(*(const u32x4*)(base + (size_t)j * 512), a0, a1); w0 += a0; w1 += a1; } }
;     ...
;             for (int s = s0; s < s0 + 32; ++s) {
;                 f32x4 u0, u1; pg8::unpack8(*(const u32x4*)(base + (size_t)s * 512), u0, u1);
;                 const int jlo = (s - hw) > 0 ? (s - hw) : 0, jhi = (s + hw) < SEQ ? (s + hw) : SEQ;
;                 const float rc = 1.0f / (float)(jhi - jlo);
;                 *(u32x4*)(obase + (size_t)s * 1024) = pg8::pack8(w0 * rc - u0, w1 * rc - u1);
;                 if (s + hw < SEQ) { f32x4 a0, a1; pg8::unpack8(*(const u32x4*)(base + (size_t)(s + hw) * 512), a0, a1); w0 += a0; w1 += a1; }
;                 if (s - hw >= 0) { f32x4 a0, a1; pg8::unpack8(*(const u32x4*)(base + (size_t)(s - hw) * 512), a0, a1); w0 -= a0; w1 -= a1; }
.Lpool_g1_nomask:
	v_lshlrev_b32_e32 v124, 16, v0
	v_and_b32_e32 v125, 0xffff0000, v0
	v_lshlrev_b32_e32 v126, 16, v1
	v_and_b32_e32 v127, 0xffff0000, v1
	v_lshlrev_b32_e32 v128, 16, v2
	v_and_b32_e32 v129, 0xffff0000, v2
	v_lshlrev_b32_e32 v130, 16, v3
	v_and_b32_e32 v131, 0xffff0000, v3
	v_lshlrev_b32_e32 v132, 16, v4
	v_and_b32_e32 v133, 0xffff0000, v4
	v_lshlrev_b32_e32 v134, 16, v5
	v_and_b32_e32 v135, 0xffff0000, v5
	v_lshlrev_b32_e32 v136, 16, v6
	v_and_b32_e32 v137, 0xffff0000, v6
	v_lshlrev_b32_e32 v138, 16, v7
	v_and_b32_e32 v139, 0xffff0000, v7
	v_pk_add_f32 v[124:125], v[124:125], v[132:133]
	v_pk_add_f32 v[126:127], v[126:127], v[134:135]
	v_pk_add_f32 v[128:129], v[128:129], v[136:137]
	v_pk_add_f32 v[130:131], v[130:131], v[138:139]
	v_lshlrev_b32_e32 v132, 16, v8
	v_and_b32_e32 v133, 0xffff0000, v8
	v_lshlrev_b32_e32 v134, 16, v9
	v_and_b32_e32 v135, 0xffff0000, v9
	v_lshlrev_b32_e32 v136, 16, v10
	v_and_b32_e32 v137, 0xffff0000, v10
	v_lshlrev_b32_e32 v138, 16, v11
	v_and_b32_e32 v139, 0xffff0000, v11
	v_pk_add_f32 v[124:125], v[124:125], v[132:133]
	v_pk_add_f32 v[126:127], v[126:127], v[134:135]
	v_pk_add_f32 v[128:129], v[128:129], v[136:137]
	v_pk_add_f32 v[130:131], v[130:131], v[138:139]
	v_lshlrev_b32_e32 v132, 16, v12
	v_and_b32_e32 v133, 0xffff0000, v12
	v_lshlrev_b32_e32 v134, 16, v13
	v_and_b32_e32 v135, 0xffff0000, v13
	v_lshlrev_b32_e32 v136, 16, v14
	v_and_b32_e32 v137, 0xffff0000, v14
	v_lshlrev_b32_e32 v138, 16, v15
	v_and_b32_e32 v139, 0xffff0000, v15
	v_pk_add_f32 v[124:125], v[124:125], v[132:133]
	v_pk_add_f32 v[126:127], v[126:127], v[134:135]
	v_pk_add_f32 v[128:129], v[128:129], v[136:137]
	v_pk_add_f32 v[130:131], v[130:131], v[138:139]
	v_add_u32_e32 v170, 2, v169
	v_min_u32_e32 v170, s56, v170
	v_add_u32_e32 v171, -2, v169
	v_max_i32_e32 v171, 0, v171
	v_sub_u32_e32 v170, v170, v171
	v_cvt_f32_u32_e32 v170, v170
	v_rcp_f32_e32 v174, v170
	v_lshlrev_b32_e32 v132, 16, v8
	v_and_b32_e32 v133, 0xffff0000, v8
	v_lshlrev_b32_e32 v134, 16, v9
	v_and_b32_e32 v135, 0xffff0000, v9
	v_lshlrev_b32_e32 v136, 16, v10
	v_and_b32_e32 v137, 0xffff0000, v10
	v_lshlrev_b32_e32 v138, 16, v11
	v_and_b32_e32 v139, 0xffff0000, v11
	v_pk_fma_f32 v[140:141], v[124:125], v[174:175], v[132:133] op_sel_hi:[1,0,1] neg_lo:[0,0,1] neg_hi:[0,0,1]
	v_pk_fma_f32 v[142:143], v[126:127], v[174:175], v[134:135] op_sel_hi:[1,0,1] neg_lo:[0,0,1] neg_hi:[0,0,1]
	v_pk_fma_f32 v[144:145], v[128:129], v[174:175], v[136:137] op_sel_hi:[1,0,1] neg_lo:[0,0,1] neg_hi:[0,0,1]
	v_pk_fma_f32 v[146:147], v[130:131], v[174:175], v[138:139] op_sel_hi:[1,0,1] neg_lo:[0,0,1] neg_hi:[0,0,1]
	v_cvt_pk_bf16_f32 v148, v140, v141
	v_cvt_pk_bf16_f32 v149, v142, v143
	v_cvt_pk_bf16_f32 v150, v144, v145
	v_cvt_pk_bf16_f32 v151, v146, v147
	global_store_dwordx4 v168, v[148:151], s[54:55]
	v_add_u32_e32 v168, 0x800, v168
	v_lshlrev_b32_e32 v132, 16, v16
	v_and_b32_e32 v133, 0xffff0000, v16
	v_lshlrev_b32_e32 v134, 16, v17
	v_and_b32_e32 v135, 0xffff0000, v17
	v_lshlrev_b32_e32 v136, 16, v18
	v_and_b32_e32 v137, 0xffff0000, v18
	v_lshlrev_b32_e32 v138, 16, v19
	v_and_b32_e32 v139, 0xffff0000, v19
	v_lshlrev_b32_e32 v140, 16, v0
	v_and_b32_e32 v141, 0xffff0000, v0
	v_lshlrev_b32_e32 v142, 16, v1
	v_and_b32_e32 v143, 0xffff0000, v1
	v_lshlrev_b32_e32 v144, 16, v2
	v_and_b32_e32 v145, 0xffff0000, v2
	v_lshlrev_b32_e32 v146, 16, v3
	v_and_b32_e32 v147, 0xffff0000, v3
	v_pk_add_f32 v[124:125], v[124:125], v[132:133]
	v_pk_add_f32 v[126:127], v[126:127], v[134:135]
	v_pk_add_f32 v[128:129], v[128:129], v[136:137]
	v_pk_add_f32 v[130:131], v[130:131], v[138:139]
	v_pk_add_f32 v[124:125], v[124:125], v[140:141] neg_lo:[0,1] neg_hi:[0,1]
	v_pk_add_f32 v[126:127], v[126:127], v[142:143] neg_lo:[0,1] neg_hi:[0,1]
	v_pk_add_f32 v[128:129], v[128:129], v[144:145] neg_lo:[0,1] neg_hi:[0,1]
	v_pk_add_f32 v[130:131], v[130:131], v[146:147] neg_lo:[0,1] neg_hi:[0,1]
	v_add_u32_e32 v170, 3, v169
	v_min_u32_e32 v170, s56, v170
	v_add_u32_e32 v171, -1, v169
	v_max_i32_e32 v171, 0, v171
	v_sub_u32_e32 v170, v170, v171
	v_cvt_f32_u32_e32 v170, v170
	v_rcp_f32_e32 v174, v170
	v_lshlrev_b32_e32 v132, 16, v12
	v_and_b32_e32 v133, 0xffff0000, v12
	v_lshlrev_b32_e32 v134, 16, v13
	v_and_b32_e32 v135, 0xffff0000, v13
	v_lshlrev_b32_e32 v136, 16, v14
	v_and_b32_e32 v137, 0xffff0000, v14
	v_lshlrev_b32_e32 v138, 16, v15
	v_and_b32_e32 v139, 0xffff0000, v15
	v_pk_fma_f32 v[140:141], v[124:125], v[174:175], v[132:133] op_sel_hi:[1,0,1] neg_lo:[0,0,1] neg_hi:[0,0,1]
	v_pk_fma_f32 v[142:143], v[126:127], v[174:175], v[134:135] op_sel_hi:[1,0,1] neg_lo:[0,0,1] neg_hi:[0,0,1]
	v_pk_fma_f32 v[144:145], v[128:129], v[174:175], v[136:137] op_sel_hi:[1,0,1] neg_lo:[0,0,1] neg_hi:[0,0,1]
	v_pk_fma_f32 v[146:147], v[130:131], v[174:175], v[138:139] op_sel_hi:[1,0,1] neg_lo:[0,0,1] neg_hi:[0,0,1]
	v_cvt_pk_bf16_f32 v148, v140, v141
	v_cvt_pk_bf16_f32 v149, v142, v143
	v_cvt_pk_bf16_f32 v150, v144, v145
	v_cvt_pk_bf16_f32 v151, v146, v147
	global_store_dwordx4 v168, v[148:151], s[54:55]
	v_add_u32_e32 v168, 0x800, v168
	v_lshlrev_b32_e32 v132, 16, v20
	v_and_b32_e32 v133, 0xffff0000, v20
	v_lshlrev_b32_e32 v134, 16, v21
	v_and_b32_e32 v135, 0xffff0000, v21
	v_lshlrev_b32_e32 v136, 16, v22
	v_and_b32_e32 v137, 0xffff0000, v22
	v_lshlrev_b32_e32 v138, 16, v23
	v_and_b32_e32 v139, 0xffff0000, v23
	v_lshlrev_b32_e32 v140, 16, v4
	v_and_b32_e32 v141, 0xffff0000, v4
	v_lshlrev_b32_e32 v142, 16, v5
	v_and_b32_e32 v143, 0xffff0000, v5
	v_lshlrev_b32_e32 v144, 16, v6
	v_and_b32_e32 v145, 0xffff0000, v6
	v_lshlrev_b32_e32 v146, 16, v7
	v_and_b32_e32 v147, 0xffff0000, v7
	v_pk_add_f32 v[124:125], v[124:125], v[132:133]
; __device__ __forceinline__ u32x4 pack8(const f32x4 a, const f32x4 b) { u32x4 w; w.x = cvt_pk_bf16(a[0], a[1]); w.y = cvt_pk_bf16(a[2], a[3]); w.z = cvt_pk_bf16(b[0], b[1]); w.w = cvt_pk_bf16(b[2], b[3]); return w; }
; __global__ void __launch_bounds__(512, 2) fwd_mega(Args a) {
;     ...
;             for (int s = s0; s < s0 + 32; ++s) {
;                 f32x4 u0, u1; pg8::unpack8(*(const u32x4*)(base + (size_t)s * 512), u0, u1);
;                 const int jlo = (s - hw) > 0 ? (s - hw) : 0, jhi = (s + hw) < SEQ ? (s + hw) : SEQ;
;                 const float rc = 1.0f / (float)(jhi - jlo);
;                 *(u32x4*)(obase + (size_t)s * 1024) = pg8::pack8(w0 * rc - u0, w1 * rc - u1);
;                 if (s + hw < SEQ) { f32x4 a0, a1; pg8::unpack8(*(const u32x4*)(base + (size_t)(s + hw) * 512), a0, a1); w0 += a0; w1 += a1; }
;                 if (s - hw >= 0) { f32x4 a0, a1; pg8::unpack8(*(const u32x4*)(base + (size_t)(s - hw) * 512), a0, a1); w0 -= a0; w1 -= a1; }
	v_pk_add_f32 v[126:127], v[126:127], v[134:135]
	v_pk_add_f32 v[128:129], v[128:129], v[136:137]
	v_pk_add_f32 v[130:131], v[130:131], v[138:139]
	v_pk_add_f32 v[124:125], v[124:125], v[140:141] neg_lo:[0,1] neg_hi:[0,1]
	v_pk_add_f32 v[126:127], v[126:127], v[142:143] neg_lo:[0,1] neg_hi:[0,1]
	v_pk_add_f32 v[128:129], v[128:129], v[144:145] neg_lo:[0,1] neg_hi:[0,1]
	v_pk_add_f32 v[130:131], v[130:131], v[146:147] neg_lo:[0,1] neg_hi:[0,1]
	v_add_u32_e32 v170, 4, v169
	v_min_u32_e32 v170, s56, v170
	v_add_u32_e32 v171, 0, v169
	v_max_i32_e32 v171, 0, v171
	v_sub_u32_e32 v170, v170, v171
	v_cvt_f32_u32_e32 v170, v170
	v_rcp_f32_e32 v174, v170
	v_lshlrev_b32_e32 v132, 16, v16
	v_and_b32_e32 v133, 0xffff0000, v16
	v_lshlrev_b32_e32 v134, 16, v17
	v_and_b32_e32 v135, 0xffff0000, v17
	v_lshlrev_b32_e32 v136, 16, v18
	v_and_b32_e32 v137, 0xffff0000, v18
	v_lshlrev_b32_e32 v138, 16, v19
	v_and_b32_e32 v139, 0xffff0000, v19
	v_pk_fma_f32 v[140:141], v[124:125], v[174:175], v[132:133] op_sel_hi:[1,0,1] neg_lo:[0,0,1] neg_hi:[0,0,1]
	v_pk_fma_f32 v[142:143], v[126:127], v[174:175], v[134:135] op_sel_hi:[1,0,1] neg_lo:[0,0,1] neg_hi:[0,0,1]
	v_pk_fma_f32 v[144:145], v[128:129], v[174:175], v[136:137] op_sel_hi:[1,0,1] neg_lo:[0,0,1] neg_hi:[0,0,1]
	v_pk_fma_f32 v[146:147], v[130:131], v[174:175], v[138:139] op_sel_hi:[1,0,1] neg_lo:[0,0,1] neg_hi:[0,0,1]
	v_cvt_pk_bf16_f32 v148, v140, v141
	v_cvt_pk_bf16_f32 v149, v142, v143
	v_cvt_pk_bf16_f32 v150, v144, v145
	v_cvt_pk_bf16_f32 v151, v146, v147
	global_store_dwordx4 v168, v[148:151], s[54:55]
	v_add_u32_e32 v168, 0x800, v168
	v_lshlrev_b32_e32 v132, 16, v24
	v_and_b32_e32 v133, 0xffff0000, v24
	v_lshlrev_b32_e32 v134, 16, v25
	v_and_b32_e32 v135, 0xffff0000, v25
	v_lshlrev_b32_e32 v136, 16, v26
	v_and_b32_e32 v137, 0xffff0000, v26
	v_lshlrev_b32_e32 v138, 16, v27
	v_and_b32_e32 v139, 0xffff0000, v27
	v_lshlrev_b32_e32 v140, 16, v8
	v_and_b32_e32 v141, 0xffff0000, v8
	v_lshlrev_b32_e32 v142, 16, v9
	v_and_b32_e32 v143, 0xffff0000, v9
	v_lshlrev_b32_e32 v144, 16, v10
	v_and_b32_e32 v145, 0xffff0000, v10
	v_lshlrev_b32_e32 v146, 16, v11
	v_and_b32_e32 v147, 0xffff0000, v11
	v_pk_add_f32 v[124:125], v[124:125], v[132:133]
	v_pk_add_f32 v[126:127], v[126:127], v[134:135]
	v_pk_add_f32 v[128:129], v[128:129], v[136:137]
	v_pk_add_f32 v[130:131], v[130:131], v[138:139]
	v_pk_add_f32 v[124:125], v[124:125], v[140:141] neg_lo:[0,1] neg_hi:[0,1]
	v_pk_add_f32 v[126:127], v[126:127], v[142:143] neg_lo:[0,1] neg_hi:[0,1]
	v_pk_add_f32 v[128:129], v[128:129], v[144:145] neg_lo:[0,1] neg_hi:[0,1]
	v_pk_add_f32 v[130:131], v[130:131], v[146:147] neg_lo:[0,1] neg_hi:[0,1]
	v_add_u32_e32 v170, 5, v169
	v_min_u32_e32 v170, s56, v170
	v_add_u32_e32 v171, 1, v169
	v_max_i32_e32 v171, 0, v171
	v_sub_u32_e32 v170, v170, v171
	v_cvt_f32_u32_e32 v170, v170
	v_rcp_f32_e32 v174, v170
	v_lshlrev_b32_e32 v132, 16, v20
	v_and_b32_e32 v133, 0xffff0000, v20
	v_lshlrev_b32_e32 v134, 16, v21
	v_and_b32_e32 v135, 0xffff0000, v21
	v_lshlrev_b32_e32 v136, 16, v22
	v_and_b32_e32 v137, 0xffff0000, v22
	v_lshlrev_b32_e32 v138, 16, v23
	v_and_b32_e32 v139, 0xffff0000, v23
	v_pk_fma_f32 v[140:141], v[124:125], v[174:175], v[132:133] op_sel_hi:[1,0,1] neg_lo:[0,0,1] neg_hi:[0,0,1]
	v_pk_fma_f32 v[142:143], v[126:127], v[174:175], v[134:135] op_sel_hi:[1,0,1] neg_lo:[0,0,1] neg_hi:[0,0,1]
	v_pk_fma_f32 v[144:145], v[128:129], v[174:175], v[136:137] op_sel_hi:[1,0,1] neg_lo:[0,0,1] neg_hi:[0,0,1]
	v_pk_fma_f32 v[146:147], v[130:131], v[174:175], v[138:139] op_sel_hi:[1,0,1] neg_lo:[0,0,1] neg_hi:[0,0,1]
	v_cvt_pk_bf16_f32 v148, v140, v141
	v_cvt_pk_bf16_f32 v149, v142, v143
	v_cvt_pk_bf16_f32 v150, v144, v145
	v_cvt_pk_bf16_f32 v151, v146, v147
	global_store_dwordx4 v168, v[148:151], s[54:55]
	v_add_u32_e32 v168, 0x800, v168
	v_lshlrev_b32_e32 v132, 16, v28
	v_and_b32_e32 v133, 0xffff0000, v28
	v_lshlrev_b32_e32 v134, 16, v29
	v_and_b32_e32 v135, 0xffff0000, v29
	v_lshlrev_b32_e32 v136, 16, v30
	v_and_b32_e32 v137, 0xffff0000, v30
	v_lshlrev_b32_e32 v138, 16, v31
	v_and_b32_e32 v139, 0xffff0000, v31
	v_lshlrev_b32_e32 v140, 16, v12
	v_and_b32_e32 v141, 0xffff0000, v12
	v_lshlrev_b32_e32 v142, 16, v13
	v_and_b32_e32 v143, 0xffff0000, v13
	v_lshlrev_b32_e32 v144, 16, v14
	v_and_b32_e32 v145, 0xffff0000, v14
	v_lshlrev_b32_e32 v146, 16, v15
	v_and_b32_e32 v147, 0xffff0000, v15
	v_pk_add_f32 v[124:125], v[124:125], v[132:133]
	v_pk_add_f32 v[126:127], v[126:127], v[134:135]
	v_pk_add_f32 v[128:129], v[128:129], v[136:137]
	v_pk_add_f32 v[130:131], v[130:131], v[138:139]
	v_pk_add_f32 v[124:125], v[124:125], v[140:141] neg_lo:[0,1] neg_hi:[0,1]
	v_pk_add_f32 v[126:127], v[126:127], v[142:143] neg_lo:[0,1] neg_hi:[0,1]
	v_pk_add_f32 v[128:129], v[128:129], v[144:145] neg_lo:[0,1] neg_hi:[0,1]
	v_pk_add_f32 v[130:131], v[130:131], v[146:147] neg_lo:[0,1] neg_hi:[0,1]
	v_add_u32_e32 v170, 6, v169
	v_min_u32_e32 v170, s56, v170
	v_add_u32_e32 v171, 2, v169
	v_max_i32_e32 v171, 0, v171
	v_sub_u32_e32 v170, v170, v171
	v_cvt_f32_u32_e32 v170, v170
	v_rcp_f32_e32 v174, v170
	v_lshlrev_b32_e32 v132, 16, v24
	v_and_b32_e32 v133, 0xffff0000, v24
	v_lshlrev_b32_e32 v134, 16, v25
	v_and_b32_e32 v135, 0xffff0000, v25
	v_lshlrev_b32_e32 v136, 16, v26
	v_and_b32_e32 v137, 0xffff0000, v26
	v_lshlrev_b32_e32 v138, 16, v27
	v_and_b32_e32 v139, 0xffff0000, v27
	v_pk_fma_f32 v[140:141], v[124:125], v[174:175], v[132:133] op_sel_hi:[1,0,1] neg_lo:[0,0,1] neg_hi:[0,0,1]
	v_pk_fma_f32 v[142:143], v[126:127], v[174:175], v[134:135] op_sel_hi:[1,0,1] neg_lo:[0,0,1] neg_hi:[0,0,1]
	v_pk_fma_f32 v[144:145], v[128:129], v[174:175], v[136:137] op_sel_hi:[1,0,1] neg_lo:[0,0,1] neg_hi:[0,0,1]
; __device__ __forceinline__ u32x4 pack8(const f32x4 a, const f32x4 b) { u32x4 w; w.x = cvt_pk_bf16(a[0], a[1]); w.y = cvt_pk_bf16(a[2], a[3]); w.z = cvt_pk_bf16(b[0], b[1]); w.w = cvt_pk_bf16(b[2], b[3]); return w; }
; __global__ void __launch_bounds__(512, 2) fwd_mega(Args a) {
;     ...
;             for (int s = s0; s < s0 + 32; ++s) {
;                 f32x4 u0, u1; pg8::unpack8(*(const u32x4*)(base + (size_t)s * 512), u0, u1);
;                 const int jlo = (s - hw) > 0 ? (s - hw) : 0, jhi = (s + hw) < SEQ ? (s + hw) : SEQ;
;                 const float rc = 1.0f / (float)(jhi - jlo);
;                 *(u32x4*)(obase + (size_t)s * 1024) = pg8::pack8(w0 * rc - u0, w1 * rc - u1);
;                 if (s + hw < SEQ) { f32x4 a0, a1; pg8::unpack8(*(const u32x4*)(base + (size_t)(s + hw) * 512), a0, a1); w0 += a0; w1 += a1; }
;                 if (s - hw >= 0) { f32x4 a0, a1; pg8::unpack8(*(const u32x4*)(base + (size_t)(s - hw) * 512), a0, a1); w0 -= a0; w1 -= a1; }
	v_pk_fma_f32 v[146:147], v[130:131], v[174:175], v[138:139] op_sel_hi:[1,0,1] neg_lo:[0,0,1] neg_hi:[0,0,1]
	v_cvt_pk_bf16_f32 v148, v140, v141
	v_cvt_pk_bf16_f32 v149, v142, v143
	v_cvt_pk_bf16_f32 v150, v144, v145
	v_cvt_pk_bf16_f32 v151, v146, v147
	global_store_dwordx4 v168, v[148:151], s[54:55]
	v_add_u32_e32 v168, 0x800, v168
	v_lshlrev_b32_e32 v132, 16, v32
	v_and_b32_e32 v133, 0xffff0000, v32
	v_lshlrev_b32_e32 v134, 16, v33
	v_and_b32_e32 v135, 0xffff0000, v33
	v_lshlrev_b32_e32 v136, 16, v34
	v_and_b32_e32 v137, 0xffff0000, v34
	v_lshlrev_b32_e32 v138, 16, v35
	v_and_b32_e32 v139, 0xffff0000, v35
	v_lshlrev_b32_e32 v140, 16, v16
	v_and_b32_e32 v141, 0xffff0000, v16
	v_lshlrev_b32_e32 v142, 16, v17
	v_and_b32_e32 v143, 0xffff0000, v17
	v_lshlrev_b32_e32 v144, 16, v18
	v_and_b32_e32 v145, 0xffff0000, v18
	v_lshlrev_b32_e32 v146, 16, v19
	v_and_b32_e32 v147, 0xffff0000, v19
	v_pk_add_f32 v[124:125], v[124:125], v[132:133]
	v_pk_add_f32 v[126:127], v[126:127], v[134:135]
	v_pk_add_f32 v[128:129], v[128:129], v[136:137]
	v_pk_add_f32 v[130:131], v[130:131], v[138:139]
	v_pk_add_f32 v[124:125], v[124:125], v[140:141] neg_lo:[0,1] neg_hi:[0,1]
	v_pk_add_f32 v[126:127], v[126:127], v[142:143] neg_lo:[0,1] neg_hi:[0,1]
	v_pk_add_f32 v[128:129], v[128:129], v[144:145] neg_lo:[0,1] neg_hi:[0,1]
	v_pk_add_f32 v[130:131], v[130:131], v[146:147] neg_lo:[0,1] neg_hi:[0,1]
	v_add_u32_e32 v170, 7, v169
	v_min_u32_e32 v170, s56, v170
	v_add_u32_e32 v171, 3, v169
	v_max_i32_e32 v171, 0, v171
	v_sub_u32_e32 v170, v170, v171
	v_cvt_f32_u32_e32 v170, v170
	v_rcp_f32_e32 v174, v170
	v_lshlrev_b32_e32 v132, 16, v28
	v_and_b32_e32 v133, 0xffff0000, v28
	v_lshlrev_b32_e32 v134, 16, v29
	v_and_b32_e32 v135, 0xffff0000, v29
	v_lshlrev_b32_e32 v136, 16, v30
	v_and_b32_e32 v137, 0xffff0000, v30
	v_lshlrev_b32_e32 v138, 16, v31
	v_and_b32_e32 v139, 0xffff0000, v31
	v_pk_fma_f32 v[140:141], v[124:125], v[174:175], v[132:133] op_sel_hi:[1,0,1] neg_lo:[0,0,1] neg_hi:[0,0,1]
	v_pk_fma_f32 v[142:143], v[126:127], v[174:175], v[134:135] op_sel_hi:[1,0,1] neg_lo:[0,0,1] neg_hi:[0,0,1]
	v_pk_fma_f32 v[144:145], v[128:129], v[174:175], v[136:137] op_sel_hi:[1,0,1] neg_lo:[0,0,1] neg_hi:[0,0,1]
	v_pk_fma_f32 v[146:147], v[130:131], v[174:175], v[138:139] op_sel_hi:[1,0,1] neg_lo:[0,0,1] neg_hi:[0,0,1]
	v_cvt_pk_bf16_f32 v148, v140, v141
	v_cvt_pk_bf16_f32 v149, v142, v143
	v_cvt_pk_bf16_f32 v150, v144, v145
	v_cvt_pk_bf16_f32 v151, v146, v147
	global_store_dwordx4 v168, v[148:151], s[54:55]
	v_add_u32_e32 v168, 0x800, v168
	v_lshlrev_b32_e32 v132, 16, v36
	v_and_b32_e32 v133, 0xffff0000, v36
	v_lshlrev_b32_e32 v134, 16, v37
	v_and_b32_e32 v135, 0xffff0000, v37
	v_lshlrev_b32_e32 v136, 16, v38
	v_and_b32_e32 v137, 0xffff0000, v38
	v_lshlrev_b32_e32 v138, 16, v39
	v_and_b32_e32 v139, 0xffff0000, v39
	v_lshlrev_b32_e32 v140, 16, v20
	v_and_b32_e32 v141, 0xffff0000, v20
	v_lshlrev_b32_e32 v142, 16, v21
	v_and_b32_e32 v143, 0xffff0000, v21
	v_lshlrev_b32_e32 v144, 16, v22
	v_and_b32_e32 v145, 0xffff0000, v22
	v_lshlrev_b32_e32 v146, 16, v23
	v_and_b32_e32 v147, 0xffff0000, v23
	v_pk_add_f32 v[124:125], v[124:125], v[132:133]
	v_pk_add_f32 v[126:127], v[126:127], v[134:135]
	v_pk_add_f32 v[128:129], v[128:129], v[136:137]
	v_pk_add_f32 v[130:131], v[130:131], v[138:139]
	v_pk_add_f32 v[124:125], v[124:125], v[140:141] neg_lo:[0,1] neg_hi:[0,1]
	v_pk_add_f32 v[126:127], v[126:127], v[142:143] neg_lo:[0,1] neg_hi:[0,1]
	v_pk_add_f32 v[128:129], v[128:129], v[144:145] neg_lo:[0,1] neg_hi:[0,1]
	v_pk_add_f32 v[130:131], v[130:131], v[146:147] neg_lo:[0,1] neg_hi:[0,1]
	v_add_u32_e32 v170, 8, v169
	v_min_u32_e32 v170, s56, v170
	v_add_u32_e32 v171, 4, v169
	v_max_i32_e32 v171, 0, v171
	v_sub_u32_e32 v170, v170, v171
	v_cvt_f32_u32_e32 v170, v170
	v_rcp_f32_e32 v174, v170
	v_lshlrev_b32_e32 v132, 16, v32
	v_and_b32_e32 v133, 0xffff0000, v32
	v_lshlrev_b32_e32 v134, 16, v33
	v_and_b32_e32 v135, 0xffff0000, v33
	v_lshlrev_b32_e32 v136, 16, v34
	v_and_b32_e32 v137, 0xffff0000, v34
	v_lshlrev_b32_e32 v138, 16, v35
	v_and_b32_e32 v139, 0xffff0000, v35
	v_pk_fma_f32 v[140:141], v[124:125], v[174:175], v[132:133] op_sel_hi:[1,0,1] neg_lo:[0,0,1] neg_hi:[0,0,1]
	v_pk_fma_f32 v[142:143], v[126:127], v[174:175], v[134:135] op_sel_hi:[1,0,1] neg_lo:[0,0,1] neg_hi:[0,0,1]
	v_pk_fma_f32 v[144:145], v[128:129], v[174:175], v[136:137] op_sel_hi:[1,0,1] neg_lo:[0,0,1] neg_hi:[0,0,1]
	v_pk_fma_f32 v[146:147], v[130:131], v[174:175], v[138:139] op_sel_hi:[1,0,1] neg_lo:[0,0,1] neg_hi:[0,0,1]
	v_cvt_pk_bf16_f32 v148, v140, v141
	v_cvt_pk_bf16_f32 v149, v142, v143
	v_cvt_pk_bf16_f32 v150, v144, v145
	v_cvt_pk_bf16_f32 v151, v146, v147
	global_store_dwordx4 v168, v[148:151], s[54:55]
	v_add_u32_e32 v168, 0x800, v168
	v_lshlrev_b32_e32 v132, 16, v40
	v_and_b32_e32 v133, 0xffff0000, v40
	v_lshlrev_b32_e32 v134, 16, v41
	v_and_b32_e32 v135, 0xffff0000, v41
	v_lshlrev_b32_e32 v136, 16, v42
	v_and_b32_e32 v137, 0xffff0000, v42
	v_lshlrev_b32_e32 v138, 16, v43
	v_and_b32_e32 v139, 0xffff0000, v43
	v_lshlrev_b32_e32 v140, 16, v24
	v_and_b32_e32 v141, 0xffff0000, v24
	v_lshlrev_b32_e32 v142, 16, v25
	v_and_b32_e32 v143, 0xffff0000, v25
	v_lshlrev_b32_e32 v144, 16, v26
	v_and_b32_e32 v145, 0xffff0000, v26
	v_lshlrev_b32_e32 v146, 16, v27
	v_and_b32_e32 v147, 0xffff0000, v27
	v_pk_add_f32 v[124:125], v[124:125], v[132:133]
	v_pk_add_f32 v[126:127], v[126:127], v[134:135]
	v_pk_add_f32 v[128:129], v[128:129], v[136:137]
	v_pk_add_f32 v[130:131], v[130:131], v[138:139]
	v_pk_add_f32 v[124:125], v[124:125], v[140:141] neg_lo:[0,1] neg_hi:[0,1]
	v_pk_add_f32 v[126:127], v[126:127], v[142:143] neg_lo:[0,1] neg_hi:[0,1]
; __device__ __forceinline__ u32x4 pack8(const f32x4 a, const f32x4 b) { u32x4 w; w.x = cvt_pk_bf16(a[0], a[1]); w.y = cvt_pk_bf16(a[2], a[3]); w.z = cvt_pk_bf16(b[0], b[1]); w.w = cvt_pk_bf16(b[2], b[3]); return w; }
; __global__ void __launch_bounds__(512, 2) fwd_mega(Args a) {
;     ...
;             for (int s = s0; s < s0 + 32; ++s) {
;                 f32x4 u0, u1; pg8::unpack8(*(const u32x4*)(base + (size_t)s * 512), u0, u1);
;                 const int jlo = (s - hw) > 0 ? (s - hw) : 0, jhi = (s + hw) < SEQ ? (s + hw) : SEQ;
;                 const float rc = 1.0f / (float)(jhi - jlo);
;                 *(u32x4*)(obase + (size_t)s * 1024) = pg8::pack8(w0 * rc - u0, w1 * rc - u1);
;                 if (s + hw < SEQ) { f32x4 a0, a1; pg8::unpack8(*(const u32x4*)(base + (size_t)(s + hw) * 512), a0, a1); w0 += a0; w1 += a1; }
;                 if (s - hw >= 0) { f32x4 a0, a1; pg8::unpack8(*(const u32x4*)(base + (size_t)(s - hw) * 512), a0, a1); w0 -= a0; w1 -= a1; }
	v_pk_add_f32 v[128:129], v[128:129], v[144:145] neg_lo:[0,1] neg_hi:[0,1]
	v_pk_add_f32 v[130:131], v[130:131], v[146:147] neg_lo:[0,1] neg_hi:[0,1]
	v_add_u32_e32 v170, 9, v169
	v_min_u32_e32 v170, s56, v170
	v_add_u32_e32 v171, 5, v169
	v_max_i32_e32 v171, 0, v171
	v_sub_u32_e32 v170, v170, v171
	v_cvt_f32_u32_e32 v170, v170
	v_rcp_f32_e32 v174, v170
	v_lshlrev_b32_e32 v132, 16, v36
	v_and_b32_e32 v133, 0xffff0000, v36
	v_lshlrev_b32_e32 v134, 16, v37
	v_and_b32_e32 v135, 0xffff0000, v37
	v_lshlrev_b32_e32 v136, 16, v38
	v_and_b32_e32 v137, 0xffff0000, v38
	v_lshlrev_b32_e32 v138, 16, v39
	v_and_b32_e32 v139, 0xffff0000, v39
	v_pk_fma_f32 v[140:141], v[124:125], v[174:175], v[132:133] op_sel_hi:[1,0,1] neg_lo:[0,0,1] neg_hi:[0,0,1]
	v_pk_fma_f32 v[142:143], v[126:127], v[174:175], v[134:135] op_sel_hi:[1,0,1] neg_lo:[0,0,1] neg_hi:[0,0,1]
	v_pk_fma_f32 v[144:145], v[128:129], v[174:175], v[136:137] op_sel_hi:[1,0,1] neg_lo:[0,0,1] neg_hi:[0,0,1]
	v_pk_fma_f32 v[146:147], v[130:131], v[174:175], v[138:139] op_sel_hi:[1,0,1] neg_lo:[0,0,1] neg_hi:[0,0,1]
	v_cvt_pk_bf16_f32 v148, v140, v141
	v_cvt_pk_bf16_f32 v149, v142, v143
	v_cvt_pk_bf16_f32 v150, v144, v145
	v_cvt_pk_bf16_f32 v151, v146, v147
	global_store_dwordx4 v168, v[148:151], s[54:55]
	v_add_u32_e32 v168, 0x800, v168
	v_lshlrev_b32_e32 v132, 16, v44
	v_and_b32_e32 v133, 0xffff0000, v44
	v_lshlrev_b32_e32 v134, 16, v45
	v_and_b32_e32 v135, 0xffff0000, v45
	v_lshlrev_b32_e32 v136, 16, v46
	v_and_b32_e32 v137, 0xffff0000, v46
	v_lshlrev_b32_e32 v138, 16, v47
	v_and_b32_e32 v139, 0xffff0000, v47
	v_lshlrev_b32_e32 v140, 16, v28
	v_and_b32_e32 v141, 0xffff0000, v28
	v_lshlrev_b32_e32 v142, 16, v29
	v_and_b32_e32 v143, 0xffff0000, v29
	v_lshlrev_b32_e32 v144, 16, v30
	v_and_b32_e32 v145, 0xffff0000, v30
	v_lshlrev_b32_e32 v146, 16, v31
	v_and_b32_e32 v147, 0xffff0000, v31
	v_pk_add_f32 v[124:125], v[124:125], v[132:133]
	v_pk_add_f32 v[126:127], v[126:127], v[134:135]
	v_pk_add_f32 v[128:129], v[128:129], v[136:137]
	v_pk_add_f32 v[130:131], v[130:131], v[138:139]
	v_pk_add_f32 v[124:125], v[124:125], v[140:141] neg_lo:[0,1] neg_hi:[0,1]
	v_pk_add_f32 v[126:127], v[126:127], v[142:143] neg_lo:[0,1] neg_hi:[0,1]
	v_pk_add_f32 v[128:129], v[128:129], v[144:145] neg_lo:[0,1] neg_hi:[0,1]
	v_pk_add_f32 v[130:131], v[130:131], v[146:147] neg_lo:[0,1] neg_hi:[0,1]
	v_add_u32_e32 v170, 10, v169
	v_min_u32_e32 v170, s56, v170
	v_add_u32_e32 v171, 6, v169
	v_max_i32_e32 v171, 0, v171
	v_sub_u32_e32 v170, v170, v171
	v_cvt_f32_u32_e32 v170, v170
	v_rcp_f32_e32 v174, v170
	v_lshlrev_b32_e32 v132, 16, v40
	v_and_b32_e32 v133, 0xffff0000, v40
	v_lshlrev_b32_e32 v134, 16, v41
	v_and_b32_e32 v135, 0xffff0000, v41
	v_lshlrev_b32_e32 v136, 16, v42
	v_and_b32_e32 v137, 0xffff0000, v42
	v_lshlrev_b32_e32 v138, 16, v43
	v_and_b32_e32 v139, 0xffff0000, v43
	v_pk_fma_f32 v[140:141], v[124:125], v[174:175], v[132:133] op_sel_hi:[1,0,1] neg_lo:[0,0,1] neg_hi:[0,0,1]
	v_pk_fma_f32 v[142:143], v[126:127], v[174:175], v[134:135] op_sel_hi:[1,0,1] neg_lo:[0,0,1] neg_hi:[0,0,1]
	v_pk_fma_f32 v[144:145], v[128:129], v[174:175], v[136:137] op_sel_hi:[1,0,1] neg_lo:[0,0,1] neg_hi:[0,0,1]
	v_pk_fma_f32 v[146:147], v[130:131], v[174:175], v[138:139] op_sel_hi:[1,0,1] neg_lo:[0,0,1] neg_hi:[0,0,1]
	v_cvt_pk_bf16_f32 v148, v140, v141
	v_cvt_pk_bf16_f32 v149, v142, v143
	v_cvt_pk_bf16_f32 v150, v144, v145
	v_cvt_pk_bf16_f32 v151, v146, v147
	global_store_dwordx4 v168, v[148:151], s[54:55]
	v_add_u32_e32 v168, 0x800, v168
	v_lshlrev_b32_e32 v132, 16, v48
	v_and_b32_e32 v133, 0xffff0000, v48
	v_lshlrev_b32_e32 v134, 16, v49
	v_and_b32_e32 v135, 0xffff0000, v49
	v_lshlrev_b32_e32 v136, 16, v50
	v_and_b32_e32 v137, 0xffff0000, v50
	v_lshlrev_b32_e32 v138, 16, v51
	v_and_b32_e32 v139, 0xffff0000, v51
	v_lshlrev_b32_e32 v140, 16, v32
	v_and_b32_e32 v141, 0xffff0000, v32
	v_lshlrev_b32_e32 v142, 16, v33
	v_and_b32_e32 v143, 0xffff0000, v33
	v_lshlrev_b32_e32 v144, 16, v34
	v_and_b32_e32 v145, 0xffff0000, v34
	v_lshlrev_b32_e32 v146, 16, v35
	v_and_b32_e32 v147, 0xffff0000, v35
	v_pk_add_f32 v[124:125], v[124:125], v[132:133]
	v_pk_add_f32 v[126:127], v[126:127], v[134:135]
	v_pk_add_f32 v[128:129], v[128:129], v[136:137]
	v_pk_add_f32 v[130:131], v[130:131], v[138:139]
	v_pk_add_f32 v[124:125], v[124:125], v[140:141] neg_lo:[0,1] neg_hi:[0,1]
	v_pk_add_f32 v[126:127], v[126:127], v[142:143] neg_lo:[0,1] neg_hi:[0,1]
	v_pk_add_f32 v[128:129], v[128:129], v[144:145] neg_lo:[0,1] neg_hi:[0,1]
	v_pk_add_f32 v[130:131], v[130:131], v[146:147] neg_lo:[0,1] neg_hi:[0,1]
	v_add_u32_e32 v170, 11, v169
	v_min_u32_e32 v170, s56, v170
	v_add_u32_e32 v171, 7, v169
	v_max_i32_e32 v171, 0, v171
	v_sub_u32_e32 v170, v170, v171
	v_cvt_f32_u32_e32 v170, v170
	v_rcp_f32_e32 v174, v170
	v_lshlrev_b32_e32 v132, 16, v44
	v_and_b32_e32 v133, 0xffff0000, v44
	v_lshlrev_b32_e32 v134, 16, v45
	v_and_b32_e32 v135, 0xffff0000, v45
	v_lshlrev_b32_e32 v136, 16, v46
	v_and_b32_e32 v137, 0xffff0000, v46
	v_lshlrev_b32_e32 v138, 16, v47
	v_and_b32_e32 v139, 0xffff0000, v47
	v_pk_fma_f32 v[140:141], v[124:125], v[174:175], v[132:133] op_sel_hi:[1,0,1] neg_lo:[0,0,1] neg_hi:[0,0,1]
	v_pk_fma_f32 v[142:143], v[126:127], v[174:175], v[134:135] op_sel_hi:[1,0,1] neg_lo:[0,0,1] neg_hi:[0,0,1]
	v_pk_fma_f32 v[144:145], v[128:129], v[174:175], v[136:137] op_sel_hi:[1,0,1] neg_lo:[0,0,1] neg_hi:[0,0,1]
	v_pk_fma_f32 v[146:147], v[130:131], v[174:175], v[138:139] op_sel_hi:[1,0,1] neg_lo:[0,0,1] neg_hi:[0,0,1]
	v_cvt_pk_bf16_f32 v148, v140, v141
	v_cvt_pk_bf16_f32 v149, v142, v143
	v_cvt_pk_bf16_f32 v150, v144, v145
	v_cvt_pk_bf16_f32 v151, v146, v147
; __device__ __forceinline__ u32x4 pack8(const f32x4 a, const f32x4 b) { u32x4 w; w.x = cvt_pk_bf16(a[0], a[1]); w.y = cvt_pk_bf16(a[2], a[3]); w.z = cvt_pk_bf16(b[0], b[1]); w.w = cvt_pk_bf16(b[2], b[3]); return w; }
; __global__ void __launch_bounds__(512, 2) fwd_mega(Args a) {
;     ...
;             for (int s = s0; s < s0 + 32; ++s) {
;                 f32x4 u0, u1; pg8::unpack8(*(const u32x4*)(base + (size_t)s * 512), u0, u1);
;                 const int jlo = (s - hw) > 0 ? (s - hw) : 0, jhi = (s + hw) < SEQ ? (s + hw) : SEQ;
;                 const float rc = 1.0f / (float)(jhi - jlo);
;                 *(u32x4*)(obase + (size_t)s * 1024) = pg8::pack8(w0 * rc - u0, w1 * rc - u1);
;                 if (s + hw < SEQ) { f32x4 a0, a1; pg8::unpack8(*(const u32x4*)(base + (size_t)(s + hw) * 512), a0, a1); w0 += a0; w1 += a1; }
;                 if (s - hw >= 0) { f32x4 a0, a1; pg8::unpack8(*(const u32x4*)(base + (size_t)(s - hw) * 512), a0, a1); w0 -= a0; w1 -= a1; }
	global_store_dwordx4 v168, v[148:151], s[54:55]
	v_add_u32_e32 v168, 0x800, v168
	v_lshlrev_b32_e32 v132, 16, v52
	v_and_b32_e32 v133, 0xffff0000, v52
	v_lshlrev_b32_e32 v134, 16, v53
	v_and_b32_e32 v135, 0xffff0000, v53
	v_lshlrev_b32_e32 v136, 16, v54
	v_and_b32_e32 v137, 0xffff0000, v54
	v_lshlrev_b32_e32 v138, 16, v55
	v_and_b32_e32 v139, 0xffff0000, v55
	v_lshlrev_b32_e32 v140, 16, v36
	v_and_b32_e32 v141, 0xffff0000, v36
	v_lshlrev_b32_e32 v142, 16, v37
	v_and_b32_e32 v143, 0xffff0000, v37
	v_lshlrev_b32_e32 v144, 16, v38
	v_and_b32_e32 v145, 0xffff0000, v38
	v_lshlrev_b32_e32 v146, 16, v39
	v_and_b32_e32 v147, 0xffff0000, v39
	v_pk_add_f32 v[124:125], v[124:125], v[132:133]
	v_pk_add_f32 v[126:127], v[126:127], v[134:135]
	v_pk_add_f32 v[128:129], v[128:129], v[136:137]
	v_pk_add_f32 v[130:131], v[130:131], v[138:139]
	v_pk_add_f32 v[124:125], v[124:125], v[140:141] neg_lo:[0,1] neg_hi:[0,1]
	v_pk_add_f32 v[126:127], v[126:127], v[142:143] neg_lo:[0,1] neg_hi:[0,1]
	v_pk_add_f32 v[128:129], v[128:129], v[144:145] neg_lo:[0,1] neg_hi:[0,1]
	v_pk_add_f32 v[130:131], v[130:131], v[146:147] neg_lo:[0,1] neg_hi:[0,1]
	v_add_u32_e32 v170, 12, v169
	v_min_u32_e32 v170, s56, v170
	v_add_u32_e32 v171, 8, v169
	v_max_i32_e32 v171, 0, v171
	v_sub_u32_e32 v170, v170, v171
	v_cvt_f32_u32_e32 v170, v170
	v_rcp_f32_e32 v174, v170
	v_lshlrev_b32_e32 v132, 16, v48
	v_and_b32_e32 v133, 0xffff0000, v48
	v_lshlrev_b32_e32 v134, 16, v49
	v_and_b32_e32 v135, 0xffff0000, v49
	v_lshlrev_b32_e32 v136, 16, v50
	v_and_b32_e32 v137, 0xffff0000, v50
	v_lshlrev_b32_e32 v138, 16, v51
	v_and_b32_e32 v139, 0xffff0000, v51
	v_pk_fma_f32 v[140:141], v[124:125], v[174:175], v[132:133] op_sel_hi:[1,0,1] neg_lo:[0,0,1] neg_hi:[0,0,1]
	v_pk_fma_f32 v[142:143], v[126:127], v[174:175], v[134:135] op_sel_hi:[1,0,1] neg_lo:[0,0,1] neg_hi:[0,0,1]
	v_pk_fma_f32 v[144:145], v[128:129], v[174:175], v[136:137] op_sel_hi:[1,0,1] neg_lo:[0,0,1] neg_hi:[0,0,1]
	v_pk_fma_f32 v[146:147], v[130:131], v[174:175], v[138:139] op_sel_hi:[1,0,1] neg_lo:[0,0,1] neg_hi:[0,0,1]
	v_cvt_pk_bf16_f32 v148, v140, v141
	v_cvt_pk_bf16_f32 v149, v142, v143
	v_cvt_pk_bf16_f32 v150, v144, v145
	v_cvt_pk_bf16_f32 v151, v146, v147
	global_store_dwordx4 v168, v[148:151], s[54:55]
	v_add_u32_e32 v168, 0x800, v168
	v_lshlrev_b32_e32 v132, 16, v56
	v_and_b32_e32 v133, 0xffff0000, v56
	v_lshlrev_b32_e32 v134, 16, v57
	v_and_b32_e32 v135, 0xffff0000, v57
	v_lshlrev_b32_e32 v136, 16, v58
	v_and_b32_e32 v137, 0xffff0000, v58
	v_lshlrev_b32_e32 v138, 16, v59
	v_and_b32_e32 v139, 0xffff0000, v59
	v_lshlrev_b32_e32 v140, 16, v40
	v_and_b32_e32 v141, 0xffff0000, v40
	v_lshlrev_b32_e32 v142, 16, v41
	v_and_b32_e32 v143, 0xffff0000, v41
	v_lshlrev_b32_e32 v144, 16, v42
	v_and_b32_e32 v145, 0xffff0000, v42
	v_lshlrev_b32_e32 v146, 16, v43
	v_and_b32_e32 v147, 0xffff0000, v43
	v_pk_add_f32 v[124:125], v[124:125], v[132:133]
	v_pk_add_f32 v[126:127], v[126:127], v[134:135]
	v_pk_add_f32 v[128:129], v[128:129], v[136:137]
	v_pk_add_f32 v[130:131], v[130:131], v[138:139]
	v_pk_add_f32 v[124:125], v[124:125], v[140:141] neg_lo:[0,1] neg_hi:[0,1]
	v_pk_add_f32 v[126:127], v[126:127], v[142:143] neg_lo:[0,1] neg_hi:[0,1]
	v_pk_add_f32 v[128:129], v[128:129], v[144:145] neg_lo:[0,1] neg_hi:[0,1]
	v_pk_add_f32 v[130:131], v[130:131], v[146:147] neg_lo:[0,1] neg_hi:[0,1]
	v_add_u32_e32 v170, 13, v169
	v_min_u32_e32 v170, s56, v170
	v_add_u32_e32 v171, 9, v169
	v_max_i32_e32 v171, 0, v171
	v_sub_u32_e32 v170, v170, v171
	v_cvt_f32_u32_e32 v170, v170
	v_rcp_f32_e32 v174, v170
	v_lshlrev_b32_e32 v132, 16, v52
	v_and_b32_e32 v133, 0xffff0000, v52
	v_lshlrev_b32_e32 v134, 16, v53
	v_and_b32_e32 v135, 0xffff0000, v53
	v_lshlrev_b32_e32 v136, 16, v54
	v_and_b32_e32 v137, 0xffff0000, v54
	v_lshlrev_b32_e32 v138, 16, v55
	v_and_b32_e32 v139, 0xffff0000, v55
	v_pk_fma_f32 v[140:141], v[124:125], v[174:175], v[132:133] op_sel_hi:[1,0,1] neg_lo:[0,0,1] neg_hi:[0,0,1]
	v_pk_fma_f32 v[142:143], v[126:127], v[174:175], v[134:135] op_sel_hi:[1,0,1] neg_lo:[0,0,1] neg_hi:[0,0,1]
	v_pk_fma_f32 v[144:145], v[128:129], v[174:175], v[136:137] op_sel_hi:[1,0,1] neg_lo:[0,0,1] neg_hi:[0,0,1]
	v_pk_fma_f32 v[146:147], v[130:131], v[174:175], v[138:139] op_sel_hi:[1,0,1] neg_lo:[0,0,1] neg_hi:[0,0,1]
	v_cvt_pk_bf16_f32 v148, v140, v141
	v_cvt_pk_bf16_f32 v149, v142, v143
	v_cvt_pk_bf16_f32 v150, v144, v145
	v_cvt_pk_bf16_f32 v151, v146, v147
	global_store_dwordx4 v168, v[148:151], s[54:55]
	v_add_u32_e32 v168, 0x800, v168
	v_lshlrev_b32_e32 v132, 16, v60
	v_and_b32_e32 v133, 0xffff0000, v60
	v_lshlrev_b32_e32 v134, 16, v61
	v_and_b32_e32 v135, 0xffff0000, v61
	v_lshlrev_b32_e32 v136, 16, v62
	v_and_b32_e32 v137, 0xffff0000, v62
	v_lshlrev_b32_e32 v138, 16, v63
	v_and_b32_e32 v139, 0xffff0000, v63
	v_lshlrev_b32_e32 v140, 16, v44
	v_and_b32_e32 v141, 0xffff0000, v44
	v_lshlrev_b32_e32 v142, 16, v45
	v_and_b32_e32 v143, 0xffff0000, v45
	v_lshlrev_b32_e32 v144, 16, v46
	v_and_b32_e32 v145, 0xffff0000, v46
	v_lshlrev_b32_e32 v146, 16, v47
	v_and_b32_e32 v147, 0xffff0000, v47
	v_pk_add_f32 v[124:125], v[124:125], v[132:133]
	v_pk_add_f32 v[126:127], v[126:127], v[134:135]
	v_pk_add_f32 v[128:129], v[128:129], v[136:137]
	v_pk_add_f32 v[130:131], v[130:131], v[138:139]
	v_pk_add_f32 v[124:125], v[124:125], v[140:141] neg_lo:[0,1] neg_hi:[0,1]
	v_pk_add_f32 v[126:127], v[126:127], v[142:143] neg_lo:[0,1] neg_hi:[0,1]
	v_pk_add_f32 v[128:129], v[128:129], v[144:145] neg_lo:[0,1] neg_hi:[0,1]
	v_pk_add_f32 v[130:131], v[130:131], v[146:147] neg_lo:[0,1] neg_hi:[0,1]
	v_add_u32_e32 v170, 14, v169
	v_min_u32_e32 v170, s56, v170
	v_add_u32_e32 v171, 10, v169
; __device__ __forceinline__ u32x4 pack8(const f32x4 a, const f32x4 b) { u32x4 w; w.x = cvt_pk_bf16(a[0], a[1]); w.y = cvt_pk_bf16(a[2], a[3]); w.z = cvt_pk_bf16(b[0], b[1]); w.w = cvt_pk_bf16(b[2], b[3]); return w; }
; __global__ void __launch_bounds__(512, 2) fwd_mega(Args a) {
;     ...
;             for (int s = s0; s < s0 + 32; ++s) {
;                 f32x4 u0, u1; pg8::unpack8(*(const u32x4*)(base + (size_t)s * 512), u0, u1);
;                 const int jlo = (s - hw) > 0 ? (s - hw) : 0, jhi = (s + hw) < SEQ ? (s + hw) : SEQ;
;                 const float rc = 1.0f / (float)(jhi - jlo);
;                 *(u32x4*)(obase + (size_t)s * 1024) = pg8::pack8(w0 * rc - u0, w1 * rc - u1);
;                 if (s + hw < SEQ) { f32x4 a0, a1; pg8::unpack8(*(const u32x4*)(base + (size_t)(s + hw) * 512), a0, a1); w0 += a0; w1 += a1; }
;                 if (s - hw >= 0) { f32x4 a0, a1; pg8::unpack8(*(const u32x4*)(base + (size_t)(s - hw) * 512), a0, a1); w0 -= a0; w1 -= a1; }
	v_max_i32_e32 v171, 0, v171
	v_sub_u32_e32 v170, v170, v171
	v_cvt_f32_u32_e32 v170, v170
	v_rcp_f32_e32 v174, v170
	v_lshlrev_b32_e32 v132, 16, v56
	v_and_b32_e32 v133, 0xffff0000, v56
	v_lshlrev_b32_e32 v134, 16, v57
	v_and_b32_e32 v135, 0xffff0000, v57
	v_lshlrev_b32_e32 v136, 16, v58
	v_and_b32_e32 v137, 0xffff0000, v58
	v_lshlrev_b32_e32 v138, 16, v59
	v_and_b32_e32 v139, 0xffff0000, v59
	v_pk_fma_f32 v[140:141], v[124:125], v[174:175], v[132:133] op_sel_hi:[1,0,1] neg_lo:[0,0,1] neg_hi:[0,0,1]
	v_pk_fma_f32 v[142:143], v[126:127], v[174:175], v[134:135] op_sel_hi:[1,0,1] neg_lo:[0,0,1] neg_hi:[0,0,1]
	v_pk_fma_f32 v[144:145], v[128:129], v[174:175], v[136:137] op_sel_hi:[1,0,1] neg_lo:[0,0,1] neg_hi:[0,0,1]
	v_pk_fma_f32 v[146:147], v[130:131], v[174:175], v[138:139] op_sel_hi:[1,0,1] neg_lo:[0,0,1] neg_hi:[0,0,1]
	v_cvt_pk_bf16_f32 v148, v140, v141
	v_cvt_pk_bf16_f32 v149, v142, v143
	v_cvt_pk_bf16_f32 v150, v144, v145
	v_cvt_pk_bf16_f32 v151, v146, v147
	global_store_dwordx4 v168, v[148:151], s[54:55]
	v_add_u32_e32 v168, 0x800, v168
	v_lshlrev_b32_e32 v132, 16, v64
	v_and_b32_e32 v133, 0xffff0000, v64
	v_lshlrev_b32_e32 v134, 16, v65
	v_and_b32_e32 v135, 0xffff0000, v65
	v_lshlrev_b32_e32 v136, 16, v66
	v_and_b32_e32 v137, 0xffff0000, v66
	v_lshlrev_b32_e32 v138, 16, v67
	v_and_b32_e32 v139, 0xffff0000, v67
	v_lshlrev_b32_e32 v140, 16, v48
	v_and_b32_e32 v141, 0xffff0000, v48
	v_lshlrev_b32_e32 v142, 16, v49
	v_and_b32_e32 v143, 0xffff0000, v49
	v_lshlrev_b32_e32 v144, 16, v50
	v_and_b32_e32 v145, 0xffff0000, v50
	v_lshlrev_b32_e32 v146, 16, v51
	v_and_b32_e32 v147, 0xffff0000, v51
	v_pk_add_f32 v[124:125], v[124:125], v[132:133]
	v_pk_add_f32 v[126:127], v[126:127], v[134:135]
	v_pk_add_f32 v[128:129], v[128:129], v[136:137]
	v_pk_add_f32 v[130:131], v[130:131], v[138:139]
	v_pk_add_f32 v[124:125], v[124:125], v[140:141] neg_lo:[0,1] neg_hi:[0,1]
	v_pk_add_f32 v[126:127], v[126:127], v[142:143] neg_lo:[0,1] neg_hi:[0,1]
	v_pk_add_f32 v[128:129], v[128:129], v[144:145] neg_lo:[0,1] neg_hi:[0,1]
	v_pk_add_f32 v[130:131], v[130:131], v[146:147] neg_lo:[0,1] neg_hi:[0,1]
	v_add_u32_e32 v170, 15, v169
	v_min_u32_e32 v170, s56, v170
	v_add_u32_e32 v171, 11, v169
	v_max_i32_e32 v171, 0, v171
	v_sub_u32_e32 v170, v170, v171
	v_cvt_f32_u32_e32 v170, v170
	v_rcp_f32_e32 v174, v170
	v_lshlrev_b32_e32 v132, 16, v60
	v_and_b32_e32 v133, 0xffff0000, v60
	v_lshlrev_b32_e32 v134, 16, v61
	v_and_b32_e32 v135, 0xffff0000, v61
	v_lshlrev_b32_e32 v136, 16, v62
	v_and_b32_e32 v137, 0xffff0000, v62
	v_lshlrev_b32_e32 v138, 16, v63
	v_and_b32_e32 v139, 0xffff0000, v63
	v_pk_fma_f32 v[140:141], v[124:125], v[174:175], v[132:133] op_sel_hi:[1,0,1] neg_lo:[0,0,1] neg_hi:[0,0,1]
	v_pk_fma_f32 v[142:143], v[126:127], v[174:175], v[134:135] op_sel_hi:[1,0,1] neg_lo:[0,0,1] neg_hi:[0,0,1]
	v_pk_fma_f32 v[144:145], v[128:129], v[174:175], v[136:137] op_sel_hi:[1,0,1] neg_lo:[0,0,1] neg_hi:[0,0,1]
	v_pk_fma_f32 v[146:147], v[130:131], v[174:175], v[138:139] op_sel_hi:[1,0,1] neg_lo:[0,0,1] neg_hi:[0,0,1]
	v_cvt_pk_bf16_f32 v148, v140, v141
	v_cvt_pk_bf16_f32 v149, v142, v143
	v_cvt_pk_bf16_f32 v150, v144, v145
	v_cvt_pk_bf16_f32 v151, v146, v147
	global_store_dwordx4 v168, v[148:151], s[54:55]
	v_add_u32_e32 v168, 0x800, v168
	v_lshlrev_b32_e32 v132, 16, v68
	v_and_b32_e32 v133, 0xffff0000, v68
	v_lshlrev_b32_e32 v134, 16, v69
	v_and_b32_e32 v135, 0xffff0000, v69
	v_lshlrev_b32_e32 v136, 16, v70
	v_and_b32_e32 v137, 0xffff0000, v70
	v_lshlrev_b32_e32 v138, 16, v71
	v_and_b32_e32 v139, 0xffff0000, v71
	v_lshlrev_b32_e32 v140, 16, v52
	v_and_b32_e32 v141, 0xffff0000, v52
	v_lshlrev_b32_e32 v142, 16, v53
	v_and_b32_e32 v143, 0xffff0000, v53
	v_lshlrev_b32_e32 v144, 16, v54
	v_and_b32_e32 v145, 0xffff0000, v54
	v_lshlrev_b32_e32 v146, 16, v55
	v_and_b32_e32 v147, 0xffff0000, v55
	v_pk_add_f32 v[124:125], v[124:125], v[132:133]
	v_pk_add_f32 v[126:127], v[126:127], v[134:135]
	v_pk_add_f32 v[128:129], v[128:129], v[136:137]
	v_pk_add_f32 v[130:131], v[130:131], v[138:139]
	v_pk_add_f32 v[124:125], v[124:125], v[140:141] neg_lo:[0,1] neg_hi:[0,1]
	v_pk_add_f32 v[126:127], v[126:127], v[142:143] neg_lo:[0,1] neg_hi:[0,1]
	v_pk_add_f32 v[128:129], v[128:129], v[144:145] neg_lo:[0,1] neg_hi:[0,1]
	v_pk_add_f32 v[130:131], v[130:131], v[146:147] neg_lo:[0,1] neg_hi:[0,1]
	v_add_u32_e32 v170, 16, v169
	v_min_u32_e32 v170, s56, v170
	v_add_u32_e32 v171, 12, v169
	v_max_i32_e32 v171, 0, v171
	v_sub_u32_e32 v170, v170, v171
	v_cvt_f32_u32_e32 v170, v170
	v_rcp_f32_e32 v174, v170
	v_lshlrev_b32_e32 v132, 16, v64
	v_and_b32_e32 v133, 0xffff0000, v64
	v_lshlrev_b32_e32 v134, 16, v65
	v_and_b32_e32 v135, 0xffff0000, v65
	v_lshlrev_b32_e32 v136, 16, v66
	v_and_b32_e32 v137, 0xffff0000, v66
	v_lshlrev_b32_e32 v138, 16, v67
	v_and_b32_e32 v139, 0xffff0000, v67
	v_pk_fma_f32 v[140:141], v[124:125], v[174:175], v[132:133] op_sel_hi:[1,0,1] neg_lo:[0,0,1] neg_hi:[0,0,1]
	v_pk_fma_f32 v[142:143], v[126:127], v[174:175], v[134:135] op_sel_hi:[1,0,1] neg_lo:[0,0,1] neg_hi:[0,0,1]
	v_pk_fma_f32 v[144:145], v[128:129], v[174:175], v[136:137] op_sel_hi:[1,0,1] neg_lo:[0,0,1] neg_hi:[0,0,1]
	v_pk_fma_f32 v[146:147], v[130:131], v[174:175], v[138:139] op_sel_hi:[1,0,1] neg_lo:[0,0,1] neg_hi:[0,0,1]
	v_cvt_pk_bf16_f32 v148, v140, v141
	v_cvt_pk_bf16_f32 v149, v142, v143
	v_cvt_pk_bf16_f32 v150, v144, v145
	v_cvt_pk_bf16_f32 v151, v146, v147
	global_store_dwordx4 v168, v[148:151], s[54:55]
	v_add_u32_e32 v168, 0x800, v168
	v_lshlrev_b32_e32 v132, 16, v72
	v_and_b32_e32 v133, 0xffff0000, v72
	v_lshlrev_b32_e32 v134, 16, v73
	v_and_b32_e32 v135, 0xffff0000, v73
	v_lshlrev_b32_e32 v136, 16, v74
; __device__ __forceinline__ u32x4 pack8(const f32x4 a, const f32x4 b) { u32x4 w; w.x = cvt_pk_bf16(a[0], a[1]); w.y = cvt_pk_bf16(a[2], a[3]); w.z = cvt_pk_bf16(b[0], b[1]); w.w = cvt_pk_bf16(b[2], b[3]); return w; }
; __global__ void __launch_bounds__(512, 2) fwd_mega(Args a) {
;     ...
;             { const int jlo = (s0 - hw) > 0 ? (s0 - hw) : 0, jhi = (s0 + hw) < SEQ ? (s0 + hw) : SEQ;
;               for (int j = jlo; j < jhi; ++j) { f32x4 a0, a1; pg8::unpack8(*(const u32x4*)(base + (size_t)j * 512), a0, a1); w0 += a0; w1 += a1; } }
;     ...
;             for (int s = s0; s < s0 + 32; ++s) {
;                 f32x4 u0, u1; pg8::unpack8(*(const u32x4*)(base + (size_t)s * 512), u0, u1);
;                 const int jlo = (s - hw) > 0 ? (s - hw) : 0, jhi = (s + hw) < SEQ ? (s + hw) : SEQ;
;                 const float rc = 1.0f / (float)(jhi - jlo);
;                 *(u32x4*)(obase + (size_t)s * 1024) = pg8::pack8(w0 * rc - u0, w1 * rc - u1);
;                 if (s + hw < SEQ) { f32x4 a0, a1; pg8::unpack8(*(const u32x4*)(base + (size_t)(s + hw) * 512), a0, a1); w0 += a0; w1 += a1; }
;                 if (s - hw >= 0) { f32x4 a0, a1; pg8::unpack8(*(const u32x4*)(base + (size_t)(s - hw) * 512), a0, a1); w0 -= a0; w1 -= a1; }
	v_and_b32_e32 v137, 0xffff0000, v74
	v_lshlrev_b32_e32 v138, 16, v75
	v_and_b32_e32 v139, 0xffff0000, v75
	v_lshlrev_b32_e32 v140, 16, v56
	v_and_b32_e32 v141, 0xffff0000, v56
	v_lshlrev_b32_e32 v142, 16, v57
	v_and_b32_e32 v143, 0xffff0000, v57
	v_lshlrev_b32_e32 v144, 16, v58
	v_and_b32_e32 v145, 0xffff0000, v58
	v_lshlrev_b32_e32 v146, 16, v59
	v_and_b32_e32 v147, 0xffff0000, v59
	v_pk_add_f32 v[124:125], v[124:125], v[132:133]
	v_pk_add_f32 v[126:127], v[126:127], v[134:135]
	v_pk_add_f32 v[128:129], v[128:129], v[136:137]
	v_pk_add_f32 v[130:131], v[130:131], v[138:139]
	v_pk_add_f32 v[124:125], v[124:125], v[140:141] neg_lo:[0,1] neg_hi:[0,1]
	v_pk_add_f32 v[126:127], v[126:127], v[142:143] neg_lo:[0,1] neg_hi:[0,1]
	v_pk_add_f32 v[128:129], v[128:129], v[144:145] neg_lo:[0,1] neg_hi:[0,1]
	v_pk_add_f32 v[130:131], v[130:131], v[146:147] neg_lo:[0,1] neg_hi:[0,1]
	v_add_u32_e32 v170, 17, v169
	v_min_u32_e32 v170, s56, v170
	v_add_u32_e32 v171, 13, v169
	v_max_i32_e32 v171, 0, v171
	v_sub_u32_e32 v170, v170, v171
	v_cvt_f32_u32_e32 v170, v170
	v_rcp_f32_e32 v174, v170
	v_lshlrev_b32_e32 v132, 16, v68
	v_and_b32_e32 v133, 0xffff0000, v68
	v_lshlrev_b32_e32 v134, 16, v69
	v_and_b32_e32 v135, 0xffff0000, v69
	v_lshlrev_b32_e32 v136, 16, v70
	v_and_b32_e32 v137, 0xffff0000, v70
	v_lshlrev_b32_e32 v138, 16, v71
	v_and_b32_e32 v139, 0xffff0000, v71
	v_pk_fma_f32 v[140:141], v[124:125], v[174:175], v[132:133] op_sel_hi:[1,0,1] neg_lo:[0,0,1] neg_hi:[0,0,1]
	v_pk_fma_f32 v[142:143], v[126:127], v[174:175], v[134:135] op_sel_hi:[1,0,1] neg_lo:[0,0,1] neg_hi:[0,0,1]
	v_pk_fma_f32 v[144:145], v[128:129], v[174:175], v[136:137] op_sel_hi:[1,0,1] neg_lo:[0,0,1] neg_hi:[0,0,1]
	v_pk_fma_f32 v[146:147], v[130:131], v[174:175], v[138:139] op_sel_hi:[1,0,1] neg_lo:[0,0,1] neg_hi:[0,0,1]
	v_cvt_pk_bf16_f32 v148, v140, v141
	v_cvt_pk_bf16_f32 v149, v142, v143
	v_cvt_pk_bf16_f32 v150, v144, v145
	v_cvt_pk_bf16_f32 v151, v146, v147
	global_store_dwordx4 v168, v[148:151], s[54:55]
	s_branch .Lpool_next
.Lpool_g2:
	s_sub_i32 s52, s49, 4
	s_ashr_i32 s53, s52, 31
	s_lshl_b64 s[52:53], s[52:53], 10
	s_add_u32 s52, s52, s8
	s_addc_u32 s53, s53, s9
	s_add_u32 s52, s52, 512
	s_addc_u32 s53, s53, 0
	s_lshl_b32 s54, s49, 11
	s_add_u32 s54, s54, 0x3000600
	s_add_u32 s54, s30, s54
	s_addc_u32 s55, s31, 0
	global_load_dwordx4 v[0:3], v160, s[52:53] offset:0
	global_load_dwordx4 v[4:7], v160, s[52:53] offset:1024
	global_load_dwordx4 v[8:11], v160, s[52:53] offset:2048
	global_load_dwordx4 v[12:15], v160, s[52:53] offset:3072
	global_load_dwordx4 v[16:19], v161, s[52:53] offset:0
	global_load_dwordx4 v[20:23], v161, s[52:53] offset:1024
	global_load_dwordx4 v[24:27], v161, s[52:53] offset:2048
	global_load_dwordx4 v[28:31], v161, s[52:53] offset:3072
	global_load_dwordx4 v[32:35], v162, s[52:53] offset:0
	global_load_dwordx4 v[36:39], v162, s[52:53] offset:1024
	global_load_dwordx4 v[40:43], v162, s[52:53] offset:2048
	global_load_dwordx4 v[44:47], v162, s[52:53] offset:3072
	global_load_dwordx4 v[48:51], v163, s[52:53] offset:0
	global_load_dwordx4 v[52:55], v163, s[52:53] offset:1024
	global_load_dwordx4 v[56:59], v163, s[52:53] offset:2048
	global_load_dwordx4 v[60:63], v163, s[52:53] offset:3072
	global_load_dwordx4 v[64:67], v164, s[52:53] offset:0
	global_load_dwordx4 v[68:71], v164, s[52:53] offset:1024
	global_load_dwordx4 v[72:75], v164, s[52:53] offset:2048
	global_load_dwordx4 v[76:79], v164, s[52:53] offset:3072
	global_load_dwordx4 v[80:83], v165, s[52:53] offset:0
	global_load_dwordx4 v[84:87], v165, s[52:53] offset:1024
	global_load_dwordx4 v[88:91], v165, s[52:53] offset:2048
	s_waitcnt vmcnt(0)
	s_cmp_eq_u32 s50, 0
	s_cbranch_scc1 .Lpool_g2_mask
	s_cmpk_eq_i32 s50, 0x7c0
	s_cbranch_scc0 .Lpool_g2_nomask
.Lpool_g2_mask:
	v_add_u32_e32 v170, -4, v169
	v_cmp_gt_u32_e32 vcc, s56, v170
	s_nop 1
	v_cndmask_b32_e32 v0, 0, v0, vcc
	v_cndmask_b32_e32 v1, 0, v1, vcc
	v_cndmask_b32_e32 v2, 0, v2, vcc
	v_cndmask_b32_e32 v3, 0, v3, vcc
	v_add_u32_e32 v170, -3, v169
	v_cmp_gt_u32_e32 vcc, s56, v170
	s_nop 1
	v_cndmask_b32_e32 v4, 0, v4, vcc
	v_cndmask_b32_e32 v5, 0, v5, vcc
	v_cndmask_b32_e32 v6, 0, v6, vcc
	v_cndmask_b32_e32 v7, 0, v7, vcc
	v_add_u32_e32 v170, -2, v169
	v_cmp_gt_u32_e32 vcc, s56, v170
	s_nop 1
	v_cndmask_b32_e32 v8, 0, v8, vcc
	v_cndmask_b32_e32 v9, 0, v9, vcc
	v_cndmask_b32_e32 v10, 0, v10, vcc
	v_cndmask_b32_e32 v11, 0, v11, vcc
	v_add_u32_e32 v170, -1, v169
	v_cmp_gt_u32_e32 vcc, s56, v170
	s_nop 1
	v_cndmask_b32_e32 v12, 0, v12, vcc
	v_cndmask_b32_e32 v13, 0, v13, vcc
	v_cndmask_b32_e32 v14, 0, v14, vcc
	v_cndmask_b32_e32 v15, 0, v15, vcc
	v_add_u32_e32 v170, 0, v169
	v_cmp_gt_u32_e32 vcc, s56, v170
	s_nop 1
	v_cndmask_b32_e32 v16, 0, v16, vcc
	v_cndmask_b32_e32 v17, 0, v17, vcc
	v_cndmask_b32_e32 v18, 0, v18, vcc
	v_cndmask_b32_e32 v19, 0, v19, vcc
	v_add_u32_e32 v170, 1, v169
	v_cmp_gt_u32_e32 vcc, s56, v170
	s_nop 1
	v_cndmask_b32_e32 v20, 0, v20, vcc
	v_cndmask_b32_e32 v21, 0, v21, vcc
	v_cndmask_b32_e32 v22, 0, v22, vcc
	v_cndmask_b32_e32 v23, 0, v23, vcc
	v_add_u32_e32 v170, 2, v169
	v_cmp_gt_u32_e32 vcc, s56, v170
	s_nop 1
	v_cndmask_b32_e32 v24, 0, v24, vcc
	v_cndmask_b32_e32 v25, 0, v25, vcc
	v_cndmask_b32_e32 v26, 0, v26, vcc
	v_cndmask_b32_e32 v27, 0, v27, vcc
	v_add_u32_e32 v170, 3, v169
	v_cmp_gt_u32_e32 vcc, s56, v170
	s_nop 1
	v_cndmask_b32_e32 v28, 0, v28, vcc
	v_cndmask_b32_e32 v29, 0, v29, vcc
	v_cndmask_b32_e32 v30, 0, v30, vcc
	v_cndmask_b32_e32 v31, 0, v31, vcc
	v_add_u32_e32 v170, 4, v169
	v_cmp_gt_u32_e32 vcc, s56, v170
	s_nop 1
	v_cndmask_b32_e32 v32, 0, v32, vcc
	v_cndmask_b32_e32 v33, 0, v33, vcc
; __device__ __forceinline__ u32x4 pack8(const f32x4 a, const f32x4 b) { u32x4 w; w.x = cvt_pk_bf16(a[0], a[1]); w.y = cvt_pk_bf16(a[2], a[3]); w.z = cvt_pk_bf16(b[0], b[1]); w.w = cvt_pk_bf16(b[2], b[3]); return w; }
; __global__ void __launch_bounds__(512, 2) fwd_mega(Args a) {
;     ...
;             { const int jlo = (s0 - hw) > 0 ? (s0 - hw) : 0, jhi = (s0 + hw) < SEQ ? (s0 + hw) : SEQ;
;               for (int j = jlo; j < jhi; ++j) { f32x4 a0, a1; pg8::unpack8(*(const u32x4*)(base + (size_t)j * 512), a0, a1); w0 += a0; w1 += a1; } }
;     ...
;             for (int s = s0; s < s0 + 32; ++s) {
;                 f32x4 u0, u1; pg8::unpack8(*(const u32x4*)(base + (size_t)s * 512), u0, u1);
;                 const int jlo = (s - hw) > 0 ? (s - hw) : 0, jhi = (s + hw) < SEQ ? (s + hw) : SEQ;
;                 const float rc = 1.0f / (float)(jhi - jlo);
;                 *(u32x4*)(obase + (size_t)s * 1024) = pg8::pack8(w0 * rc - u0, w1 * rc - u1);
;                 if (s + hw < SEQ) { f32x4 a0, a1; pg8::unpack8(*(const u32x4*)(base + (size_t)(s + hw) * 512), a0, a1); w0 += a0; w1 += a1; }
;                 if (s - hw >= 0) { f32x4 a0, a1; pg8::unpack8(*(const u32x4*)(base + (size_t)(s - hw) * 512), a0, a1); w0 -= a0; w1 -= a1; }
	v_cndmask_b32_e32 v34, 0, v34, vcc
	v_cndmask_b32_e32 v35, 0, v35, vcc
	v_add_u32_e32 v170, 5, v169
	v_cmp_gt_u32_e32 vcc, s56, v170
	s_nop 1
	v_cndmask_b32_e32 v36, 0, v36, vcc
	v_cndmask_b32_e32 v37, 0, v37, vcc
	v_cndmask_b32_e32 v38, 0, v38, vcc
	v_cndmask_b32_e32 v39, 0, v39, vcc
	v_add_u32_e32 v170, 6, v169
	v_cmp_gt_u32_e32 vcc, s56, v170
	s_nop 1
	v_cndmask_b32_e32 v40, 0, v40, vcc
	v_cndmask_b32_e32 v41, 0, v41, vcc
	v_cndmask_b32_e32 v42, 0, v42, vcc
	v_cndmask_b32_e32 v43, 0, v43, vcc
	v_add_u32_e32 v170, 7, v169
	v_cmp_gt_u32_e32 vcc, s56, v170
	s_nop 1
	v_cndmask_b32_e32 v44, 0, v44, vcc
	v_cndmask_b32_e32 v45, 0, v45, vcc
	v_cndmask_b32_e32 v46, 0, v46, vcc
	v_cndmask_b32_e32 v47, 0, v47, vcc
	v_add_u32_e32 v170, 8, v169
	v_cmp_gt_u32_e32 vcc, s56, v170
	s_nop 1
	v_cndmask_b32_e32 v48, 0, v48, vcc
	v_cndmask_b32_e32 v49, 0, v49, vcc
	v_cndmask_b32_e32 v50, 0, v50, vcc
	v_cndmask_b32_e32 v51, 0, v51, vcc
	v_add_u32_e32 v170, 9, v169
	v_cmp_gt_u32_e32 vcc, s56, v170
	s_nop 1
	v_cndmask_b32_e32 v52, 0, v52, vcc
	v_cndmask_b32_e32 v53, 0, v53, vcc
	v_cndmask_b32_e32 v54, 0, v54, vcc
	v_cndmask_b32_e32 v55, 0, v55, vcc
	v_add_u32_e32 v170, 10, v169
	v_cmp_gt_u32_e32 vcc, s56, v170
	s_nop 1
	v_cndmask_b32_e32 v56, 0, v56, vcc
	v_cndmask_b32_e32 v57, 0, v57, vcc
	v_cndmask_b32_e32 v58, 0, v58, vcc
	v_cndmask_b32_e32 v59, 0, v59, vcc
	v_add_u32_e32 v170, 11, v169
	v_cmp_gt_u32_e32 vcc, s56, v170
	s_nop 1
	v_cndmask_b32_e32 v60, 0, v60, vcc
	v_cndmask_b32_e32 v61, 0, v61, vcc
	v_cndmask_b32_e32 v62, 0, v62, vcc
	v_cndmask_b32_e32 v63, 0, v63, vcc
	v_add_u32_e32 v170, 12, v169
	v_cmp_gt_u32_e32 vcc, s56, v170
	s_nop 1
	v_cndmask_b32_e32 v64, 0, v64, vcc
	v_cndmask_b32_e32 v65, 0, v65, vcc
	v_cndmask_b32_e32 v66, 0, v66, vcc
	v_cndmask_b32_e32 v67, 0, v67, vcc
	v_add_u32_e32 v170, 13, v169
	v_cmp_gt_u32_e32 vcc, s56, v170
	s_nop 1
	v_cndmask_b32_e32 v68, 0, v68, vcc
	v_cndmask_b32_e32 v69, 0, v69, vcc
	v_cndmask_b32_e32 v70, 0, v70, vcc
	v_cndmask_b32_e32 v71, 0, v71, vcc
	v_add_u32_e32 v170, 14, v169
	v_cmp_gt_u32_e32 vcc, s56, v170
	s_nop 1
	v_cndmask_b32_e32 v72, 0, v72, vcc
	v_cndmask_b32_e32 v73, 0, v73, vcc
	v_cndmask_b32_e32 v74, 0, v74, vcc
	v_cndmask_b32_e32 v75, 0, v75, vcc
	v_add_u32_e32 v170, 15, v169
	v_cmp_gt_u32_e32 vcc, s56, v170
	s_nop 1
	v_cndmask_b32_e32 v76, 0, v76, vcc
	v_cndmask_b32_e32 v77, 0, v77, vcc
	v_cndmask_b32_e32 v78, 0, v78, vcc
	v_cndmask_b32_e32 v79, 0, v79, vcc
	v_add_u32_e32 v170, 16, v169
	v_cmp_gt_u32_e32 vcc, s56, v170
	s_nop 1
	v_cndmask_b32_e32 v80, 0, v80, vcc
	v_cndmask_b32_e32 v81, 0, v81, vcc
	v_cndmask_b32_e32 v82, 0, v82, vcc
	v_cndmask_b32_e32 v83, 0, v83, vcc
	v_add_u32_e32 v170, 17, v169
	v_cmp_gt_u32_e32 vcc, s56, v170
	s_nop 1
	v_cndmask_b32_e32 v84, 0, v84, vcc
	v_cndmask_b32_e32 v85, 0, v85, vcc
	v_cndmask_b32_e32 v86, 0, v86, vcc
	v_cndmask_b32_e32 v87, 0, v87, vcc
	v_add_u32_e32 v170, 18, v169
	v_cmp_gt_u32_e32 vcc, s56, v170
	s_nop 1
	v_cndmask_b32_e32 v88, 0, v88, vcc
	v_cndmask_b32_e32 v89, 0, v89, vcc
	v_cndmask_b32_e32 v90, 0, v90, vcc
	v_cndmask_b32_e32 v91, 0, v91, vcc
.Lpool_g2_nomask:
	v_lshlrev_b32_e32 v124, 16, v0
	v_and_b32_e32 v125, 0xffff0000, v0
	v_lshlrev_b32_e32 v126, 16, v1
	v_and_b32_e32 v127, 0xffff0000, v1
	v_lshlrev_b32_e32 v128, 16, v2
	v_and_b32_e32 v129, 0xffff0000, v2
	v_lshlrev_b32_e32 v130, 16, v3
	v_and_b32_e32 v131, 0xffff0000, v3
	v_lshlrev_b32_e32 v132, 16, v4
	v_and_b32_e32 v133, 0xffff0000, v4
	v_lshlrev_b32_e32 v134, 16, v5
	v_and_b32_e32 v135, 0xffff0000, v5
	v_lshlrev_b32_e32 v136, 16, v6
	v_and_b32_e32 v137, 0xffff0000, v6
	v_lshlrev_b32_e32 v138, 16, v7
	v_and_b32_e32 v139, 0xffff0000, v7
	v_pk_add_f32 v[124:125], v[124:125], v[132:133]
	v_pk_add_f32 v[126:127], v[126:127], v[134:135]
	v_pk_add_f32 v[128:129], v[128:129], v[136:137]
	v_pk_add_f32 v[130:131], v[130:131], v[138:139]
	v_lshlrev_b32_e32 v132, 16, v8
	v_and_b32_e32 v133, 0xffff0000, v8
	v_lshlrev_b32_e32 v134, 16, v9
	v_and_b32_e32 v135, 0xffff0000, v9
	v_lshlrev_b32_e32 v136, 16, v10
	v_and_b32_e32 v137, 0xffff0000, v10
	v_lshlrev_b32_e32 v138, 16, v11
	v_and_b32_e32 v139, 0xffff0000, v11
	v_pk_add_f32 v[124:125], v[124:125], v[132:133]
	v_pk_add_f32 v[126:127], v[126:127], v[134:135]
	v_pk_add_f32 v[128:129], v[128:129], v[136:137]
	v_pk_add_f32 v[130:131], v[130:131], v[138:139]
	v_lshlrev_b32_e32 v132, 16, v12
	v_and_b32_e32 v133, 0xffff0000, v12
	v_lshlrev_b32_e32 v134, 16, v13
	v_and_b32_e32 v135, 0xffff0000, v13
	v_lshlrev_b32_e32 v136, 16, v14
	v_and_b32_e32 v137, 0xffff0000, v14
	v_lshlrev_b32_e32 v138, 16, v15
	v_and_b32_e32 v139, 0xffff0000, v15
	v_pk_add_f32 v[124:125], v[124:125], v[132:133]
	v_pk_add_f32 v[126:127], v[126:127], v[134:135]
	v_pk_add_f32 v[128:129], v[128:129], v[136:137]
	v_pk_add_f32 v[130:131], v[130:131], v[138:139]
	v_lshlrev_b32_e32 v132, 16, v16
	v_and_b32_e32 v133, 0xffff0000, v16
	v_lshlrev_b32_e32 v134, 16, v17
	v_and_b32_e32 v135, 0xffff0000, v17
	v_lshlrev_b32_e32 v136, 16, v18
	v_and_b32_e32 v137, 0xffff0000, v18
	v_lshlrev_b32_e32 v138, 16, v19
	v_and_b32_e32 v139, 0xffff0000, v19
	v_pk_add_f32 v[124:125], v[124:125], v[132:133]
	v_pk_add_f32 v[126:127], v[126:127], v[134:135]
	v_pk_add_f32 v[128:129], v[128:129], v[136:137]
	v_pk_add_f32 v[130:131], v[130:131], v[138:139]
	v_lshlrev_b32_e32 v132, 16, v20
	v_and_b32_e32 v133, 0xffff0000, v20
	v_lshlrev_b32_e32 v134, 16, v21
	v_and_b32_e32 v135, 0xffff0000, v21
	v_lshlrev_b32_e32 v136, 16, v22
	v_and_b32_e32 v137, 0xffff0000, v22
	v_lshlrev_b32_e32 v138, 16, v23
	v_and_b32_e32 v139, 0xffff0000, v23
	v_pk_add_f32 v[124:125], v[124:125], v[132:133]
	v_pk_add_f32 v[126:127], v[126:127], v[134:135]
; __device__ __forceinline__ u32x4 pack8(const f32x4 a, const f32x4 b) { u32x4 w; w.x = cvt_pk_bf16(a[0], a[1]); w.y = cvt_pk_bf16(a[2], a[3]); w.z = cvt_pk_bf16(b[0], b[1]); w.w = cvt_pk_bf16(b[2], b[3]); return w; }
; __global__ void __launch_bounds__(512, 2) fwd_mega(Args a) {
;     ...
;             for (int s = s0; s < s0 + 32; ++s) {
;                 f32x4 u0, u1; pg8::unpack8(*(const u32x4*)(base + (size_t)s * 512), u0, u1);
;                 const int jlo = (s - hw) > 0 ? (s - hw) : 0, jhi = (s + hw) < SEQ ? (s + hw) : SEQ;
;                 const float rc = 1.0f / (float)(jhi - jlo);
;                 *(u32x4*)(obase + (size_t)s * 1024) = pg8::pack8(w0 * rc - u0, w1 * rc - u1);
;                 if (s + hw < SEQ) { f32x4 a0, a1; pg8::unpack8(*(const u32x4*)(base + (size_t)(s + hw) * 512), a0, a1); w0 += a0; w1 += a1; }
;                 if (s - hw >= 0) { f32x4 a0, a1; pg8::unpack8(*(const u32x4*)(base + (size_t)(s - hw) * 512), a0, a1); w0 -= a0; w1 -= a1; }
	v_pk_add_f32 v[128:129], v[128:129], v[136:137]
	v_pk_add_f32 v[130:131], v[130:131], v[138:139]
	v_lshlrev_b32_e32 v132, 16, v24
	v_and_b32_e32 v133, 0xffff0000, v24
	v_lshlrev_b32_e32 v134, 16, v25
	v_and_b32_e32 v135, 0xffff0000, v25
	v_lshlrev_b32_e32 v136, 16, v26
	v_and_b32_e32 v137, 0xffff0000, v26
	v_lshlrev_b32_e32 v138, 16, v27
	v_and_b32_e32 v139, 0xffff0000, v27
	v_pk_add_f32 v[124:125], v[124:125], v[132:133]
	v_pk_add_f32 v[126:127], v[126:127], v[134:135]
	v_pk_add_f32 v[128:129], v[128:129], v[136:137]
	v_pk_add_f32 v[130:131], v[130:131], v[138:139]
	v_lshlrev_b32_e32 v132, 16, v28
	v_and_b32_e32 v133, 0xffff0000, v28
	v_lshlrev_b32_e32 v134, 16, v29
	v_and_b32_e32 v135, 0xffff0000, v29
	v_lshlrev_b32_e32 v136, 16, v30
	v_and_b32_e32 v137, 0xffff0000, v30
	v_lshlrev_b32_e32 v138, 16, v31
	v_and_b32_e32 v139, 0xffff0000, v31
	v_pk_add_f32 v[124:125], v[124:125], v[132:133]
	v_pk_add_f32 v[126:127], v[126:127], v[134:135]
	v_pk_add_f32 v[128:129], v[128:129], v[136:137]
	v_pk_add_f32 v[130:131], v[130:131], v[138:139]
	v_add_u32_e32 v170, 4, v169
	v_min_u32_e32 v170, s56, v170
	v_add_u32_e32 v171, -4, v169
	v_max_i32_e32 v171, 0, v171
	v_sub_u32_e32 v170, v170, v171
	v_cvt_f32_u32_e32 v170, v170
	v_rcp_f32_e32 v174, v170
	v_lshlrev_b32_e32 v132, 16, v16
	v_and_b32_e32 v133, 0xffff0000, v16
	v_lshlrev_b32_e32 v134, 16, v17
	v_and_b32_e32 v135, 0xffff0000, v17
	v_lshlrev_b32_e32 v136, 16, v18
	v_and_b32_e32 v137, 0xffff0000, v18
	v_lshlrev_b32_e32 v138, 16, v19
	v_and_b32_e32 v139, 0xffff0000, v19
	v_pk_fma_f32 v[140:141], v[124:125], v[174:175], v[132:133] op_sel_hi:[1,0,1] neg_lo:[0,0,1] neg_hi:[0,0,1]
	v_pk_fma_f32 v[142:143], v[126:127], v[174:175], v[134:135] op_sel_hi:[1,0,1] neg_lo:[0,0,1] neg_hi:[0,0,1]
	v_pk_fma_f32 v[144:145], v[128:129], v[174:175], v[136:137] op_sel_hi:[1,0,1] neg_lo:[0,0,1] neg_hi:[0,0,1]
	v_pk_fma_f32 v[146:147], v[130:131], v[174:175], v[138:139] op_sel_hi:[1,0,1] neg_lo:[0,0,1] neg_hi:[0,0,1]
	v_cvt_pk_bf16_f32 v148, v140, v141
	v_cvt_pk_bf16_f32 v149, v142, v143
	v_cvt_pk_bf16_f32 v150, v144, v145
	v_cvt_pk_bf16_f32 v151, v146, v147
	global_store_dwordx4 v168, v[148:151], s[54:55]
	v_add_u32_e32 v168, 0x800, v168
	v_lshlrev_b32_e32 v132, 16, v32
	v_and_b32_e32 v133, 0xffff0000, v32
	v_lshlrev_b32_e32 v134, 16, v33
	v_and_b32_e32 v135, 0xffff0000, v33
	v_lshlrev_b32_e32 v136, 16, v34
	v_and_b32_e32 v137, 0xffff0000, v34
	v_lshlrev_b32_e32 v138, 16, v35
	v_and_b32_e32 v139, 0xffff0000, v35
	v_lshlrev_b32_e32 v140, 16, v0
	v_and_b32_e32 v141, 0xffff0000, v0
	v_lshlrev_b32_e32 v142, 16, v1
	v_and_b32_e32 v143, 0xffff0000, v1
	v_lshlrev_b32_e32 v144, 16, v2
	v_and_b32_e32 v145, 0xffff0000, v2
	v_lshlrev_b32_e32 v146, 16, v3
	v_and_b32_e32 v147, 0xffff0000, v3
	v_pk_add_f32 v[124:125], v[124:125], v[132:133]
	v_pk_add_f32 v[126:127], v[126:127], v[134:135]
	v_pk_add_f32 v[128:129], v[128:129], v[136:137]
	v_pk_add_f32 v[130:131], v[130:131], v[138:139]
	v_pk_add_f32 v[124:125], v[124:125], v[140:141] neg_lo:[0,1] neg_hi:[0,1]
	v_pk_add_f32 v[126:127], v[126:127], v[142:143] neg_lo:[0,1] neg_hi:[0,1]
	v_pk_add_f32 v[128:129], v[128:129], v[144:145] neg_lo:[0,1] neg_hi:[0,1]
	v_pk_add_f32 v[130:131], v[130:131], v[146:147] neg_lo:[0,1] neg_hi:[0,1]
	v_add_u32_e32 v170, 5, v169
	v_min_u32_e32 v170, s56, v170
	v_add_u32_e32 v171, -3, v169
	v_max_i32_e32 v171, 0, v171
	v_sub_u32_e32 v170, v170, v171
	v_cvt_f32_u32_e32 v170, v170
	v_rcp_f32_e32 v174, v170
	v_lshlrev_b32_e32 v132, 16, v20
	v_and_b32_e32 v133, 0xffff0000, v20
	v_lshlrev_b32_e32 v134, 16, v21
	v_and_b32_e32 v135, 0xffff0000, v21
	v_lshlrev_b32_e32 v136, 16, v22
	v_and_b32_e32 v137, 0xffff0000, v22
	v_lshlrev_b32_e32 v138, 16, v23
	v_and_b32_e32 v139, 0xffff0000, v23
	v_pk_fma_f32 v[140:141], v[124:125], v[174:175], v[132:133] op_sel_hi:[1,0,1] neg_lo:[0,0,1] neg_hi:[0,0,1]
	v_pk_fma_f32 v[142:143], v[126:127], v[174:175], v[134:135] op_sel_hi:[1,0,1] neg_lo:[0,0,1] neg_hi:[0,0,1]
	v_pk_fma_f32 v[144:145], v[128:129], v[174:175], v[136:137] op_sel_hi:[1,0,1] neg_lo:[0,0,1] neg_hi:[0,0,1]
	v_pk_fma_f32 v[146:147], v[130:131], v[174:175], v[138:139] op_sel_hi:[1,0,1] neg_lo:[0,0,1] neg_hi:[0,0,1]
	v_cvt_pk_bf16_f32 v148, v140, v141
	v_cvt_pk_bf16_f32 v149, v142, v143
	v_cvt_pk_bf16_f32 v150, v144, v145
	v_cvt_pk_bf16_f32 v151, v146, v147
	global_store_dwordx4 v168, v[148:151], s[54:55]
	v_add_u32_e32 v168, 0x800, v168
	v_lshlrev_b32_e32 v132, 16, v36
	v_and_b32_e32 v133, 0xffff0000, v36
	v_lshlrev_b32_e32 v134, 16, v37
	v_and_b32_e32 v135, 0xffff0000, v37
	v_lshlrev_b32_e32 v136, 16, v38
	v_and_b32_e32 v137, 0xffff0000, v38
	v_lshlrev_b32_e32 v138, 16, v39
	v_and_b32_e32 v139, 0xffff0000, v39
	v_lshlrev_b32_e32 v140, 16, v4
	v_and_b32_e32 v141, 0xffff0000, v4
	v_lshlrev_b32_e32 v142, 16, v5
	v_and_b32_e32 v143, 0xffff0000, v5
	v_lshlrev_b32_e32 v144, 16, v6
	v_and_b32_e32 v145, 0xffff0000, v6
	v_lshlrev_b32_e32 v146, 16, v7
	v_and_b32_e32 v147, 0xffff0000, v7
	v_pk_add_f32 v[124:125], v[124:125], v[132:133]
	v_pk_add_f32 v[126:127], v[126:127], v[134:135]
	v_pk_add_f32 v[128:129], v[128:129], v[136:137]
	v_pk_add_f32 v[130:131], v[130:131], v[138:139]
	v_pk_add_f32 v[124:125], v[124:125], v[140:141] neg_lo:[0,1] neg_hi:[0,1]
	v_pk_add_f32 v[126:127], v[126:127], v[142:143] neg_lo:[0,1] neg_hi:[0,1]
	v_pk_add_f32 v[128:129], v[128:129], v[144:145] neg_lo:[0,1] neg_hi:[0,1]
	v_pk_add_f32 v[130:131], v[130:131], v[146:147] neg_lo:[0,1] neg_hi:[0,1]
	v_add_u32_e32 v170, 6, v169
	v_min_u32_e32 v170, s56, v170
	v_add_u32_e32 v171, -2, v169
	v_max_i32_e32 v171, 0, v171
	v_sub_u32_e32 v170, v170, v171
	v_cvt_f32_u32_e32 v170, v170
	v_rcp_f32_e32 v174, v170
; __device__ __forceinline__ u32x4 pack8(const f32x4 a, const f32x4 b) { u32x4 w; w.x = cvt_pk_bf16(a[0], a[1]); w.y = cvt_pk_bf16(a[2], a[3]); w.z = cvt_pk_bf16(b[0], b[1]); w.w = cvt_pk_bf16(b[2], b[3]); return w; }
; __global__ void __launch_bounds__(512, 2) fwd_mega(Args a) {
;     ...
;             for (int s = s0; s < s0 + 32; ++s) {
;                 f32x4 u0, u1; pg8::unpack8(*(const u32x4*)(base + (size_t)s * 512), u0, u1);
;                 const int jlo = (s - hw) > 0 ? (s - hw) : 0, jhi = (s + hw) < SEQ ? (s + hw) : SEQ;
;                 const float rc = 1.0f / (float)(jhi - jlo);
;                 *(u32x4*)(obase + (size_t)s * 1024) = pg8::pack8(w0 * rc - u0, w1 * rc - u1);
;                 if (s + hw < SEQ) { f32x4 a0, a1; pg8::unpack8(*(const u32x4*)(base + (size_t)(s + hw) * 512), a0, a1); w0 += a0; w1 += a1; }
;                 if (s - hw >= 0) { f32x4 a0, a1; pg8::unpack8(*(const u32x4*)(base + (size_t)(s - hw) * 512), a0, a1); w0 -= a0; w1 -= a1; }
	v_lshlrev_b32_e32 v132, 16, v24
	v_and_b32_e32 v133, 0xffff0000, v24
	v_lshlrev_b32_e32 v134, 16, v25
	v_and_b32_e32 v135, 0xffff0000, v25
	v_lshlrev_b32_e32 v136, 16, v26
	v_and_b32_e32 v137, 0xffff0000, v26
	v_lshlrev_b32_e32 v138, 16, v27
	v_and_b32_e32 v139, 0xffff0000, v27
	v_pk_fma_f32 v[140:141], v[124:125], v[174:175], v[132:133] op_sel_hi:[1,0,1] neg_lo:[0,0,1] neg_hi:[0,0,1]
	v_pk_fma_f32 v[142:143], v[126:127], v[174:175], v[134:135] op_sel_hi:[1,0,1] neg_lo:[0,0,1] neg_hi:[0,0,1]
	v_pk_fma_f32 v[144:145], v[128:129], v[174:175], v[136:137] op_sel_hi:[1,0,1] neg_lo:[0,0,1] neg_hi:[0,0,1]
	v_pk_fma_f32 v[146:147], v[130:131], v[174:175], v[138:139] op_sel_hi:[1,0,1] neg_lo:[0,0,1] neg_hi:[0,0,1]
	v_cvt_pk_bf16_f32 v148, v140, v141
	v_cvt_pk_bf16_f32 v149, v142, v143
	v_cvt_pk_bf16_f32 v150, v144, v145
	v_cvt_pk_bf16_f32 v151, v146, v147
	global_store_dwordx4 v168, v[148:151], s[54:55]
	v_add_u32_e32 v168, 0x800, v168
	v_lshlrev_b32_e32 v132, 16, v40
	v_and_b32_e32 v133, 0xffff0000, v40
	v_lshlrev_b32_e32 v134, 16, v41
	v_and_b32_e32 v135, 0xffff0000, v41
	v_lshlrev_b32_e32 v136, 16, v42
	v_and_b32_e32 v137, 0xffff0000, v42
	v_lshlrev_b32_e32 v138, 16, v43
	v_and_b32_e32 v139, 0xffff0000, v43
	v_lshlrev_b32_e32 v140, 16, v8
	v_and_b32_e32 v141, 0xffff0000, v8
	v_lshlrev_b32_e32 v142, 16, v9
	v_and_b32_e32 v143, 0xffff0000, v9
	v_lshlrev_b32_e32 v144, 16, v10
	v_and_b32_e32 v145, 0xffff0000, v10
	v_lshlrev_b32_e32 v146, 16, v11
	v_and_b32_e32 v147, 0xffff0000, v11
	v_pk_add_f32 v[124:125], v[124:125], v[132:133]
	v_pk_add_f32 v[126:127], v[126:127], v[134:135]
	v_pk_add_f32 v[128:129], v[128:129], v[136:137]
	v_pk_add_f32 v[130:131], v[130:131], v[138:139]
	v_pk_add_f32 v[124:125], v[124:125], v[140:141] neg_lo:[0,1] neg_hi:[0,1]
	v_pk_add_f32 v[126:127], v[126:127], v[142:143] neg_lo:[0,1] neg_hi:[0,1]
	v_pk_add_f32 v[128:129], v[128:129], v[144:145] neg_lo:[0,1] neg_hi:[0,1]
	v_pk_add_f32 v[130:131], v[130:131], v[146:147] neg_lo:[0,1] neg_hi:[0,1]
	v_add_u32_e32 v170, 7, v169
	v_min_u32_e32 v170, s56, v170
	v_add_u32_e32 v171, -1, v169
	v_max_i32_e32 v171, 0, v171
	v_sub_u32_e32 v170, v170, v171
	v_cvt_f32_u32_e32 v170, v170
	v_rcp_f32_e32 v174, v170
	v_lshlrev_b32_e32 v132, 16, v28
	v_and_b32_e32 v133, 0xffff0000, v28
	v_lshlrev_b32_e32 v134, 16, v29
	v_and_b32_e32 v135, 0xffff0000, v29
	v_lshlrev_b32_e32 v136, 16, v30
	v_and_b32_e32 v137, 0xffff0000, v30
	v_lshlrev_b32_e32 v138, 16, v31
	v_and_b32_e32 v139, 0xffff0000, v31
	v_pk_fma_f32 v[140:141], v[124:125], v[174:175], v[132:133] op_sel_hi:[1,0,1] neg_lo:[0,0,1] neg_hi:[0,0,1]
	v_pk_fma_f32 v[142:143], v[126:127], v[174:175], v[134:135] op_sel_hi:[1,0,1] neg_lo:[0,0,1] neg_hi:[0,0,1]
	v_pk_fma_f32 v[144:145], v[128:129], v[174:175], v[136:137] op_sel_hi:[1,0,1] neg_lo:[0,0,1] neg_hi:[0,0,1]
	v_pk_fma_f32 v[146:147], v[130:131], v[174:175], v[138:139] op_sel_hi:[1,0,1] neg_lo:[0,0,1] neg_hi:[0,0,1]
	v_cvt_pk_bf16_f32 v148, v140, v141
	v_cvt_pk_bf16_f32 v149, v142, v143
	v_cvt_pk_bf16_f32 v150, v144, v145
	v_cvt_pk_bf16_f32 v151, v146, v147
	global_store_dwordx4 v168, v[148:151], s[54:55]
	v_add_u32_e32 v168, 0x800, v168
	v_lshlrev_b32_e32 v132, 16, v44
	v_and_b32_e32 v133, 0xffff0000, v44
	v_lshlrev_b32_e32 v134, 16, v45
	v_and_b32_e32 v135, 0xffff0000, v45
	v_lshlrev_b32_e32 v136, 16, v46
	v_and_b32_e32 v137, 0xffff0000, v46
	v_lshlrev_b32_e32 v138, 16, v47
	v_and_b32_e32 v139, 0xffff0000, v47
	v_lshlrev_b32_e32 v140, 16, v12
	v_and_b32_e32 v141, 0xffff0000, v12
	v_lshlrev_b32_e32 v142, 16, v13
	v_and_b32_e32 v143, 0xffff0000, v13
	v_lshlrev_b32_e32 v144, 16, v14
	v_and_b32_e32 v145, 0xffff0000, v14
	v_lshlrev_b32_e32 v146, 16, v15
	v_and_b32_e32 v147, 0xffff0000, v15
	v_pk_add_f32 v[124:125], v[124:125], v[132:133]
	v_pk_add_f32 v[126:127], v[126:127], v[134:135]
	v_pk_add_f32 v[128:129], v[128:129], v[136:137]
	v_pk_add_f32 v[130:131], v[130:131], v[138:139]
	v_pk_add_f32 v[124:125], v[124:125], v[140:141] neg_lo:[0,1] neg_hi:[0,1]
	v_pk_add_f32 v[126:127], v[126:127], v[142:143] neg_lo:[0,1] neg_hi:[0,1]
	v_pk_add_f32 v[128:129], v[128:129], v[144:145] neg_lo:[0,1] neg_hi:[0,1]
	v_pk_add_f32 v[130:131], v[130:131], v[146:147] neg_lo:[0,1] neg_hi:[0,1]
	v_add_u32_e32 v170, 8, v169
	v_min_u32_e32 v170, s56, v170
	v_add_u32_e32 v171, 0, v169
	v_max_i32_e32 v171, 0, v171
	v_sub_u32_e32 v170, v170, v171
	v_cvt_f32_u32_e32 v170, v170
	v_rcp_f32_e32 v174, v170
	v_lshlrev_b32_e32 v132, 16, v32
	v_and_b32_e32 v133, 0xffff0000, v32
	v_lshlrev_b32_e32 v134, 16, v33
	v_and_b32_e32 v135, 0xffff0000, v33
	v_lshlrev_b32_e32 v136, 16, v34
	v_and_b32_e32 v137, 0xffff0000, v34
	v_lshlrev_b32_e32 v138, 16, v35
	v_and_b32_e32 v139, 0xffff0000, v35
	v_pk_fma_f32 v[140:141], v[124:125], v[174:175], v[132:133] op_sel_hi:[1,0,1] neg_lo:[0,0,1] neg_hi:[0,0,1]
	v_pk_fma_f32 v[142:143], v[126:127], v[174:175], v[134:135] op_sel_hi:[1,0,1] neg_lo:[0,0,1] neg_hi:[0,0,1]
	v_pk_fma_f32 v[144:145], v[128:129], v[174:175], v[136:137] op_sel_hi:[1,0,1] neg_lo:[0,0,1] neg_hi:[0,0,1]
	v_pk_fma_f32 v[146:147], v[130:131], v[174:175], v[138:139] op_sel_hi:[1,0,1] neg_lo:[0,0,1] neg_hi:[0,0,1]
	v_cvt_pk_bf16_f32 v148, v140, v141
	v_cvt_pk_bf16_f32 v149, v142, v143
	v_cvt_pk_bf16_f32 v150, v144, v145
	v_cvt_pk_bf16_f32 v151, v146, v147
	global_store_dwordx4 v168, v[148:151], s[54:55]
	v_add_u32_e32 v168, 0x800, v168
	v_lshlrev_b32_e32 v132, 16, v48
	v_and_b32_e32 v133, 0xffff0000, v48
	v_lshlrev_b32_e32 v134, 16, v49
	v_and_b32_e32 v135, 0xffff0000, v49
	v_lshlrev_b32_e32 v136, 16, v50
	v_and_b32_e32 v137, 0xffff0000, v50
	v_lshlrev_b32_e32 v138, 16, v51
	v_and_b32_e32 v139, 0xffff0000, v51
; __device__ __forceinline__ u32x4 pack8(const f32x4 a, const f32x4 b) { u32x4 w; w.x = cvt_pk_bf16(a[0], a[1]); w.y = cvt_pk_bf16(a[2], a[3]); w.z = cvt_pk_bf16(b[0], b[1]); w.w = cvt_pk_bf16(b[2], b[3]); return w; }
; __global__ void __launch_bounds__(512, 2) fwd_mega(Args a) {
;     ...
;             for (int s = s0; s < s0 + 32; ++s) {
;                 f32x4 u0, u1; pg8::unpack8(*(const u32x4*)(base + (size_t)s * 512), u0, u1);
;                 const int jlo = (s - hw) > 0 ? (s - hw) : 0, jhi = (s + hw) < SEQ ? (s + hw) : SEQ;
;                 const float rc = 1.0f / (float)(jhi - jlo);
;                 *(u32x4*)(obase + (size_t)s * 1024) = pg8::pack8(w0 * rc - u0, w1 * rc - u1);
;                 if (s + hw < SEQ) { f32x4 a0, a1; pg8::unpack8(*(const u32x4*)(base + (size_t)(s + hw) * 512), a0, a1); w0 += a0; w1 += a1; }
;                 if (s - hw >= 0) { f32x4 a0, a1; pg8::unpack8(*(const u32x4*)(base + (size_t)(s - hw) * 512), a0, a1); w0 -= a0; w1 -= a1; }
	v_lshlrev_b32_e32 v140, 16, v16
	v_and_b32_e32 v141, 0xffff0000, v16
	v_lshlrev_b32_e32 v142, 16, v17
	v_and_b32_e32 v143, 0xffff0000, v17
	v_lshlrev_b32_e32 v144, 16, v18
	v_and_b32_e32 v145, 0xffff0000, v18
	v_lshlrev_b32_e32 v146, 16, v19
	v_and_b32_e32 v147, 0xffff0000, v19
	v_pk_add_f32 v[124:125], v[124:125], v[132:133]
	v_pk_add_f32 v[126:127], v[126:127], v[134:135]
	v_pk_add_f32 v[128:129], v[128:129], v[136:137]
	v_pk_add_f32 v[130:131], v[130:131], v[138:139]
	v_pk_add_f32 v[124:125], v[124:125], v[140:141] neg_lo:[0,1] neg_hi:[0,1]
	v_pk_add_f32 v[126:127], v[126:127], v[142:143] neg_lo:[0,1] neg_hi:[0,1]
	v_pk_add_f32 v[128:129], v[128:129], v[144:145] neg_lo:[0,1] neg_hi:[0,1]
	v_pk_add_f32 v[130:131], v[130:131], v[146:147] neg_lo:[0,1] neg_hi:[0,1]
	v_add_u32_e32 v170, 9, v169
	v_min_u32_e32 v170, s56, v170
	v_add_u32_e32 v171, 1, v169
	v_max_i32_e32 v171, 0, v171
	v_sub_u32_e32 v170, v170, v171
	v_cvt_f32_u32_e32 v170, v170
	v_rcp_f32_e32 v174, v170
	v_lshlrev_b32_e32 v132, 16, v36
	v_and_b32_e32 v133, 0xffff0000, v36
	v_lshlrev_b32_e32 v134, 16, v37
	v_and_b32_e32 v135, 0xffff0000, v37
	v_lshlrev_b32_e32 v136, 16, v38
	v_and_b32_e32 v137, 0xffff0000, v38
	v_lshlrev_b32_e32 v138, 16, v39
	v_and_b32_e32 v139, 0xffff0000, v39
	v_pk_fma_f32 v[140:141], v[124:125], v[174:175], v[132:133] op_sel_hi:[1,0,1] neg_lo:[0,0,1] neg_hi:[0,0,1]
	v_pk_fma_f32 v[142:143], v[126:127], v[174:175], v[134:135] op_sel_hi:[1,0,1] neg_lo:[0,0,1] neg_hi:[0,0,1]
	v_pk_fma_f32 v[144:145], v[128:129], v[174:175], v[136:137] op_sel_hi:[1,0,1] neg_lo:[0,0,1] neg_hi:[0,0,1]
	v_pk_fma_f32 v[146:147], v[130:131], v[174:175], v[138:139] op_sel_hi:[1,0,1] neg_lo:[0,0,1] neg_hi:[0,0,1]
	v_cvt_pk_bf16_f32 v148, v140, v141
	v_cvt_pk_bf16_f32 v149, v142, v143
	v_cvt_pk_bf16_f32 v150, v144, v145
	v_cvt_pk_bf16_f32 v151, v146, v147
	global_store_dwordx4 v168, v[148:151], s[54:55]
	v_add_u32_e32 v168, 0x800, v168
	v_lshlrev_b32_e32 v132, 16, v52
	v_and_b32_e32 v133, 0xffff0000, v52
	v_lshlrev_b32_e32 v134, 16, v53
	v_and_b32_e32 v135, 0xffff0000, v53
	v_lshlrev_b32_e32 v136, 16, v54
	v_and_b32_e32 v137, 0xffff0000, v54
	v_lshlrev_b32_e32 v138, 16, v55
	v_and_b32_e32 v139, 0xffff0000, v55
	v_lshlrev_b32_e32 v140, 16, v20
	v_and_b32_e32 v141, 0xffff0000, v20
	v_lshlrev_b32_e32 v142, 16, v21
	v_and_b32_e32 v143, 0xffff0000, v21
	v_lshlrev_b32_e32 v144, 16, v22
	v_and_b32_e32 v145, 0xffff0000, v22
	v_lshlrev_b32_e32 v146, 16, v23
	v_and_b32_e32 v147, 0xffff0000, v23
	v_pk_add_f32 v[124:125], v[124:125], v[132:133]
	v_pk_add_f32 v[126:127], v[126:127], v[134:135]
	v_pk_add_f32 v[128:129], v[128:129], v[136:137]
	v_pk_add_f32 v[130:131], v[130:131], v[138:139]
	v_pk_add_f32 v[124:125], v[124:125], v[140:141] neg_lo:[0,1] neg_hi:[0,1]
	v_pk_add_f32 v[126:127], v[126:127], v[142:143] neg_lo:[0,1] neg_hi:[0,1]
	v_pk_add_f32 v[128:129], v[128:129], v[144:145] neg_lo:[0,1] neg_hi:[0,1]
	v_pk_add_f32 v[130:131], v[130:131], v[146:147] neg_lo:[0,1] neg_hi:[0,1]
	v_add_u32_e32 v170, 10, v169
	v_min_u32_e32 v170, s56, v170
	v_add_u32_e32 v171, 2, v169
	v_max_i32_e32 v171, 0, v171
	v_sub_u32_e32 v170, v170, v171
	v_cvt_f32_u32_e32 v170, v170
	v_rcp_f32_e32 v174, v170
	v_lshlrev_b32_e32 v132, 16, v40
	v_and_b32_e32 v133, 0xffff0000, v40
	v_lshlrev_b32_e32 v134, 16, v41
	v_and_b32_e32 v135, 0xffff0000, v41
	v_lshlrev_b32_e32 v136, 16, v42
	v_and_b32_e32 v137, 0xffff0000, v42
	v_lshlrev_b32_e32 v138, 16, v43
	v_and_b32_e32 v139, 0xffff0000, v43
	v_pk_fma_f32 v[140:141], v[124:125], v[174:175], v[132:133] op_sel_hi:[1,0,1] neg_lo:[0,0,1] neg_hi:[0,0,1]
	v_pk_fma_f32 v[142:143], v[126:127], v[174:175], v[134:135] op_sel_hi:[1,0,1] neg_lo:[0,0,1] neg_hi:[0,0,1]
	v_pk_fma_f32 v[144:145], v[128:129], v[174:175], v[136:137] op_sel_hi:[1,0,1] neg_lo:[0,0,1] neg_hi:[0,0,1]
	v_pk_fma_f32 v[146:147], v[130:131], v[174:175], v[138:139] op_sel_hi:[1,0,1] neg_lo:[0,0,1] neg_hi:[0,0,1]
	v_cvt_pk_bf16_f32 v148, v140, v141
	v_cvt_pk_bf16_f32 v149, v142, v143
	v_cvt_pk_bf16_f32 v150, v144, v145
	v_cvt_pk_bf16_f32 v151, v146, v147
	global_store_dwordx4 v168, v[148:151], s[54:55]
	v_add_u32_e32 v168, 0x800, v168
	v_lshlrev_b32_e32 v132, 16, v56
	v_and_b32_e32 v133, 0xffff0000, v56
	v_lshlrev_b32_e32 v134, 16, v57
	v_and_b32_e32 v135, 0xffff0000, v57
	v_lshlrev_b32_e32 v136, 16, v58
	v_and_b32_e32 v137, 0xffff0000, v58
	v_lshlrev_b32_e32 v138, 16, v59
	v_and_b32_e32 v139, 0xffff0000, v59
	v_lshlrev_b32_e32 v140, 16, v24
	v_and_b32_e32 v141, 0xffff0000, v24
	v_lshlrev_b32_e32 v142, 16, v25
	v_and_b32_e32 v143, 0xffff0000, v25
	v_lshlrev_b32_e32 v144, 16, v26
	v_and_b32_e32 v145, 0xffff0000, v26
	v_lshlrev_b32_e32 v146, 16, v27
	v_and_b32_e32 v147, 0xffff0000, v27
	v_pk_add_f32 v[124:125], v[124:125], v[132:133]
	v_pk_add_f32 v[126:127], v[126:127], v[134:135]
	v_pk_add_f32 v[128:129], v[128:129], v[136:137]
	v_pk_add_f32 v[130:131], v[130:131], v[138:139]
	v_pk_add_f32 v[124:125], v[124:125], v[140:141] neg_lo:[0,1] neg_hi:[0,1]
	v_pk_add_f32 v[126:127], v[126:127], v[142:143] neg_lo:[0,1] neg_hi:[0,1]
	v_pk_add_f32 v[128:129], v[128:129], v[144:145] neg_lo:[0,1] neg_hi:[0,1]
	v_pk_add_f32 v[130:131], v[130:131], v[146:147] neg_lo:[0,1] neg_hi:[0,1]
	v_add_u32_e32 v170, 11, v169
	v_min_u32_e32 v170, s56, v170
	v_add_u32_e32 v171, 3, v169
	v_max_i32_e32 v171, 0, v171
	v_sub_u32_e32 v170, v170, v171
	v_cvt_f32_u32_e32 v170, v170
	v_rcp_f32_e32 v174, v170
	v_lshlrev_b32_e32 v132, 16, v44
	v_and_b32_e32 v133, 0xffff0000, v44
	v_lshlrev_b32_e32 v134, 16, v45
	v_and_b32_e32 v135, 0xffff0000, v45
	v_lshlrev_b32_e32 v136, 16, v46
	v_and_b32_e32 v137, 0xffff0000, v46
	v_lshlrev_b32_e32 v138, 16, v47
; __device__ __forceinline__ u32x4 pack8(const f32x4 a, const f32x4 b) { u32x4 w; w.x = cvt_pk_bf16(a[0], a[1]); w.y = cvt_pk_bf16(a[2], a[3]); w.z = cvt_pk_bf16(b[0], b[1]); w.w = cvt_pk_bf16(b[2], b[3]); return w; }
; __global__ void __launch_bounds__(512, 2) fwd_mega(Args a) {
;     ...
;             for (int s = s0; s < s0 + 32; ++s) {
;                 f32x4 u0, u1; pg8::unpack8(*(const u32x4*)(base + (size_t)s * 512), u0, u1);
;                 const int jlo = (s - hw) > 0 ? (s - hw) : 0, jhi = (s + hw) < SEQ ? (s + hw) : SEQ;
;                 const float rc = 1.0f / (float)(jhi - jlo);
;                 *(u32x4*)(obase + (size_t)s * 1024) = pg8::pack8(w0 * rc - u0, w1 * rc - u1);
;                 if (s + hw < SEQ) { f32x4 a0, a1; pg8::unpack8(*(const u32x4*)(base + (size_t)(s + hw) * 512), a0, a1); w0 += a0; w1 += a1; }
;                 if (s - hw >= 0) { f32x4 a0, a1; pg8::unpack8(*(const u32x4*)(base + (size_t)(s - hw) * 512), a0, a1); w0 -= a0; w1 -= a1; }
	v_and_b32_e32 v139, 0xffff0000, v47
	v_pk_fma_f32 v[140:141], v[124:125], v[174:175], v[132:133] op_sel_hi:[1,0,1] neg_lo:[0,0,1] neg_hi:[0,0,1]
	v_pk_fma_f32 v[142:143], v[126:127], v[174:175], v[134:135] op_sel_hi:[1,0,1] neg_lo:[0,0,1] neg_hi:[0,0,1]
	v_pk_fma_f32 v[144:145], v[128:129], v[174:175], v[136:137] op_sel_hi:[1,0,1] neg_lo:[0,0,1] neg_hi:[0,0,1]
	v_pk_fma_f32 v[146:147], v[130:131], v[174:175], v[138:139] op_sel_hi:[1,0,1] neg_lo:[0,0,1] neg_hi:[0,0,1]
	v_cvt_pk_bf16_f32 v148, v140, v141
	v_cvt_pk_bf16_f32 v149, v142, v143
	v_cvt_pk_bf16_f32 v150, v144, v145
	v_cvt_pk_bf16_f32 v151, v146, v147
	global_store_dwordx4 v168, v[148:151], s[54:55]
	v_add_u32_e32 v168, 0x800, v168
	v_lshlrev_b32_e32 v132, 16, v60
	v_and_b32_e32 v133, 0xffff0000, v60
	v_lshlrev_b32_e32 v134, 16, v61
	v_and_b32_e32 v135, 0xffff0000, v61
	v_lshlrev_b32_e32 v136, 16, v62
	v_and_b32_e32 v137, 0xffff0000, v62
	v_lshlrev_b32_e32 v138, 16, v63
	v_and_b32_e32 v139, 0xffff0000, v63
	v_lshlrev_b32_e32 v140, 16, v28
	v_and_b32_e32 v141, 0xffff0000, v28
	v_lshlrev_b32_e32 v142, 16, v29
	v_and_b32_e32 v143, 0xffff0000, v29
	v_lshlrev_b32_e32 v144, 16, v30
	v_and_b32_e32 v145, 0xffff0000, v30
	v_lshlrev_b32_e32 v146, 16, v31
	v_and_b32_e32 v147, 0xffff0000, v31
	v_pk_add_f32 v[124:125], v[124:125], v[132:133]
	v_pk_add_f32 v[126:127], v[126:127], v[134:135]
	v_pk_add_f32 v[128:129], v[128:129], v[136:137]
	v_pk_add_f32 v[130:131], v[130:131], v[138:139]
	v_pk_add_f32 v[124:125], v[124:125], v[140:141] neg_lo:[0,1] neg_hi:[0,1]
	v_pk_add_f32 v[126:127], v[126:127], v[142:143] neg_lo:[0,1] neg_hi:[0,1]
	v_pk_add_f32 v[128:129], v[128:129], v[144:145] neg_lo:[0,1] neg_hi:[0,1]
	v_pk_add_f32 v[130:131], v[130:131], v[146:147] neg_lo:[0,1] neg_hi:[0,1]
	v_add_u32_e32 v170, 12, v169
	v_min_u32_e32 v170, s56, v170
	v_add_u32_e32 v171, 4, v169
	v_max_i32_e32 v171, 0, v171
	v_sub_u32_e32 v170, v170, v171
	v_cvt_f32_u32_e32 v170, v170
	v_rcp_f32_e32 v174, v170
	v_lshlrev_b32_e32 v132, 16, v48
	v_and_b32_e32 v133, 0xffff0000, v48
	v_lshlrev_b32_e32 v134, 16, v49
	v_and_b32_e32 v135, 0xffff0000, v49
	v_lshlrev_b32_e32 v136, 16, v50
	v_and_b32_e32 v137, 0xffff0000, v50
	v_lshlrev_b32_e32 v138, 16, v51
	v_and_b32_e32 v139, 0xffff0000, v51
	v_pk_fma_f32 v[140:141], v[124:125], v[174:175], v[132:133] op_sel_hi:[1,0,1] neg_lo:[0,0,1] neg_hi:[0,0,1]
	v_pk_fma_f32 v[142:143], v[126:127], v[174:175], v[134:135] op_sel_hi:[1,0,1] neg_lo:[0,0,1] neg_hi:[0,0,1]
	v_pk_fma_f32 v[144:145], v[128:129], v[174:175], v[136:137] op_sel_hi:[1,0,1] neg_lo:[0,0,1] neg_hi:[0,0,1]
	v_pk_fma_f32 v[146:147], v[130:131], v[174:175], v[138:139] op_sel_hi:[1,0,1] neg_lo:[0,0,1] neg_hi:[0,0,1]
	v_cvt_pk_bf16_f32 v148, v140, v141
	v_cvt_pk_bf16_f32 v149, v142, v143
	v_cvt_pk_bf16_f32 v150, v144, v145
	v_cvt_pk_bf16_f32 v151, v146, v147
	global_store_dwordx4 v168, v[148:151], s[54:55]
	v_add_u32_e32 v168, 0x800, v168
	v_lshlrev_b32_e32 v132, 16, v64
	v_and_b32_e32 v133, 0xffff0000, v64
	v_lshlrev_b32_e32 v134, 16, v65
	v_and_b32_e32 v135, 0xffff0000, v65
	v_lshlrev_b32_e32 v136, 16, v66
	v_and_b32_e32 v137, 0xffff0000, v66
	v_lshlrev_b32_e32 v138, 16, v67
	v_and_b32_e32 v139, 0xffff0000, v67
	v_lshlrev_b32_e32 v140, 16, v32
	v_and_b32_e32 v141, 0xffff0000, v32
	v_lshlrev_b32_e32 v142, 16, v33
	v_and_b32_e32 v143, 0xffff0000, v33
	v_lshlrev_b32_e32 v144, 16, v34
	v_and_b32_e32 v145, 0xffff0000, v34
	v_lshlrev_b32_e32 v146, 16, v35
	v_and_b32_e32 v147, 0xffff0000, v35
	v_pk_add_f32 v[124:125], v[124:125], v[132:133]
	v_pk_add_f32 v[126:127], v[126:127], v[134:135]
	v_pk_add_f32 v[128:129], v[128:129], v[136:137]
	v_pk_add_f32 v[130:131], v[130:131], v[138:139]
	v_pk_add_f32 v[124:125], v[124:125], v[140:141] neg_lo:[0,1] neg_hi:[0,1]
	v_pk_add_f32 v[126:127], v[126:127], v[142:143] neg_lo:[0,1] neg_hi:[0,1]
	v_pk_add_f32 v[128:129], v[128:129], v[144:145] neg_lo:[0,1] neg_hi:[0,1]
	v_pk_add_f32 v[130:131], v[130:131], v[146:147] neg_lo:[0,1] neg_hi:[0,1]
	v_add_u32_e32 v170, 13, v169
	v_min_u32_e32 v170, s56, v170
	v_add_u32_e32 v171, 5, v169
	v_max_i32_e32 v171, 0, v171
	v_sub_u32_e32 v170, v170, v171
	v_cvt_f32_u32_e32 v170, v170
	v_rcp_f32_e32 v174, v170
	v_lshlrev_b32_e32 v132, 16, v52
	v_and_b32_e32 v133, 0xffff0000, v52
	v_lshlrev_b32_e32 v134, 16, v53
	v_and_b32_e32 v135, 0xffff0000, v53
	v_lshlrev_b32_e32 v136, 16, v54
	v_and_b32_e32 v137, 0xffff0000, v54
	v_lshlrev_b32_e32 v138, 16, v55
	v_and_b32_e32 v139, 0xffff0000, v55
	v_pk_fma_f32 v[140:141], v[124:125], v[174:175], v[132:133] op_sel_hi:[1,0,1] neg_lo:[0,0,1] neg_hi:[0,0,1]
	v_pk_fma_f32 v[142:143], v[126:127], v[174:175], v[134:135] op_sel_hi:[1,0,1] neg_lo:[0,0,1] neg_hi:[0,0,1]
	v_pk_fma_f32 v[144:145], v[128:129], v[174:175], v[136:137] op_sel_hi:[1,0,1] neg_lo:[0,0,1] neg_hi:[0,0,1]
	v_pk_fma_f32 v[146:147], v[130:131], v[174:175], v[138:139] op_sel_hi:[1,0,1] neg_lo:[0,0,1] neg_hi:[0,0,1]
	v_cvt_pk_bf16_f32 v148, v140, v141
	v_cvt_pk_bf16_f32 v149, v142, v143
	v_cvt_pk_bf16_f32 v150, v144, v145
	v_cvt_pk_bf16_f32 v151, v146, v147
	global_store_dwordx4 v168, v[148:151], s[54:55]
	v_add_u32_e32 v168, 0x800, v168
	v_lshlrev_b32_e32 v132, 16, v68
	v_and_b32_e32 v133, 0xffff0000, v68
	v_lshlrev_b32_e32 v134, 16, v69
	v_and_b32_e32 v135, 0xffff0000, v69
	v_lshlrev_b32_e32 v136, 16, v70
	v_and_b32_e32 v137, 0xffff0000, v70
	v_lshlrev_b32_e32 v138, 16, v71
	v_and_b32_e32 v139, 0xffff0000, v71
	v_lshlrev_b32_e32 v140, 16, v36
	v_and_b32_e32 v141, 0xffff0000, v36
	v_lshlrev_b32_e32 v142, 16, v37
	v_and_b32_e32 v143, 0xffff0000, v37
	v_lshlrev_b32_e32 v144, 16, v38
	v_and_b32_e32 v145, 0xffff0000, v38
	v_lshlrev_b32_e32 v146, 16, v39
; __device__ __forceinline__ u32x4 pack8(const f32x4 a, const f32x4 b) { u32x4 w; w.x = cvt_pk_bf16(a[0], a[1]); w.y = cvt_pk_bf16(a[2], a[3]); w.z = cvt_pk_bf16(b[0], b[1]); w.w = cvt_pk_bf16(b[2], b[3]); return w; }
; __global__ void __launch_bounds__(512, 2) fwd_mega(Args a) {
;     ...
;             for (int s = s0; s < s0 + 32; ++s) {
;                 f32x4 u0, u1; pg8::unpack8(*(const u32x4*)(base + (size_t)s * 512), u0, u1);
;                 const int jlo = (s - hw) > 0 ? (s - hw) : 0, jhi = (s + hw) < SEQ ? (s + hw) : SEQ;
;                 const float rc = 1.0f / (float)(jhi - jlo);
;                 *(u32x4*)(obase + (size_t)s * 1024) = pg8::pack8(w0 * rc - u0, w1 * rc - u1);
;                 if (s + hw < SEQ) { f32x4 a0, a1; pg8::unpack8(*(const u32x4*)(base + (size_t)(s + hw) * 512), a0, a1); w0 += a0; w1 += a1; }
;                 if (s - hw >= 0) { f32x4 a0, a1; pg8::unpack8(*(const u32x4*)(base + (size_t)(s - hw) * 512), a0, a1); w0 -= a0; w1 -= a1; }
	v_and_b32_e32 v147, 0xffff0000, v39
	v_pk_add_f32 v[124:125], v[124:125], v[132:133]
	v_pk_add_f32 v[126:127], v[126:127], v[134:135]
	v_pk_add_f32 v[128:129], v[128:129], v[136:137]
	v_pk_add_f32 v[130:131], v[130:131], v[138:139]
	v_pk_add_f32 v[124:125], v[124:125], v[140:141] neg_lo:[0,1] neg_hi:[0,1]
	v_pk_add_f32 v[126:127], v[126:127], v[142:143] neg_lo:[0,1] neg_hi:[0,1]
	v_pk_add_f32 v[128:129], v[128:129], v[144:145] neg_lo:[0,1] neg_hi:[0,1]
	v_pk_add_f32 v[130:131], v[130:131], v[146:147] neg_lo:[0,1] neg_hi:[0,1]
	v_add_u32_e32 v170, 14, v169
	v_min_u32_e32 v170, s56, v170
	v_add_u32_e32 v171, 6, v169
	v_max_i32_e32 v171, 0, v171
	v_sub_u32_e32 v170, v170, v171
	v_cvt_f32_u32_e32 v170, v170
	v_rcp_f32_e32 v174, v170
	v_lshlrev_b32_e32 v132, 16, v56
	v_and_b32_e32 v133, 0xffff0000, v56
	v_lshlrev_b32_e32 v134, 16, v57
	v_and_b32_e32 v135, 0xffff0000, v57
	v_lshlrev_b32_e32 v136, 16, v58
	v_and_b32_e32 v137, 0xffff0000, v58
	v_lshlrev_b32_e32 v138, 16, v59
	v_and_b32_e32 v139, 0xffff0000, v59
	v_pk_fma_f32 v[140:141], v[124:125], v[174:175], v[132:133] op_sel_hi:[1,0,1] neg_lo:[0,0,1] neg_hi:[0,0,1]
	v_pk_fma_f32 v[142:143], v[126:127], v[174:175], v[134:135] op_sel_hi:[1,0,1] neg_lo:[0,0,1] neg_hi:[0,0,1]
	v_pk_fma_f32 v[144:145], v[128:129], v[174:175], v[136:137] op_sel_hi:[1,0,1] neg_lo:[0,0,1] neg_hi:[0,0,1]
	v_pk_fma_f32 v[146:147], v[130:131], v[174:175], v[138:139] op_sel_hi:[1,0,1] neg_lo:[0,0,1] neg_hi:[0,0,1]
	v_cvt_pk_bf16_f32 v148, v140, v141
	v_cvt_pk_bf16_f32 v149, v142, v143
	v_cvt_pk_bf16_f32 v150, v144, v145
	v_cvt_pk_bf16_f32 v151, v146, v147
	global_store_dwordx4 v168, v[148:151], s[54:55]
	v_add_u32_e32 v168, 0x800, v168
	v_lshlrev_b32_e32 v132, 16, v72
	v_and_b32_e32 v133, 0xffff0000, v72
	v_lshlrev_b32_e32 v134, 16, v73
	v_and_b32_e32 v135, 0xffff0000, v73
	v_lshlrev_b32_e32 v136, 16, v74
	v_and_b32_e32 v137, 0xffff0000, v74
	v_lshlrev_b32_e32 v138, 16, v75
	v_and_b32_e32 v139, 0xffff0000, v75
	v_lshlrev_b32_e32 v140, 16, v40
	v_and_b32_e32 v141, 0xffff0000, v40
	v_lshlrev_b32_e32 v142, 16, v41
	v_and_b32_e32 v143, 0xffff0000, v41
	v_lshlrev_b32_e32 v144, 16, v42
	v_and_b32_e32 v145, 0xffff0000, v42
	v_lshlrev_b32_e32 v146, 16, v43
	v_and_b32_e32 v147, 0xffff0000, v43
	v_pk_add_f32 v[124:125], v[124:125], v[132:133]
	v_pk_add_f32 v[126:127], v[126:127], v[134:135]
	v_pk_add_f32 v[128:129], v[128:129], v[136:137]
	v_pk_add_f32 v[130:131], v[130:131], v[138:139]
	v_pk_add_f32 v[124:125], v[124:125], v[140:141] neg_lo:[0,1] neg_hi:[0,1]
	v_pk_add_f32 v[126:127], v[126:127], v[142:143] neg_lo:[0,1] neg_hi:[0,1]
	v_pk_add_f32 v[128:129], v[128:129], v[144:145] neg_lo:[0,1] neg_hi:[0,1]
	v_pk_add_f32 v[130:131], v[130:131], v[146:147] neg_lo:[0,1] neg_hi:[0,1]
	v_add_u32_e32 v170, 15, v169
	v_min_u32_e32 v170, s56, v170
	v_add_u32_e32 v171, 7, v169
	v_max_i32_e32 v171, 0, v171
	v_sub_u32_e32 v170, v170, v171
	v_cvt_f32_u32_e32 v170, v170
	v_rcp_f32_e32 v174, v170
	v_lshlrev_b32_e32 v132, 16, v60
	v_and_b32_e32 v133, 0xffff0000, v60
	v_lshlrev_b32_e32 v134, 16, v61
	v_and_b32_e32 v135, 0xffff0000, v61
	v_lshlrev_b32_e32 v136, 16, v62
	v_and_b32_e32 v137, 0xffff0000, v62
	v_lshlrev_b32_e32 v138, 16, v63
	v_and_b32_e32 v139, 0xffff0000, v63
	v_pk_fma_f32 v[140:141], v[124:125], v[174:175], v[132:133] op_sel_hi:[1,0,1] neg_lo:[0,0,1] neg_hi:[0,0,1]
	v_pk_fma_f32 v[142:143], v[126:127], v[174:175], v[134:135] op_sel_hi:[1,0,1] neg_lo:[0,0,1] neg_hi:[0,0,1]
	v_pk_fma_f32 v[144:145], v[128:129], v[174:175], v[136:137] op_sel_hi:[1,0,1] neg_lo:[0,0,1] neg_hi:[0,0,1]
	v_pk_fma_f32 v[146:147], v[130:131], v[174:175], v[138:139] op_sel_hi:[1,0,1] neg_lo:[0,0,1] neg_hi:[0,0,1]
	v_cvt_pk_bf16_f32 v148, v140, v141
	v_cvt_pk_bf16_f32 v149, v142, v143
	v_cvt_pk_bf16_f32 v150, v144, v145
	v_cvt_pk_bf16_f32 v151, v146, v147
	global_store_dwordx4 v168, v[148:151], s[54:55]
	v_add_u32_e32 v168, 0x800, v168
	v_lshlrev_b32_e32 v132, 16, v76
	v_and_b32_e32 v133, 0xffff0000, v76
	v_lshlrev_b32_e32 v134, 16, v77
	v_and_b32_e32 v135, 0xffff0000, v77
	v_lshlrev_b32_e32 v136, 16, v78
	v_and_b32_e32 v137, 0xffff0000, v78
	v_lshlrev_b32_e32 v138, 16, v79
	v_and_b32_e32 v139, 0xffff0000, v79
	v_lshlrev_b32_e32 v140, 16, v44
	v_and_b32_e32 v141, 0xffff0000, v44
	v_lshlrev_b32_e32 v142, 16, v45
	v_and_b32_e32 v143, 0xffff0000, v45
	v_lshlrev_b32_e32 v144, 16, v46
	v_and_b32_e32 v145, 0xffff0000, v46
	v_lshlrev_b32_e32 v146, 16, v47
	v_and_b32_e32 v147, 0xffff0000, v47
	v_pk_add_f32 v[124:125], v[124:125], v[132:133]
	v_pk_add_f32 v[126:127], v[126:127], v[134:135]
	v_pk_add_f32 v[128:129], v[128:129], v[136:137]
	v_pk_add_f32 v[130:131], v[130:131], v[138:139]
	v_pk_add_f32 v[124:125], v[124:125], v[140:141] neg_lo:[0,1] neg_hi:[0,1]
	v_pk_add_f32 v[126:127], v[126:127], v[142:143] neg_lo:[0,1] neg_hi:[0,1]
	v_pk_add_f32 v[128:129], v[128:129], v[144:145] neg_lo:[0,1] neg_hi:[0,1]
	v_pk_add_f32 v[130:131], v[130:131], v[146:147] neg_lo:[0,1] neg_hi:[0,1]
	v_add_u32_e32 v170, 16, v169
	v_min_u32_e32 v170, s56, v170
	v_add_u32_e32 v171, 8, v169
	v_max_i32_e32 v171, 0, v171
	v_sub_u32_e32 v170, v170, v171
	v_cvt_f32_u32_e32 v170, v170
	v_rcp_f32_e32 v174, v170
	v_lshlrev_b32_e32 v132, 16, v64
	v_and_b32_e32 v133, 0xffff0000, v64
	v_lshlrev_b32_e32 v134, 16, v65
	v_and_b32_e32 v135, 0xffff0000, v65
	v_lshlrev_b32_e32 v136, 16, v66
	v_and_b32_e32 v137, 0xffff0000, v66
	v_lshlrev_b32_e32 v138, 16, v67
	v_and_b32_e32 v139, 0xffff0000, v67
	v_pk_fma_f32 v[140:141], v[124:125], v[174:175], v[132:133] op_sel_hi:[1,0,1] neg_lo:[0,0,1] neg_hi:[0,0,1]
	v_pk_fma_f32 v[142:143], v[126:127], v[174:175], v[134:135] op_sel_hi:[1,0,1] neg_lo:[0,0,1] neg_hi:[0,0,1]
; __device__ __forceinline__ u32x4 pack8(const f32x4 a, const f32x4 b) { u32x4 w; w.x = cvt_pk_bf16(a[0], a[1]); w.y = cvt_pk_bf16(a[2], a[3]); w.z = cvt_pk_bf16(b[0], b[1]); w.w = cvt_pk_bf16(b[2], b[3]); return w; }
; __global__ void __launch_bounds__(512, 2) fwd_mega(Args a) {
;     ...
;             for (int s = s0; s < s0 + 32; ++s) {
;                 f32x4 u0, u1; pg8::unpack8(*(const u32x4*)(base + (size_t)s * 512), u0, u1);
;                 const int jlo = (s - hw) > 0 ? (s - hw) : 0, jhi = (s + hw) < SEQ ? (s + hw) : SEQ;
;                 const float rc = 1.0f / (float)(jhi - jlo);
;                 *(u32x4*)(obase + (size_t)s * 1024) = pg8::pack8(w0 * rc - u0, w1 * rc - u1);
;                 if (s + hw < SEQ) { f32x4 a0, a1; pg8::unpack8(*(const u32x4*)(base + (size_t)(s + hw) * 512), a0, a1); w0 += a0; w1 += a1; }
;                 if (s - hw >= 0) { f32x4 a0, a1; pg8::unpack8(*(const u32x4*)(base + (size_t)(s - hw) * 512), a0, a1); w0 -= a0; w1 -= a1; }
	v_pk_fma_f32 v[144:145], v[128:129], v[174:175], v[136:137] op_sel_hi:[1,0,1] neg_lo:[0,0,1] neg_hi:[0,0,1]
	v_pk_fma_f32 v[146:147], v[130:131], v[174:175], v[138:139] op_sel_hi:[1,0,1] neg_lo:[0,0,1] neg_hi:[0,0,1]
	v_cvt_pk_bf16_f32 v148, v140, v141
	v_cvt_pk_bf16_f32 v149, v142, v143
	v_cvt_pk_bf16_f32 v150, v144, v145
	v_cvt_pk_bf16_f32 v151, v146, v147
	global_store_dwordx4 v168, v[148:151], s[54:55]
	v_add_u32_e32 v168, 0x800, v168
	v_lshlrev_b32_e32 v132, 16, v80
	v_and_b32_e32 v133, 0xffff0000, v80
	v_lshlrev_b32_e32 v134, 16, v81
	v_and_b32_e32 v135, 0xffff0000, v81
	v_lshlrev_b32_e32 v136, 16, v82
	v_and_b32_e32 v137, 0xffff0000, v82
	v_lshlrev_b32_e32 v138, 16, v83
	v_and_b32_e32 v139, 0xffff0000, v83
	v_lshlrev_b32_e32 v140, 16, v48
	v_and_b32_e32 v141, 0xffff0000, v48
	v_lshlrev_b32_e32 v142, 16, v49
	v_and_b32_e32 v143, 0xffff0000, v49
	v_lshlrev_b32_e32 v144, 16, v50
	v_and_b32_e32 v145, 0xffff0000, v50
	v_lshlrev_b32_e32 v146, 16, v51
	v_and_b32_e32 v147, 0xffff0000, v51
	v_pk_add_f32 v[124:125], v[124:125], v[132:133]
	v_pk_add_f32 v[126:127], v[126:127], v[134:135]
	v_pk_add_f32 v[128:129], v[128:129], v[136:137]
	v_pk_add_f32 v[130:131], v[130:131], v[138:139]
	v_pk_add_f32 v[124:125], v[124:125], v[140:141] neg_lo:[0,1] neg_hi:[0,1]
	v_pk_add_f32 v[126:127], v[126:127], v[142:143] neg_lo:[0,1] neg_hi:[0,1]
	v_pk_add_f32 v[128:129], v[128:129], v[144:145] neg_lo:[0,1] neg_hi:[0,1]
	v_pk_add_f32 v[130:131], v[130:131], v[146:147] neg_lo:[0,1] neg_hi:[0,1]
	v_add_u32_e32 v170, 17, v169
	v_min_u32_e32 v170, s56, v170
	v_add_u32_e32 v171, 9, v169
	v_max_i32_e32 v171, 0, v171
	v_sub_u32_e32 v170, v170, v171
	v_cvt_f32_u32_e32 v170, v170
	v_rcp_f32_e32 v174, v170
	v_lshlrev_b32_e32 v132, 16, v68
	v_and_b32_e32 v133, 0xffff0000, v68
	v_lshlrev_b32_e32 v134, 16, v69
	v_and_b32_e32 v135, 0xffff0000, v69
	v_lshlrev_b32_e32 v136, 16, v70
	v_and_b32_e32 v137, 0xffff0000, v70
	v_lshlrev_b32_e32 v138, 16, v71
	v_and_b32_e32 v139, 0xffff0000, v71
	v_pk_fma_f32 v[140:141], v[124:125], v[174:175], v[132:133] op_sel_hi:[1,0,1] neg_lo:[0,0,1] neg_hi:[0,0,1]
	v_pk_fma_f32 v[142:143], v[126:127], v[174:175], v[134:135] op_sel_hi:[1,0,1] neg_lo:[0,0,1] neg_hi:[0,0,1]
	v_pk_fma_f32 v[144:145], v[128:129], v[174:175], v[136:137] op_sel_hi:[1,0,1] neg_lo:[0,0,1] neg_hi:[0,0,1]
	v_pk_fma_f32 v[146:147], v[130:131], v[174:175], v[138:139] op_sel_hi:[1,0,1] neg_lo:[0,0,1] neg_hi:[0,0,1]
	v_cvt_pk_bf16_f32 v148, v140, v141
	v_cvt_pk_bf16_f32 v149, v142, v143
	v_cvt_pk_bf16_f32 v150, v144, v145
	v_cvt_pk_bf16_f32 v151, v146, v147
	global_store_dwordx4 v168, v[148:151], s[54:55]
	v_add_u32_e32 v168, 0x800, v168
	v_lshlrev_b32_e32 v132, 16, v84
	v_and_b32_e32 v133, 0xffff0000, v84
	v_lshlrev_b32_e32 v134, 16, v85
	v_and_b32_e32 v135, 0xffff0000, v85
	v_lshlrev_b32_e32 v136, 16, v86
	v_and_b32_e32 v137, 0xffff0000, v86
	v_lshlrev_b32_e32 v138, 16, v87
	v_and_b32_e32 v139, 0xffff0000, v87
	v_lshlrev_b32_e32 v140, 16, v52
	v_and_b32_e32 v141, 0xffff0000, v52
	v_lshlrev_b32_e32 v142, 16, v53
	v_and_b32_e32 v143, 0xffff0000, v53
	v_lshlrev_b32_e32 v144, 16, v54
	v_and_b32_e32 v145, 0xffff0000, v54
	v_lshlrev_b32_e32 v146, 16, v55
	v_and_b32_e32 v147, 0xffff0000, v55
	v_pk_add_f32 v[124:125], v[124:125], v[132:133]
	v_pk_add_f32 v[126:127], v[126:127], v[134:135]
	v_pk_add_f32 v[128:129], v[128:129], v[136:137]
	v_pk_add_f32 v[130:131], v[130:131], v[138:139]
	v_pk_add_f32 v[124:125], v[124:125], v[140:141] neg_lo:[0,1] neg_hi:[0,1]
	v_pk_add_f32 v[126:127], v[126:127], v[142:143] neg_lo:[0,1] neg_hi:[0,1]
	v_pk_add_f32 v[128:129], v[128:129], v[144:145] neg_lo:[0,1] neg_hi:[0,1]
	v_pk_add_f32 v[130:131], v[130:131], v[146:147] neg_lo:[0,1] neg_hi:[0,1]
	v_add_u32_e32 v170, 18, v169
	v_min_u32_e32 v170, s56, v170
	v_add_u32_e32 v171, 10, v169
	v_max_i32_e32 v171, 0, v171
	v_sub_u32_e32 v170, v170, v171
	v_cvt_f32_u32_e32 v170, v170
	v_rcp_f32_e32 v174, v170
	v_lshlrev_b32_e32 v132, 16, v72
	v_and_b32_e32 v133, 0xffff0000, v72
	v_lshlrev_b32_e32 v134, 16, v73
	v_and_b32_e32 v135, 0xffff0000, v73
	v_lshlrev_b32_e32 v136, 16, v74
	v_and_b32_e32 v137, 0xffff0000, v74
	v_lshlrev_b32_e32 v138, 16, v75
	v_and_b32_e32 v139, 0xffff0000, v75
	v_pk_fma_f32 v[140:141], v[124:125], v[174:175], v[132:133] op_sel_hi:[1,0,1] neg_lo:[0,0,1] neg_hi:[0,0,1]
	v_pk_fma_f32 v[142:143], v[126:127], v[174:175], v[134:135] op_sel_hi:[1,0,1] neg_lo:[0,0,1] neg_hi:[0,0,1]
	v_pk_fma_f32 v[144:145], v[128:129], v[174:175], v[136:137] op_sel_hi:[1,0,1] neg_lo:[0,0,1] neg_hi:[0,0,1]
	v_pk_fma_f32 v[146:147], v[130:131], v[174:175], v[138:139] op_sel_hi:[1,0,1] neg_lo:[0,0,1] neg_hi:[0,0,1]
	v_cvt_pk_bf16_f32 v148, v140, v141
	v_cvt_pk_bf16_f32 v149, v142, v143
	v_cvt_pk_bf16_f32 v150, v144, v145
	v_cvt_pk_bf16_f32 v151, v146, v147
	global_store_dwordx4 v168, v[148:151], s[54:55]
	v_add_u32_e32 v168, 0x800, v168
	v_lshlrev_b32_e32 v132, 16, v88
	v_and_b32_e32 v133, 0xffff0000, v88
	v_lshlrev_b32_e32 v134, 16, v89
	v_and_b32_e32 v135, 0xffff0000, v89
	v_lshlrev_b32_e32 v136, 16, v90
	v_and_b32_e32 v137, 0xffff0000, v90
	v_lshlrev_b32_e32 v138, 16, v91
	v_and_b32_e32 v139, 0xffff0000, v91
	v_lshlrev_b32_e32 v140, 16, v56
	v_and_b32_e32 v141, 0xffff0000, v56
	v_lshlrev_b32_e32 v142, 16, v57
	v_and_b32_e32 v143, 0xffff0000, v57
	v_lshlrev_b32_e32 v144, 16, v58
	v_and_b32_e32 v145, 0xffff0000, v58
	v_lshlrev_b32_e32 v146, 16, v59
	v_and_b32_e32 v147, 0xffff0000, v59
	v_pk_add_f32 v[124:125], v[124:125], v[132:133]
	v_pk_add_f32 v[126:127], v[126:127], v[134:135]
	v_pk_add_f32 v[128:129], v[128:129], v[136:137]
	v_pk_add_f32 v[130:131], v[130:131], v[138:139]
	v_pk_add_f32 v[124:125], v[124:125], v[140:141] neg_lo:[0,1] neg_hi:[0,1]
	v_pk_add_f32 v[126:127], v[126:127], v[142:143] neg_lo:[0,1] neg_hi:[0,1]
	v_pk_add_f32 v[128:129], v[128:129], v[144:145] neg_lo:[0,1] neg_hi:[0,1]
	v_pk_add_f32 v[130:131], v[130:131], v[146:147] neg_lo:[0,1] neg_hi:[0,1]
	v_add_u32_e32 v170, 19, v169
	v_min_u32_e32 v170, s56, v170
	v_add_u32_e32 v171, 11, v169
	v_max_i32_e32 v171, 0, v171
	v_sub_u32_e32 v170, v170, v171
	v_cvt_f32_u32_e32 v170, v170
	v_rcp_f32_e32 v174, v170
	v_lshlrev_b32_e32 v132, 16, v76
	v_and_b32_e32 v133, 0xffff0000, v76
	v_lshlrev_b32_e32 v134, 16, v77
	v_and_b32_e32 v135, 0xffff0000, v77
	v_lshlrev_b32_e32 v136, 16, v78
	v_and_b32_e32 v137, 0xffff0000, v78
	v_lshlrev_b32_e32 v138, 16, v79
	v_and_b32_e32 v139, 0xffff0000, v79
	v_pk_fma_f32 v[140:141], v[124:125], v[174:175], v[132:133] op_sel_hi:[1,0,1] neg_lo:[0,0,1] neg_hi:[0,0,1]
	v_pk_fma_f32 v[142:143], v[126:127], v[174:175], v[134:135] op_sel_hi:[1,0,1] neg_lo:[0,0,1] neg_hi:[0,0,1]
	v_pk_fma_f32 v[144:145], v[128:129], v[174:175], v[136:137] op_sel_hi:[1,0,1] neg_lo:[0,0,1] neg_hi:[0,0,1]
	v_pk_fma_f32 v[146:147], v[130:131], v[174:175], v[138:139] op_sel_hi:[1,0,1] neg_lo:[0,0,1] neg_hi:[0,0,1]
	v_cvt_pk_bf16_f32 v148, v140, v141
	v_cvt_pk_bf16_f32 v149, v142, v143
	v_cvt_pk_bf16_f32 v150, v144, v145
	v_cvt_pk_bf16_f32 v151, v146, v147
	global_store_dwordx4 v168, v[148:151], s[54:55]
	s_branch .Lpool_next
; __global__ void __launch_bounds__(512, 2) fwd_mega(Args a) {
;     ...
;             const int c8 = item & 63, seg = (item >> 6) & 63, bb = item >> 12;
;             const int ch = c8 * 8, hw = 1 << (ch >> 7);
;             const bf16* base = UB + (size_t)bb * SEQ * 512 + ch;
;             bf16* obase = XB + (size_t)bb * SEQ * 1024 + 512 + ch;
;             const int s0 = seg * 32;
;             f32x4 w0 = {0.f, 0.f, 0.f, 0.f}, w1 = {0.f, 0.f, 0.f, 0.f};
;             { const int jlo = (s0 - hw) > 0 ? (s0 - hw) : 0, jhi = (s0 + hw) < SEQ ? (s0 + hw) : SEQ;
;               for (int j = jlo; j < jhi; ++j) { f32x4 a0, a1; pg8::unpack8(*(const u32x4*)(base + (size_t)j * 512), a0, a1); w0 += a0; w1 += a1; } }
.Lpool_g3:
	s_sub_i32 s52, s49, 8
	s_ashr_i32 s53, s52, 31
	s_lshl_b64 s[52:53], s[52:53], 10
	s_add_u32 s52, s52, s8
	s_addc_u32 s53, s53, s9
	s_add_u32 s52, s52, 768
	s_addc_u32 s53, s53, 0
	s_lshl_b32 s54, s49, 11
	s_add_u32 s54, s54, 0x3000700
	s_add_u32 s54, s30, s54
	s_addc_u32 s55, s31, 0
	global_load_dwordx4 v[0:3], v160, s[52:53] offset:0
	global_load_dwordx4 v[4:7], v160, s[52:53] offset:1024
	global_load_dwordx4 v[8:11], v160, s[52:53] offset:2048
	global_load_dwordx4 v[12:15], v160, s[52:53] offset:3072
	global_load_dwordx4 v[16:19], v161, s[52:53] offset:0
	global_load_dwordx4 v[20:23], v161, s[52:53] offset:1024
	global_load_dwordx4 v[24:27], v161, s[52:53] offset:2048
	global_load_dwordx4 v[28:31], v161, s[52:53] offset:3072
	global_load_dwordx4 v[32:35], v162, s[52:53] offset:0
	global_load_dwordx4 v[36:39], v162, s[52:53] offset:1024
	global_load_dwordx4 v[40:43], v162, s[52:53] offset:2048
	global_load_dwordx4 v[44:47], v162, s[52:53] offset:3072
	global_load_dwordx4 v[48:51], v163, s[52:53] offset:0
	global_load_dwordx4 v[52:55], v163, s[52:53] offset:1024
	global_load_dwordx4 v[56:59], v163, s[52:53] offset:2048
	global_load_dwordx4 v[60:63], v163, s[52:53] offset:3072
	global_load_dwordx4 v[64:67], v164, s[52:53] offset:0
	global_load_dwordx4 v[68:71], v164, s[52:53] offset:1024
	global_load_dwordx4 v[72:75], v164, s[52:53] offset:2048
	global_load_dwordx4 v[76:79], v164, s[52:53] offset:3072
	global_load_dwordx4 v[80:83], v165, s[52:53] offset:0
	global_load_dwordx4 v[84:87], v165, s[52:53] offset:1024
	global_load_dwordx4 v[88:91], v165, s[52:53] offset:2048
	global_load_dwordx4 v[92:95], v165, s[52:53] offset:3072
	global_load_dwordx4 v[96:99], v166, s[52:53] offset:0
	global_load_dwordx4 v[100:103], v166, s[52:53] offset:1024
	global_load_dwordx4 v[104:107], v166, s[52:53] offset:2048
	global_load_dwordx4 v[108:111], v166, s[52:53] offset:3072
	global_load_dwordx4 v[112:115], v167, s[52:53] offset:0
	global_load_dwordx4 v[116:119], v167, s[52:53] offset:1024
	global_load_dwordx4 v[120:123], v167, s[52:53] offset:2048
	s_waitcnt vmcnt(0)
	s_cmp_eq_u32 s50, 0
	s_cbranch_scc1 .Lpool_g3_mask
	s_cmpk_eq_i32 s50, 0x7c0
	s_cbranch_scc0 .Lpool_g3_nomask
.Lpool_g3_mask:
	v_add_u32_e32 v170, -8, v169
	v_cmp_gt_u32_e32 vcc, s56, v170
	s_nop 1
	v_cndmask_b32_e32 v0, 0, v0, vcc
	v_cndmask_b32_e32 v1, 0, v1, vcc
	v_cndmask_b32_e32 v2, 0, v2, vcc
	v_cndmask_b32_e32 v3, 0, v3, vcc
	v_add_u32_e32 v170, -7, v169
	v_cmp_gt_u32_e32 vcc, s56, v170
	s_nop 1
	v_cndmask_b32_e32 v4, 0, v4, vcc
	v_cndmask_b32_e32 v5, 0, v5, vcc
	v_cndmask_b32_e32 v6, 0, v6, vcc
	v_cndmask_b32_e32 v7, 0, v7, vcc
	v_add_u32_e32 v170, -6, v169
	v_cmp_gt_u32_e32 vcc, s56, v170
	s_nop 1
	v_cndmask_b32_e32 v8, 0, v8, vcc
	v_cndmask_b32_e32 v9, 0, v9, vcc
	v_cndmask_b32_e32 v10, 0, v10, vcc
	v_cndmask_b32_e32 v11, 0, v11, vcc
	v_add_u32_e32 v170, -5, v169
	v_cmp_gt_u32_e32 vcc, s56, v170
	s_nop 1
	v_cndmask_b32_e32 v12, 0, v12, vcc
	v_cndmask_b32_e32 v13, 0, v13, vcc
	v_cndmask_b32_e32 v14, 0, v14, vcc
	v_cndmask_b32_e32 v15, 0, v15, vcc
	v_add_u32_e32 v170, -4, v169
	v_cmp_gt_u32_e32 vcc, s56, v170
	s_nop 1
	v_cndmask_b32_e32 v16, 0, v16, vcc
	v_cndmask_b32_e32 v17, 0, v17, vcc
	v_cndmask_b32_e32 v18, 0, v18, vcc
	v_cndmask_b32_e32 v19, 0, v19, vcc
	v_add_u32_e32 v170, -3, v169
	v_cmp_gt_u32_e32 vcc, s56, v170
	s_nop 1
	v_cndmask_b32_e32 v20, 0, v20, vcc
	v_cndmask_b32_e32 v21, 0, v21, vcc
	v_cndmask_b32_e32 v22, 0, v22, vcc
	v_cndmask_b32_e32 v23, 0, v23, vcc
	v_add_u32_e32 v170, -2, v169
	v_cmp_gt_u32_e32 vcc, s56, v170
	s_nop 1
	v_cndmask_b32_e32 v24, 0, v24, vcc
	v_cndmask_b32_e32 v25, 0, v25, vcc
	v_cndmask_b32_e32 v26, 0, v26, vcc
	v_cndmask_b32_e32 v27, 0, v27, vcc
	v_add_u32_e32 v170, -1, v169
	v_cmp_gt_u32_e32 vcc, s56, v170
	s_nop 1
	v_cndmask_b32_e32 v28, 0, v28, vcc
	v_cndmask_b32_e32 v29, 0, v29, vcc
	v_cndmask_b32_e32 v30, 0, v30, vcc
	v_cndmask_b32_e32 v31, 0, v31, vcc
	v_add_u32_e32 v170, 0, v169
	v_cmp_gt_u32_e32 vcc, s56, v170
	s_nop 1
	v_cndmask_b32_e32 v32, 0, v32, vcc
	v_cndmask_b32_e32 v33, 0, v33, vcc
	v_cndmask_b32_e32 v34, 0, v34, vcc
	v_cndmask_b32_e32 v35, 0, v35, vcc
	v_add_u32_e32 v170, 1, v169
	v_cmp_gt_u32_e32 vcc, s56, v170
	s_nop 1
	v_cndmask_b32_e32 v36, 0, v36, vcc
	v_cndmask_b32_e32 v37, 0, v37, vcc
	v_cndmask_b32_e32 v38, 0, v38, vcc
	v_cndmask_b32_e32 v39, 0, v39, vcc
	v_add_u32_e32 v170, 2, v169
	v_cmp_gt_u32_e32 vcc, s56, v170
	s_nop 1
	v_cndmask_b32_e32 v40, 0, v40, vcc
	v_cndmask_b32_e32 v41, 0, v41, vcc
	v_cndmask_b32_e32 v42, 0, v42, vcc
	v_cndmask_b32_e32 v43, 0, v43, vcc
	v_add_u32_e32 v170, 3, v169
	v_cmp_gt_u32_e32 vcc, s56, v170
	s_nop 1
	v_cndmask_b32_e32 v44, 0, v44, vcc
	v_cndmask_b32_e32 v45, 0, v45, vcc
	v_cndmask_b32_e32 v46, 0, v46, vcc
	v_cndmask_b32_e32 v47, 0, v47, vcc
	v_add_u32_e32 v170, 4, v169
	v_cmp_gt_u32_e32 vcc, s56, v170
	s_nop 1
	v_cndmask_b32_e32 v48, 0, v48, vcc
	v_cndmask_b32_e32 v49, 0, v49, vcc
	v_cndmask_b32_e32 v50, 0, v50, vcc
	v_cndmask_b32_e32 v51, 0, v51, vcc
	v_add_u32_e32 v170, 5, v169
	v_cmp_gt_u32_e32 vcc, s56, v170
	s_nop 1
	v_cndmask_b32_e32 v52, 0, v52, vcc
	v_cndmask_b32_e32 v53, 0, v53, vcc
	v_cndmask_b32_e32 v54, 0, v54, vcc
	v_cndmask_b32_e32 v55, 0, v55, vcc
	v_add_u32_e32 v170, 6, v169
	v_cmp_gt_u32_e32 vcc, s56, v170
	s_nop 1
	v_cndmask_b32_e32 v56, 0, v56, vcc
	v_cndmask_b32_e32 v57, 0, v57, vcc
	v_cndmask_b32_e32 v58, 0, v58, vcc
	v_cndmask_b32_e32 v59, 0, v59, vcc
	v_add_u32_e32 v170, 7, v169
	v_cmp_gt_u32_e32 vcc, s56, v170
	s_nop 1
	v_cndmask_b32_e32 v60, 0, v60, vcc
	v_cndmask_b32_e32 v61, 0, v61, vcc
	v_cndmask_b32_e32 v62, 0, v62, vcc
	v_cndmask_b32_e32 v63, 0, v63, vcc
; __global__ void __launch_bounds__(512, 2) fwd_mega(Args a) {
;     ...
;             { const int jlo = (s0 - hw) > 0 ? (s0 - hw) : 0, jhi = (s0 + hw) < SEQ ? (s0 + hw) : SEQ;
;               for (int j = jlo; j < jhi; ++j) { f32x4 a0, a1; pg8::unpack8(*(const u32x4*)(base + (size_t)j * 512), a0, a1); w0 += a0; w1 += a1; } }
	v_add_u32_e32 v170, 8, v169
	v_cmp_gt_u32_e32 vcc, s56, v170
	s_nop 1
	v_cndmask_b32_e32 v64, 0, v64, vcc
	v_cndmask_b32_e32 v65, 0, v65, vcc
	v_cndmask_b32_e32 v66, 0, v66, vcc
	v_cndmask_b32_e32 v67, 0, v67, vcc
	v_add_u32_e32 v170, 9, v169
	v_cmp_gt_u32_e32 vcc, s56, v170
	s_nop 1
	v_cndmask_b32_e32 v68, 0, v68, vcc
	v_cndmask_b32_e32 v69, 0, v69, vcc
	v_cndmask_b32_e32 v70, 0, v70, vcc
	v_cndmask_b32_e32 v71, 0, v71, vcc
	v_add_u32_e32 v170, 10, v169
	v_cmp_gt_u32_e32 vcc, s56, v170
	s_nop 1
	v_cndmask_b32_e32 v72, 0, v72, vcc
	v_cndmask_b32_e32 v73, 0, v73, vcc
	v_cndmask_b32_e32 v74, 0, v74, vcc
	v_cndmask_b32_e32 v75, 0, v75, vcc
	v_add_u32_e32 v170, 11, v169
	v_cmp_gt_u32_e32 vcc, s56, v170
	s_nop 1
	v_cndmask_b32_e32 v76, 0, v76, vcc
	v_cndmask_b32_e32 v77, 0, v77, vcc
	v_cndmask_b32_e32 v78, 0, v78, vcc
	v_cndmask_b32_e32 v79, 0, v79, vcc
	v_add_u32_e32 v170, 12, v169
	v_cmp_gt_u32_e32 vcc, s56, v170
	s_nop 1
	v_cndmask_b32_e32 v80, 0, v80, vcc
	v_cndmask_b32_e32 v81, 0, v81, vcc
	v_cndmask_b32_e32 v82, 0, v82, vcc
	v_cndmask_b32_e32 v83, 0, v83, vcc
	v_add_u32_e32 v170, 13, v169
	v_cmp_gt_u32_e32 vcc, s56, v170
	s_nop 1
	v_cndmask_b32_e32 v84, 0, v84, vcc
	v_cndmask_b32_e32 v85, 0, v85, vcc
	v_cndmask_b32_e32 v86, 0, v86, vcc
	v_cndmask_b32_e32 v87, 0, v87, vcc
	v_add_u32_e32 v170, 14, v169
	v_cmp_gt_u32_e32 vcc, s56, v170
	s_nop 1
	v_cndmask_b32_e32 v88, 0, v88, vcc
	v_cndmask_b32_e32 v89, 0, v89, vcc
	v_cndmask_b32_e32 v90, 0, v90, vcc
	v_cndmask_b32_e32 v91, 0, v91, vcc
	v_add_u32_e32 v170, 15, v169
	v_cmp_gt_u32_e32 vcc, s56, v170
	s_nop 1
	v_cndmask_b32_e32 v92, 0, v92, vcc
	v_cndmask_b32_e32 v93, 0, v93, vcc
	v_cndmask_b32_e32 v94, 0, v94, vcc
	v_cndmask_b32_e32 v95, 0, v95, vcc
	v_add_u32_e32 v170, 16, v169
	v_cmp_gt_u32_e32 vcc, s56, v170
	s_nop 1
	v_cndmask_b32_e32 v96, 0, v96, vcc
	v_cndmask_b32_e32 v97, 0, v97, vcc
	v_cndmask_b32_e32 v98, 0, v98, vcc
	v_cndmask_b32_e32 v99, 0, v99, vcc
	v_add_u32_e32 v170, 17, v169
	v_cmp_gt_u32_e32 vcc, s56, v170
	s_nop 1
	v_cndmask_b32_e32 v100, 0, v100, vcc
	v_cndmask_b32_e32 v101, 0, v101, vcc
	v_cndmask_b32_e32 v102, 0, v102, vcc
	v_cndmask_b32_e32 v103, 0, v103, vcc
	v_add_u32_e32 v170, 18, v169
	v_cmp_gt_u32_e32 vcc, s56, v170
	s_nop 1
	v_cndmask_b32_e32 v104, 0, v104, vcc
	v_cndmask_b32_e32 v105, 0, v105, vcc
	v_cndmask_b32_e32 v106, 0, v106, vcc
	v_cndmask_b32_e32 v107, 0, v107, vcc
	v_add_u32_e32 v170, 19, v169
	v_cmp_gt_u32_e32 vcc, s56, v170
	s_nop 1
	v_cndmask_b32_e32 v108, 0, v108, vcc
	v_cndmask_b32_e32 v109, 0, v109, vcc
	v_cndmask_b32_e32 v110, 0, v110, vcc
	v_cndmask_b32_e32 v111, 0, v111, vcc
	v_add_u32_e32 v170, 20, v169
	v_cmp_gt_u32_e32 vcc, s56, v170
	s_nop 1
	v_cndmask_b32_e32 v112, 0, v112, vcc
	v_cndmask_b32_e32 v113, 0, v113, vcc
	v_cndmask_b32_e32 v114, 0, v114, vcc
	v_cndmask_b32_e32 v115, 0, v115, vcc
	v_add_u32_e32 v170, 21, v169
	v_cmp_gt_u32_e32 vcc, s56, v170
	s_nop 1
	v_cndmask_b32_e32 v116, 0, v116, vcc
	v_cndmask_b32_e32 v117, 0, v117, vcc
	v_cndmask_b32_e32 v118, 0, v118, vcc
	v_cndmask_b32_e32 v119, 0, v119, vcc
	v_add_u32_e32 v170, 22, v169
	v_cmp_gt_u32_e32 vcc, s56, v170
	s_nop 1
	v_cndmask_b32_e32 v120, 0, v120, vcc
	v_cndmask_b32_e32 v121, 0, v121, vcc
	v_cndmask_b32_e32 v122, 0, v122, vcc
	v_cndmask_b32_e32 v123, 0, v123, vcc
.Lpool_g3_nomask:
	v_lshlrev_b32_e32 v124, 16, v0
	v_and_b32_e32 v125, 0xffff0000, v0
	v_lshlrev_b32_e32 v126, 16, v1
	v_and_b32_e32 v127, 0xffff0000, v1
	v_lshlrev_b32_e32 v128, 16, v2
	v_and_b32_e32 v129, 0xffff0000, v2
	v_lshlrev_b32_e32 v130, 16, v3
	v_and_b32_e32 v131, 0xffff0000, v3
	v_lshlrev_b32_e32 v132, 16, v4
	v_and_b32_e32 v133, 0xffff0000, v4
	v_lshlrev_b32_e32 v134, 16, v5
	v_and_b32_e32 v135, 0xffff0000, v5
	v_lshlrev_b32_e32 v136, 16, v6
	v_and_b32_e32 v137, 0xffff0000, v6
	v_lshlrev_b32_e32 v138, 16, v7
	v_and_b32_e32 v139, 0xffff0000, v7
	v_pk_add_f32 v[124:125], v[124:125], v[132:133]
	v_pk_add_f32 v[126:127], v[126:127], v[134:135]
	v_pk_add_f32 v[128:129], v[128:129], v[136:137]
	v_pk_add_f32 v[130:131], v[130:131], v[138:139]
	v_lshlrev_b32_e32 v132, 16, v8
	v_and_b32_e32 v133, 0xffff0000, v8
	v_lshlrev_b32_e32 v134, 16, v9
	v_and_b32_e32 v135, 0xffff0000, v9
	v_lshlrev_b32_e32 v136, 16, v10
	v_and_b32_e32 v137, 0xffff0000, v10
	v_lshlrev_b32_e32 v138, 16, v11
	v_and_b32_e32 v139, 0xffff0000, v11
	v_pk_add_f32 v[124:125], v[124:125], v[132:133]
	v_pk_add_f32 v[126:127], v[126:127], v[134:135]
	v_pk_add_f32 v[128:129], v[128:129], v[136:137]
	v_pk_add_f32 v[130:131], v[130:131], v[138:139]
	v_lshlrev_b32_e32 v132, 16, v12
	v_and_b32_e32 v133, 0xffff0000, v12
	v_lshlrev_b32_e32 v134, 16, v13
	v_and_b32_e32 v135, 0xffff0000, v13
	v_lshlrev_b32_e32 v136, 16, v14
	v_and_b32_e32 v137, 0xffff0000, v14
	v_lshlrev_b32_e32 v138, 16, v15
	v_and_b32_e32 v139, 0xffff0000, v15
	v_pk_add_f32 v[124:125], v[124:125], v[132:133]
	v_pk_add_f32 v[126:127], v[126:127], v[134:135]
	v_pk_add_f32 v[128:129], v[128:129], v[136:137]
	v_pk_add_f32 v[130:131], v[130:131], v[138:139]
	v_lshlrev_b32_e32 v132, 16, v16
	v_and_b32_e32 v133, 0xffff0000, v16
	v_lshlrev_b32_e32 v134, 16, v17
	v_and_b32_e32 v135, 0xffff0000, v17
	v_lshlrev_b32_e32 v136, 16, v18
	v_and_b32_e32 v137, 0xffff0000, v18
	v_lshlrev_b32_e32 v138, 16, v19
	v_and_b32_e32 v139, 0xffff0000, v19
	v_pk_add_f32 v[124:125], v[124:125], v[132:133]
	v_pk_add_f32 v[126:127], v[126:127], v[134:135]
	v_pk_add_f32 v[128:129], v[128:129], v[136:137]
	v_pk_add_f32 v[130:131], v[130:131], v[138:139]
	v_lshlrev_b32_e32 v132, 16, v20
	v_and_b32_e32 v133, 0xffff0000, v20
	v_lshlrev_b32_e32 v134, 16, v21
	v_and_b32_e32 v135, 0xffff0000, v21
	v_lshlrev_b32_e32 v136, 16, v22
; __device__ __forceinline__ u32x4 pack8(const f32x4 a, const f32x4 b) { u32x4 w; w.x = cvt_pk_bf16(a[0], a[1]); w.y = cvt_pk_bf16(a[2], a[3]); w.z = cvt_pk_bf16(b[0], b[1]); w.w = cvt_pk_bf16(b[2], b[3]); return w; }
; __global__ void __launch_bounds__(512, 2) fwd_mega(Args a) {
;     ...
;             { const int jlo = (s0 - hw) > 0 ? (s0 - hw) : 0, jhi = (s0 + hw) < SEQ ? (s0 + hw) : SEQ;
;               for (int j = jlo; j < jhi; ++j) { f32x4 a0, a1; pg8::unpack8(*(const u32x4*)(base + (size_t)j * 512), a0, a1); w0 += a0; w1 += a1; } }
; #pragma unroll 4
;             for (int s = s0; s < s0 + 32; ++s) {
;                 f32x4 u0, u1; pg8::unpack8(*(const u32x4*)(base + (size_t)s * 512), u0, u1);
;                 const int jlo = (s - hw) > 0 ? (s - hw) : 0, jhi = (s + hw) < SEQ ? (s + hw) : SEQ;
;                 const float rc = 1.0f / (float)(jhi - jlo);
;                 *(u32x4*)(obase + (size_t)s * 1024) = pg8::pack8(w0 * rc - u0, w1 * rc - u1);
;                 if (s + hw < SEQ) { f32x4 a0, a1; pg8::unpack8(*(const u32x4*)(base + (size_t)(s + hw) * 512), a0, a1); w0 += a0; w1 += a1; }
;                 if (s - hw >= 0) { f32x4 a0, a1; pg8::unpack8(*(const u32x4*)(base + (size_t)(s - hw) * 512), a0, a1); w0 -= a0; w1 -= a1; }
	v_and_b32_e32 v137, 0xffff0000, v22
	v_lshlrev_b32_e32 v138, 16, v23
	v_and_b32_e32 v139, 0xffff0000, v23
	v_pk_add_f32 v[124:125], v[124:125], v[132:133]
	v_pk_add_f32 v[126:127], v[126:127], v[134:135]
	v_pk_add_f32 v[128:129], v[128:129], v[136:137]
	v_pk_add_f32 v[130:131], v[130:131], v[138:139]
	v_lshlrev_b32_e32 v132, 16, v24
	v_and_b32_e32 v133, 0xffff0000, v24
	v_lshlrev_b32_e32 v134, 16, v25
	v_and_b32_e32 v135, 0xffff0000, v25
	v_lshlrev_b32_e32 v136, 16, v26
	v_and_b32_e32 v137, 0xffff0000, v26
	v_lshlrev_b32_e32 v138, 16, v27
	v_and_b32_e32 v139, 0xffff0000, v27
	v_pk_add_f32 v[124:125], v[124:125], v[132:133]
	v_pk_add_f32 v[126:127], v[126:127], v[134:135]
	v_pk_add_f32 v[128:129], v[128:129], v[136:137]
	v_pk_add_f32 v[130:131], v[130:131], v[138:139]
	v_lshlrev_b32_e32 v132, 16, v28
	v_and_b32_e32 v133, 0xffff0000, v28
	v_lshlrev_b32_e32 v134, 16, v29
	v_and_b32_e32 v135, 0xffff0000, v29
	v_lshlrev_b32_e32 v136, 16, v30
	v_and_b32_e32 v137, 0xffff0000, v30
	v_lshlrev_b32_e32 v138, 16, v31
	v_and_b32_e32 v139, 0xffff0000, v31
	v_pk_add_f32 v[124:125], v[124:125], v[132:133]
	v_pk_add_f32 v[126:127], v[126:127], v[134:135]
	v_pk_add_f32 v[128:129], v[128:129], v[136:137]
	v_pk_add_f32 v[130:131], v[130:131], v[138:139]
	v_lshlrev_b32_e32 v132, 16, v32
	v_and_b32_e32 v133, 0xffff0000, v32
	v_lshlrev_b32_e32 v134, 16, v33
	v_and_b32_e32 v135, 0xffff0000, v33
	v_lshlrev_b32_e32 v136, 16, v34
	v_and_b32_e32 v137, 0xffff0000, v34
	v_lshlrev_b32_e32 v138, 16, v35
	v_and_b32_e32 v139, 0xffff0000, v35
	v_pk_add_f32 v[124:125], v[124:125], v[132:133]
	v_pk_add_f32 v[126:127], v[126:127], v[134:135]
	v_pk_add_f32 v[128:129], v[128:129], v[136:137]
	v_pk_add_f32 v[130:131], v[130:131], v[138:139]
	v_lshlrev_b32_e32 v132, 16, v36
	v_and_b32_e32 v133, 0xffff0000, v36
	v_lshlrev_b32_e32 v134, 16, v37
	v_and_b32_e32 v135, 0xffff0000, v37
	v_lshlrev_b32_e32 v136, 16, v38
	v_and_b32_e32 v137, 0xffff0000, v38
	v_lshlrev_b32_e32 v138, 16, v39
	v_and_b32_e32 v139, 0xffff0000, v39
	v_pk_add_f32 v[124:125], v[124:125], v[132:133]
	v_pk_add_f32 v[126:127], v[126:127], v[134:135]
	v_pk_add_f32 v[128:129], v[128:129], v[136:137]
	v_pk_add_f32 v[130:131], v[130:131], v[138:139]
	v_lshlrev_b32_e32 v132, 16, v40
	v_and_b32_e32 v133, 0xffff0000, v40
	v_lshlrev_b32_e32 v134, 16, v41
	v_and_b32_e32 v135, 0xffff0000, v41
	v_lshlrev_b32_e32 v136, 16, v42
	v_and_b32_e32 v137, 0xffff0000, v42
	v_lshlrev_b32_e32 v138, 16, v43
	v_and_b32_e32 v139, 0xffff0000, v43
	v_pk_add_f32 v[124:125], v[124:125], v[132:133]
	v_pk_add_f32 v[126:127], v[126:127], v[134:135]
	v_pk_add_f32 v[128:129], v[128:129], v[136:137]
	v_pk_add_f32 v[130:131], v[130:131], v[138:139]
	v_lshlrev_b32_e32 v132, 16, v44
	v_and_b32_e32 v133, 0xffff0000, v44
	v_lshlrev_b32_e32 v134, 16, v45
	v_and_b32_e32 v135, 0xffff0000, v45
	v_lshlrev_b32_e32 v136, 16, v46
	v_and_b32_e32 v137, 0xffff0000, v46
	v_lshlrev_b32_e32 v138, 16, v47
	v_and_b32_e32 v139, 0xffff0000, v47
	v_pk_add_f32 v[124:125], v[124:125], v[132:133]
	v_pk_add_f32 v[126:127], v[126:127], v[134:135]
	v_pk_add_f32 v[128:129], v[128:129], v[136:137]
	v_pk_add_f32 v[130:131], v[130:131], v[138:139]
	v_lshlrev_b32_e32 v132, 16, v48
	v_and_b32_e32 v133, 0xffff0000, v48
	v_lshlrev_b32_e32 v134, 16, v49
	v_and_b32_e32 v135, 0xffff0000, v49
	v_lshlrev_b32_e32 v136, 16, v50
	v_and_b32_e32 v137, 0xffff0000, v50
	v_lshlrev_b32_e32 v138, 16, v51
	v_and_b32_e32 v139, 0xffff0000, v51
	v_pk_add_f32 v[124:125], v[124:125], v[132:133]
	v_pk_add_f32 v[126:127], v[126:127], v[134:135]
	v_pk_add_f32 v[128:129], v[128:129], v[136:137]
	v_pk_add_f32 v[130:131], v[130:131], v[138:139]
	v_lshlrev_b32_e32 v132, 16, v52
	v_and_b32_e32 v133, 0xffff0000, v52
	v_lshlrev_b32_e32 v134, 16, v53
	v_and_b32_e32 v135, 0xffff0000, v53
	v_lshlrev_b32_e32 v136, 16, v54
	v_and_b32_e32 v137, 0xffff0000, v54
	v_lshlrev_b32_e32 v138, 16, v55
	v_and_b32_e32 v139, 0xffff0000, v55
	v_pk_add_f32 v[124:125], v[124:125], v[132:133]
	v_pk_add_f32 v[126:127], v[126:127], v[134:135]
	v_pk_add_f32 v[128:129], v[128:129], v[136:137]
	v_pk_add_f32 v[130:131], v[130:131], v[138:139]
	v_lshlrev_b32_e32 v132, 16, v56
	v_and_b32_e32 v133, 0xffff0000, v56
	v_lshlrev_b32_e32 v134, 16, v57
	v_and_b32_e32 v135, 0xffff0000, v57
	v_lshlrev_b32_e32 v136, 16, v58
	v_and_b32_e32 v137, 0xffff0000, v58
	v_lshlrev_b32_e32 v138, 16, v59
	v_and_b32_e32 v139, 0xffff0000, v59
	v_pk_add_f32 v[124:125], v[124:125], v[132:133]
	v_pk_add_f32 v[126:127], v[126:127], v[134:135]
	v_pk_add_f32 v[128:129], v[128:129], v[136:137]
	v_pk_add_f32 v[130:131], v[130:131], v[138:139]
	v_lshlrev_b32_e32 v132, 16, v60
	v_and_b32_e32 v133, 0xffff0000, v60
	v_lshlrev_b32_e32 v134, 16, v61
	v_and_b32_e32 v135, 0xffff0000, v61
	v_lshlrev_b32_e32 v136, 16, v62
	v_and_b32_e32 v137, 0xffff0000, v62
	v_lshlrev_b32_e32 v138, 16, v63
	v_and_b32_e32 v139, 0xffff0000, v63
	v_pk_add_f32 v[124:125], v[124:125], v[132:133]
	v_pk_add_f32 v[126:127], v[126:127], v[134:135]
	v_pk_add_f32 v[128:129], v[128:129], v[136:137]
	v_pk_add_f32 v[130:131], v[130:131], v[138:139]
	v_add_u32_e32 v170, 8, v169
	v_min_u32_e32 v170, s56, v170
	v_add_u32_e32 v171, -8, v169
	v_max_i32_e32 v171, 0, v171
	v_sub_u32_e32 v170, v170, v171
	v_cvt_f32_u32_e32 v170, v170
	v_rcp_f32_e32 v174, v170
	v_lshlrev_b32_e32 v132, 16, v32
	v_and_b32_e32 v133, 0xffff0000, v32
	v_lshlrev_b32_e32 v134, 16, v33
	v_and_b32_e32 v135, 0xffff0000, v33
	v_lshlrev_b32_e32 v136, 16, v34
	v_and_b32_e32 v137, 0xffff0000, v34
	v_lshlrev_b32_e32 v138, 16, v35
	v_and_b32_e32 v139, 0xffff0000, v35
	v_pk_fma_f32 v[140:141], v[124:125], v[174:175], v[132:133] op_sel_hi:[1,0,1] neg_lo:[0,0,1] neg_hi:[0,0,1]
; __device__ __forceinline__ u32x4 pack8(const f32x4 a, const f32x4 b) { u32x4 w; w.x = cvt_pk_bf16(a[0], a[1]); w.y = cvt_pk_bf16(a[2], a[3]); w.z = cvt_pk_bf16(b[0], b[1]); w.w = cvt_pk_bf16(b[2], b[3]); return w; }
; __global__ void __launch_bounds__(512, 2) fwd_mega(Args a) {
;     ...
;             for (int s = s0; s < s0 + 32; ++s) {
;                 f32x4 u0, u1; pg8::unpack8(*(const u32x4*)(base + (size_t)s * 512), u0, u1);
;                 const int jlo = (s - hw) > 0 ? (s - hw) : 0, jhi = (s + hw) < SEQ ? (s + hw) : SEQ;
;                 const float rc = 1.0f / (float)(jhi - jlo);
;                 *(u32x4*)(obase + (size_t)s * 1024) = pg8::pack8(w0 * rc - u0, w1 * rc - u1);
;                 if (s + hw < SEQ) { f32x4 a0, a1; pg8::unpack8(*(const u32x4*)(base + (size_t)(s + hw) * 512), a0, a1); w0 += a0; w1 += a1; }
;                 if (s - hw >= 0) { f32x4 a0, a1; pg8::unpack8(*(const u32x4*)(base + (size_t)(s - hw) * 512), a0, a1); w0 -= a0; w1 -= a1; }
	v_pk_fma_f32 v[142:143], v[126:127], v[174:175], v[134:135] op_sel_hi:[1,0,1] neg_lo:[0,0,1] neg_hi:[0,0,1]
	v_pk_fma_f32 v[144:145], v[128:129], v[174:175], v[136:137] op_sel_hi:[1,0,1] neg_lo:[0,0,1] neg_hi:[0,0,1]
	v_pk_fma_f32 v[146:147], v[130:131], v[174:175], v[138:139] op_sel_hi:[1,0,1] neg_lo:[0,0,1] neg_hi:[0,0,1]
	v_cvt_pk_bf16_f32 v148, v140, v141
	v_cvt_pk_bf16_f32 v149, v142, v143
	v_cvt_pk_bf16_f32 v150, v144, v145
	v_cvt_pk_bf16_f32 v151, v146, v147
	global_store_dwordx4 v168, v[148:151], s[54:55]
	v_add_u32_e32 v168, 0x800, v168
	v_lshlrev_b32_e32 v132, 16, v64
	v_and_b32_e32 v133, 0xffff0000, v64
	v_lshlrev_b32_e32 v134, 16, v65
	v_and_b32_e32 v135, 0xffff0000, v65
	v_lshlrev_b32_e32 v136, 16, v66
	v_and_b32_e32 v137, 0xffff0000, v66
	v_lshlrev_b32_e32 v138, 16, v67
	v_and_b32_e32 v139, 0xffff0000, v67
	v_lshlrev_b32_e32 v140, 16, v0
	v_and_b32_e32 v141, 0xffff0000, v0
	v_lshlrev_b32_e32 v142, 16, v1
	v_and_b32_e32 v143, 0xffff0000, v1
	v_lshlrev_b32_e32 v144, 16, v2
	v_and_b32_e32 v145, 0xffff0000, v2
	v_lshlrev_b32_e32 v146, 16, v3
	v_and_b32_e32 v147, 0xffff0000, v3
	v_pk_add_f32 v[124:125], v[124:125], v[132:133]
	v_pk_add_f32 v[126:127], v[126:127], v[134:135]
	v_pk_add_f32 v[128:129], v[128:129], v[136:137]
	v_pk_add_f32 v[130:131], v[130:131], v[138:139]
	v_pk_add_f32 v[124:125], v[124:125], v[140:141] neg_lo:[0,1] neg_hi:[0,1]
	v_pk_add_f32 v[126:127], v[126:127], v[142:143] neg_lo:[0,1] neg_hi:[0,1]
	v_pk_add_f32 v[128:129], v[128:129], v[144:145] neg_lo:[0,1] neg_hi:[0,1]
	v_pk_add_f32 v[130:131], v[130:131], v[146:147] neg_lo:[0,1] neg_hi:[0,1]
	v_add_u32_e32 v170, 9, v169
	v_min_u32_e32 v170, s56, v170
	v_add_u32_e32 v171, -7, v169
	v_max_i32_e32 v171, 0, v171
	v_sub_u32_e32 v170, v170, v171
	v_cvt_f32_u32_e32 v170, v170
	v_rcp_f32_e32 v174, v170
	v_lshlrev_b32_e32 v132, 16, v36
	v_and_b32_e32 v133, 0xffff0000, v36
	v_lshlrev_b32_e32 v134, 16, v37
	v_and_b32_e32 v135, 0xffff0000, v37
	v_lshlrev_b32_e32 v136, 16, v38
	v_and_b32_e32 v137, 0xffff0000, v38
	v_lshlrev_b32_e32 v138, 16, v39
	v_and_b32_e32 v139, 0xffff0000, v39
	v_pk_fma_f32 v[140:141], v[124:125], v[174:175], v[132:133] op_sel_hi:[1,0,1] neg_lo:[0,0,1] neg_hi:[0,0,1]
	v_pk_fma_f32 v[142:143], v[126:127], v[174:175], v[134:135] op_sel_hi:[1,0,1] neg_lo:[0,0,1] neg_hi:[0,0,1]
	v_pk_fma_f32 v[144:145], v[128:129], v[174:175], v[136:137] op_sel_hi:[1,0,1] neg_lo:[0,0,1] neg_hi:[0,0,1]
	v_pk_fma_f32 v[146:147], v[130:131], v[174:175], v[138:139] op_sel_hi:[1,0,1] neg_lo:[0,0,1] neg_hi:[0,0,1]
	v_cvt_pk_bf16_f32 v148, v140, v141
	v_cvt_pk_bf16_f32 v149, v142, v143
	v_cvt_pk_bf16_f32 v150, v144, v145
	v_cvt_pk_bf16_f32 v151, v146, v147
	global_store_dwordx4 v168, v[148:151], s[54:55]
	v_add_u32_e32 v168, 0x800, v168
	v_lshlrev_b32_e32 v132, 16, v68
	v_and_b32_e32 v133, 0xffff0000, v68
	v_lshlrev_b32_e32 v134, 16, v69
	v_and_b32_e32 v135, 0xffff0000, v69
	v_lshlrev_b32_e32 v136, 16, v70
	v_and_b32_e32 v137, 0xffff0000, v70
	v_lshlrev_b32_e32 v138, 16, v71
	v_and_b32_e32 v139, 0xffff0000, v71
	v_lshlrev_b32_e32 v140, 16, v4
	v_and_b32_e32 v141, 0xffff0000, v4
	v_lshlrev_b32_e32 v142, 16, v5
	v_and_b32_e32 v143, 0xffff0000, v5
	v_lshlrev_b32_e32 v144, 16, v6
	v_and_b32_e32 v145, 0xffff0000, v6
	v_lshlrev_b32_e32 v146, 16, v7
	v_and_b32_e32 v147, 0xffff0000, v7
	v_pk_add_f32 v[124:125], v[124:125], v[132:133]
	v_pk_add_f32 v[126:127], v[126:127], v[134:135]
	v_pk_add_f32 v[128:129], v[128:129], v[136:137]
	v_pk_add_f32 v[130:131], v[130:131], v[138:139]
	v_pk_add_f32 v[124:125], v[124:125], v[140:141] neg_lo:[0,1] neg_hi:[0,1]
	v_pk_add_f32 v[126:127], v[126:127], v[142:143] neg_lo:[0,1] neg_hi:[0,1]
	v_pk_add_f32 v[128:129], v[128:129], v[144:145] neg_lo:[0,1] neg_hi:[0,1]
	v_pk_add_f32 v[130:131], v[130:131], v[146:147] neg_lo:[0,1] neg_hi:[0,1]
	v_add_u32_e32 v170, 10, v169
	v_min_u32_e32 v170, s56, v170
	v_add_u32_e32 v171, -6, v169
	v_max_i32_e32 v171, 0, v171
	v_sub_u32_e32 v170, v170, v171
	v_cvt_f32_u32_e32 v170, v170
	v_rcp_f32_e32 v174, v170
	v_lshlrev_b32_e32 v132, 16, v40
	v_and_b32_e32 v133, 0xffff0000, v40
	v_lshlrev_b32_e32 v134, 16, v41
	v_and_b32_e32 v135, 0xffff0000, v41
	v_lshlrev_b32_e32 v136, 16, v42
	v_and_b32_e32 v137, 0xffff0000, v42
	v_lshlrev_b32_e32 v138, 16, v43
	v_and_b32_e32 v139, 0xffff0000, v43
	v_pk_fma_f32 v[140:141], v[124:125], v[174:175], v[132:133] op_sel_hi:[1,0,1] neg_lo:[0,0,1] neg_hi:[0,0,1]
	v_pk_fma_f32 v[142:143], v[126:127], v[174:175], v[134:135] op_sel_hi:[1,0,1] neg_lo:[0,0,1] neg_hi:[0,0,1]
	v_pk_fma_f32 v[144:145], v[128:129], v[174:175], v[136:137] op_sel_hi:[1,0,1] neg_lo:[0,0,1] neg_hi:[0,0,1]
	v_pk_fma_f32 v[146:147], v[130:131], v[174:175], v[138:139] op_sel_hi:[1,0,1] neg_lo:[0,0,1] neg_hi:[0,0,1]
	v_cvt_pk_bf16_f32 v148, v140, v141
	v_cvt_pk_bf16_f32 v149, v142, v143
	v_cvt_pk_bf16_f32 v150, v144, v145
	v_cvt_pk_bf16_f32 v151, v146, v147
	global_store_dwordx4 v168, v[148:151], s[54:55]
	v_add_u32_e32 v168, 0x800, v168
	v_lshlrev_b32_e32 v132, 16, v72
	v_and_b32_e32 v133, 0xffff0000, v72
	v_lshlrev_b32_e32 v134, 16, v73
	v_and_b32_e32 v135, 0xffff0000, v73
	v_lshlrev_b32_e32 v136, 16, v74
	v_and_b32_e32 v137, 0xffff0000, v74
	v_lshlrev_b32_e32 v138, 16, v75
	v_and_b32_e32 v139, 0xffff0000, v75
	v_lshlrev_b32_e32 v140, 16, v8
	v_and_b32_e32 v141, 0xffff0000, v8
	v_lshlrev_b32_e32 v142, 16, v9
	v_and_b32_e32 v143, 0xffff0000, v9
	v_lshlrev_b32_e32 v144, 16, v10
	v_and_b32_e32 v145, 0xffff0000, v10
	v_lshlrev_b32_e32 v146, 16, v11
	v_and_b32_e32 v147, 0xffff0000, v11
	v_pk_add_f32 v[124:125], v[124:125], v[132:133]
	v_pk_add_f32 v[126:127], v[126:127], v[134:135]
	v_pk_add_f32 v[128:129], v[128:129], v[136:137]
; __device__ __forceinline__ u32x4 pack8(const f32x4 a, const f32x4 b) { u32x4 w; w.x = cvt_pk_bf16(a[0], a[1]); w.y = cvt_pk_bf16(a[2], a[3]); w.z = cvt_pk_bf16(b[0], b[1]); w.w = cvt_pk_bf16(b[2], b[3]); return w; }
; __global__ void __launch_bounds__(512, 2) fwd_mega(Args a) {
;     ...
;             for (int s = s0; s < s0 + 32; ++s) {
;                 f32x4 u0, u1; pg8::unpack8(*(const u32x4*)(base + (size_t)s * 512), u0, u1);
;                 const int jlo = (s - hw) > 0 ? (s - hw) : 0, jhi = (s + hw) < SEQ ? (s + hw) : SEQ;
;                 const float rc = 1.0f / (float)(jhi - jlo);
;                 *(u32x4*)(obase + (size_t)s * 1024) = pg8::pack8(w0 * rc - u0, w1 * rc - u1);
;                 if (s + hw < SEQ) { f32x4 a0, a1; pg8::unpack8(*(const u32x4*)(base + (size_t)(s + hw) * 512), a0, a1); w0 += a0; w1 += a1; }
;                 if (s - hw >= 0) { f32x4 a0, a1; pg8::unpack8(*(const u32x4*)(base + (size_t)(s - hw) * 512), a0, a1); w0 -= a0; w1 -= a1; }
	v_pk_add_f32 v[130:131], v[130:131], v[138:139]
	v_pk_add_f32 v[124:125], v[124:125], v[140:141] neg_lo:[0,1] neg_hi:[0,1]
	v_pk_add_f32 v[126:127], v[126:127], v[142:143] neg_lo:[0,1] neg_hi:[0,1]
	v_pk_add_f32 v[128:129], v[128:129], v[144:145] neg_lo:[0,1] neg_hi:[0,1]
	v_pk_add_f32 v[130:131], v[130:131], v[146:147] neg_lo:[0,1] neg_hi:[0,1]
	v_add_u32_e32 v170, 11, v169
	v_min_u32_e32 v170, s56, v170
	v_add_u32_e32 v171, -5, v169
	v_max_i32_e32 v171, 0, v171
	v_sub_u32_e32 v170, v170, v171
	v_cvt_f32_u32_e32 v170, v170
	v_rcp_f32_e32 v174, v170
	v_lshlrev_b32_e32 v132, 16, v44
	v_and_b32_e32 v133, 0xffff0000, v44
	v_lshlrev_b32_e32 v134, 16, v45
	v_and_b32_e32 v135, 0xffff0000, v45
	v_lshlrev_b32_e32 v136, 16, v46
	v_and_b32_e32 v137, 0xffff0000, v46
	v_lshlrev_b32_e32 v138, 16, v47
	v_and_b32_e32 v139, 0xffff0000, v47
	v_pk_fma_f32 v[140:141], v[124:125], v[174:175], v[132:133] op_sel_hi:[1,0,1] neg_lo:[0,0,1] neg_hi:[0,0,1]
	v_pk_fma_f32 v[142:143], v[126:127], v[174:175], v[134:135] op_sel_hi:[1,0,1] neg_lo:[0,0,1] neg_hi:[0,0,1]
	v_pk_fma_f32 v[144:145], v[128:129], v[174:175], v[136:137] op_sel_hi:[1,0,1] neg_lo:[0,0,1] neg_hi:[0,0,1]
	v_pk_fma_f32 v[146:147], v[130:131], v[174:175], v[138:139] op_sel_hi:[1,0,1] neg_lo:[0,0,1] neg_hi:[0,0,1]
	v_cvt_pk_bf16_f32 v148, v140, v141
	v_cvt_pk_bf16_f32 v149, v142, v143
	v_cvt_pk_bf16_f32 v150, v144, v145
	v_cvt_pk_bf16_f32 v151, v146, v147
	global_store_dwordx4 v168, v[148:151], s[54:55]
	v_add_u32_e32 v168, 0x800, v168
	v_lshlrev_b32_e32 v132, 16, v76
	v_and_b32_e32 v133, 0xffff0000, v76
	v_lshlrev_b32_e32 v134, 16, v77
	v_and_b32_e32 v135, 0xffff0000, v77
	v_lshlrev_b32_e32 v136, 16, v78
	v_and_b32_e32 v137, 0xffff0000, v78
	v_lshlrev_b32_e32 v138, 16, v79
	v_and_b32_e32 v139, 0xffff0000, v79
	v_lshlrev_b32_e32 v140, 16, v12
	v_and_b32_e32 v141, 0xffff0000, v12
	v_lshlrev_b32_e32 v142, 16, v13
	v_and_b32_e32 v143, 0xffff0000, v13
	v_lshlrev_b32_e32 v144, 16, v14
	v_and_b32_e32 v145, 0xffff0000, v14
	v_lshlrev_b32_e32 v146, 16, v15
	v_and_b32_e32 v147, 0xffff0000, v15
	v_pk_add_f32 v[124:125], v[124:125], v[132:133]
	v_pk_add_f32 v[126:127], v[126:127], v[134:135]
	v_pk_add_f32 v[128:129], v[128:129], v[136:137]
	v_pk_add_f32 v[130:131], v[130:131], v[138:139]
	v_pk_add_f32 v[124:125], v[124:125], v[140:141] neg_lo:[0,1] neg_hi:[0,1]
	v_pk_add_f32 v[126:127], v[126:127], v[142:143] neg_lo:[0,1] neg_hi:[0,1]
	v_pk_add_f32 v[128:129], v[128:129], v[144:145] neg_lo:[0,1] neg_hi:[0,1]
	v_pk_add_f32 v[130:131], v[130:131], v[146:147] neg_lo:[0,1] neg_hi:[0,1]
	v_add_u32_e32 v170, 12, v169
	v_min_u32_e32 v170, s56, v170
	v_add_u32_e32 v171, -4, v169
	v_max_i32_e32 v171, 0, v171
	v_sub_u32_e32 v170, v170, v171
	v_cvt_f32_u32_e32 v170, v170
	v_rcp_f32_e32 v174, v170
	v_lshlrev_b32_e32 v132, 16, v48
	v_and_b32_e32 v133, 0xffff0000, v48
	v_lshlrev_b32_e32 v134, 16, v49
	v_and_b32_e32 v135, 0xffff0000, v49
	v_lshlrev_b32_e32 v136, 16, v50
	v_and_b32_e32 v137, 0xffff0000, v50
	v_lshlrev_b32_e32 v138, 16, v51
	v_and_b32_e32 v139, 0xffff0000, v51
	v_pk_fma_f32 v[140:141], v[124:125], v[174:175], v[132:133] op_sel_hi:[1,0,1] neg_lo:[0,0,1] neg_hi:[0,0,1]
	v_pk_fma_f32 v[142:143], v[126:127], v[174:175], v[134:135] op_sel_hi:[1,0,1] neg_lo:[0,0,1] neg_hi:[0,0,1]
	v_pk_fma_f32 v[144:145], v[128:129], v[174:175], v[136:137] op_sel_hi:[1,0,1] neg_lo:[0,0,1] neg_hi:[0,0,1]
	v_pk_fma_f32 v[146:147], v[130:131], v[174:175], v[138:139] op_sel_hi:[1,0,1] neg_lo:[0,0,1] neg_hi:[0,0,1]
	v_cvt_pk_bf16_f32 v148, v140, v141
	v_cvt_pk_bf16_f32 v149, v142, v143
	v_cvt_pk_bf16_f32 v150, v144, v145
	v_cvt_pk_bf16_f32 v151, v146, v147
	global_store_dwordx4 v168, v[148:151], s[54:55]
	v_add_u32_e32 v168, 0x800, v168
	v_lshlrev_b32_e32 v132, 16, v80
	v_and_b32_e32 v133, 0xffff0000, v80
	v_lshlrev_b32_e32 v134, 16, v81
	v_and_b32_e32 v135, 0xffff0000, v81
	v_lshlrev_b32_e32 v136, 16, v82
	v_and_b32_e32 v137, 0xffff0000, v82
	v_lshlrev_b32_e32 v138, 16, v83
	v_and_b32_e32 v139, 0xffff0000, v83
	v_lshlrev_b32_e32 v140, 16, v16
	v_and_b32_e32 v141, 0xffff0000, v16
	v_lshlrev_b32_e32 v142, 16, v17
	v_and_b32_e32 v143, 0xffff0000, v17
	v_lshlrev_b32_e32 v144, 16, v18
	v_and_b32_e32 v145, 0xffff0000, v18
	v_lshlrev_b32_e32 v146, 16, v19
	v_and_b32_e32 v147, 0xffff0000, v19
	v_pk_add_f32 v[124:125], v[124:125], v[132:133]
	v_pk_add_f32 v[126:127], v[126:127], v[134:135]
	v_pk_add_f32 v[128:129], v[128:129], v[136:137]
	v_pk_add_f32 v[130:131], v[130:131], v[138:139]
	v_pk_add_f32 v[124:125], v[124:125], v[140:141] neg_lo:[0,1] neg_hi:[0,1]
	v_pk_add_f32 v[126:127], v[126:127], v[142:143] neg_lo:[0,1] neg_hi:[0,1]
	v_pk_add_f32 v[128:129], v[128:129], v[144:145] neg_lo:[0,1] neg_hi:[0,1]
	v_pk_add_f32 v[130:131], v[130:131], v[146:147] neg_lo:[0,1] neg_hi:[0,1]
	v_add_u32_e32 v170, 13, v169
	v_min_u32_e32 v170, s56, v170
	v_add_u32_e32 v171, -3, v169
	v_max_i32_e32 v171, 0, v171
	v_sub_u32_e32 v170, v170, v171
	v_cvt_f32_u32_e32 v170, v170
	v_rcp_f32_e32 v174, v170
	v_lshlrev_b32_e32 v132, 16, v52
	v_and_b32_e32 v133, 0xffff0000, v52
	v_lshlrev_b32_e32 v134, 16, v53
	v_and_b32_e32 v135, 0xffff0000, v53
	v_lshlrev_b32_e32 v136, 16, v54
	v_and_b32_e32 v137, 0xffff0000, v54
	v_lshlrev_b32_e32 v138, 16, v55
	v_and_b32_e32 v139, 0xffff0000, v55
	v_pk_fma_f32 v[140:141], v[124:125], v[174:175], v[132:133] op_sel_hi:[1,0,1] neg_lo:[0,0,1] neg_hi:[0,0,1]
	v_pk_fma_f32 v[142:143], v[126:127], v[174:175], v[134:135] op_sel_hi:[1,0,1] neg_lo:[0,0,1] neg_hi:[0,0,1]
	v_pk_fma_f32 v[144:145], v[128:129], v[174:175], v[136:137] op_sel_hi:[1,0,1] neg_lo:[0,0,1] neg_hi:[0,0,1]
	v_pk_fma_f32 v[146:147], v[130:131], v[174:175], v[138:139] op_sel_hi:[1,0,1] neg_lo:[0,0,1] neg_hi:[0,0,1]
; __device__ __forceinline__ u32x4 pack8(const f32x4 a, const f32x4 b) { u32x4 w; w.x = cvt_pk_bf16(a[0], a[1]); w.y = cvt_pk_bf16(a[2], a[3]); w.z = cvt_pk_bf16(b[0], b[1]); w.w = cvt_pk_bf16(b[2], b[3]); return w; }
; __global__ void __launch_bounds__(512, 2) fwd_mega(Args a) {
;     ...
;             for (int s = s0; s < s0 + 32; ++s) {
;                 f32x4 u0, u1; pg8::unpack8(*(const u32x4*)(base + (size_t)s * 512), u0, u1);
;                 const int jlo = (s - hw) > 0 ? (s - hw) : 0, jhi = (s + hw) < SEQ ? (s + hw) : SEQ;
;                 const float rc = 1.0f / (float)(jhi - jlo);
;                 *(u32x4*)(obase + (size_t)s * 1024) = pg8::pack8(w0 * rc - u0, w1 * rc - u1);
;                 if (s + hw < SEQ) { f32x4 a0, a1; pg8::unpack8(*(const u32x4*)(base + (size_t)(s + hw) * 512), a0, a1); w0 += a0; w1 += a1; }
;                 if (s - hw >= 0) { f32x4 a0, a1; pg8::unpack8(*(const u32x4*)(base + (size_t)(s - hw) * 512), a0, a1); w0 -= a0; w1 -= a1; }
	v_cvt_pk_bf16_f32 v148, v140, v141
	v_cvt_pk_bf16_f32 v149, v142, v143
	v_cvt_pk_bf16_f32 v150, v144, v145
	v_cvt_pk_bf16_f32 v151, v146, v147
	global_store_dwordx4 v168, v[148:151], s[54:55]
	v_add_u32_e32 v168, 0x800, v168
	v_lshlrev_b32_e32 v132, 16, v84
	v_and_b32_e32 v133, 0xffff0000, v84
	v_lshlrev_b32_e32 v134, 16, v85
	v_and_b32_e32 v135, 0xffff0000, v85
	v_lshlrev_b32_e32 v136, 16, v86
	v_and_b32_e32 v137, 0xffff0000, v86
	v_lshlrev_b32_e32 v138, 16, v87
	v_and_b32_e32 v139, 0xffff0000, v87
	v_lshlrev_b32_e32 v140, 16, v20
	v_and_b32_e32 v141, 0xffff0000, v20
	v_lshlrev_b32_e32 v142, 16, v21
	v_and_b32_e32 v143, 0xffff0000, v21
	v_lshlrev_b32_e32 v144, 16, v22
	v_and_b32_e32 v145, 0xffff0000, v22
	v_lshlrev_b32_e32 v146, 16, v23
	v_and_b32_e32 v147, 0xffff0000, v23
	v_pk_add_f32 v[124:125], v[124:125], v[132:133]
	v_pk_add_f32 v[126:127], v[126:127], v[134:135]
	v_pk_add_f32 v[128:129], v[128:129], v[136:137]
	v_pk_add_f32 v[130:131], v[130:131], v[138:139]
	v_pk_add_f32 v[124:125], v[124:125], v[140:141] neg_lo:[0,1] neg_hi:[0,1]
	v_pk_add_f32 v[126:127], v[126:127], v[142:143] neg_lo:[0,1] neg_hi:[0,1]
	v_pk_add_f32 v[128:129], v[128:129], v[144:145] neg_lo:[0,1] neg_hi:[0,1]
	v_pk_add_f32 v[130:131], v[130:131], v[146:147] neg_lo:[0,1] neg_hi:[0,1]
	v_add_u32_e32 v170, 14, v169
	v_min_u32_e32 v170, s56, v170
	v_add_u32_e32 v171, -2, v169
	v_max_i32_e32 v171, 0, v171
	v_sub_u32_e32 v170, v170, v171
	v_cvt_f32_u32_e32 v170, v170
	v_rcp_f32_e32 v174, v170
	v_lshlrev_b32_e32 v132, 16, v56
	v_and_b32_e32 v133, 0xffff0000, v56
	v_lshlrev_b32_e32 v134, 16, v57
	v_and_b32_e32 v135, 0xffff0000, v57
	v_lshlrev_b32_e32 v136, 16, v58
	v_and_b32_e32 v137, 0xffff0000, v58
	v_lshlrev_b32_e32 v138, 16, v59
	v_and_b32_e32 v139, 0xffff0000, v59
	v_pk_fma_f32 v[140:141], v[124:125], v[174:175], v[132:133] op_sel_hi:[1,0,1] neg_lo:[0,0,1] neg_hi:[0,0,1]
	v_pk_fma_f32 v[142:143], v[126:127], v[174:175], v[134:135] op_sel_hi:[1,0,1] neg_lo:[0,0,1] neg_hi:[0,0,1]
	v_pk_fma_f32 v[144:145], v[128:129], v[174:175], v[136:137] op_sel_hi:[1,0,1] neg_lo:[0,0,1] neg_hi:[0,0,1]
	v_pk_fma_f32 v[146:147], v[130:131], v[174:175], v[138:139] op_sel_hi:[1,0,1] neg_lo:[0,0,1] neg_hi:[0,0,1]
	v_cvt_pk_bf16_f32 v148, v140, v141
	v_cvt_pk_bf16_f32 v149, v142, v143
	v_cvt_pk_bf16_f32 v150, v144, v145
	v_cvt_pk_bf16_f32 v151, v146, v147
	global_store_dwordx4 v168, v[148:151], s[54:55]
	v_add_u32_e32 v168, 0x800, v168
	v_lshlrev_b32_e32 v132, 16, v88
	v_and_b32_e32 v133, 0xffff0000, v88
	v_lshlrev_b32_e32 v134, 16, v89
	v_and_b32_e32 v135, 0xffff0000, v89
	v_lshlrev_b32_e32 v136, 16, v90
	v_and_b32_e32 v137, 0xffff0000, v90
	v_lshlrev_b32_e32 v138, 16, v91
	v_and_b32_e32 v139, 0xffff0000, v91
	v_lshlrev_b32_e32 v140, 16, v24
	v_and_b32_e32 v141, 0xffff0000, v24
	v_lshlrev_b32_e32 v142, 16, v25
	v_and_b32_e32 v143, 0xffff0000, v25
	v_lshlrev_b32_e32 v144, 16, v26
	v_and_b32_e32 v145, 0xffff0000, v26
	v_lshlrev_b32_e32 v146, 16, v27
	v_and_b32_e32 v147, 0xffff0000, v27
	v_pk_add_f32 v[124:125], v[124:125], v[132:133]
	v_pk_add_f32 v[126:127], v[126:127], v[134:135]
	v_pk_add_f32 v[128:129], v[128:129], v[136:137]
	v_pk_add_f32 v[130:131], v[130:131], v[138:139]
	v_pk_add_f32 v[124:125], v[124:125], v[140:141] neg_lo:[0,1] neg_hi:[0,1]
	v_pk_add_f32 v[126:127], v[126:127], v[142:143] neg_lo:[0,1] neg_hi:[0,1]
	v_pk_add_f32 v[128:129], v[128:129], v[144:145] neg_lo:[0,1] neg_hi:[0,1]
	v_pk_add_f32 v[130:131], v[130:131], v[146:147] neg_lo:[0,1] neg_hi:[0,1]
	v_add_u32_e32 v170, 15, v169
	v_min_u32_e32 v170, s56, v170
	v_add_u32_e32 v171, -1, v169
	v_max_i32_e32 v171, 0, v171
	v_sub_u32_e32 v170, v170, v171
	v_cvt_f32_u32_e32 v170, v170
	v_rcp_f32_e32 v174, v170
	v_lshlrev_b32_e32 v132, 16, v60
	v_and_b32_e32 v133, 0xffff0000, v60
	v_lshlrev_b32_e32 v134, 16, v61
	v_and_b32_e32 v135, 0xffff0000, v61
	v_lshlrev_b32_e32 v136, 16, v62
	v_and_b32_e32 v137, 0xffff0000, v62
	v_lshlrev_b32_e32 v138, 16, v63
	v_and_b32_e32 v139, 0xffff0000, v63
	v_pk_fma_f32 v[140:141], v[124:125], v[174:175], v[132:133] op_sel_hi:[1,0,1] neg_lo:[0,0,1] neg_hi:[0,0,1]
	v_pk_fma_f32 v[142:143], v[126:127], v[174:175], v[134:135] op_sel_hi:[1,0,1] neg_lo:[0,0,1] neg_hi:[0,0,1]
	v_pk_fma_f32 v[144:145], v[128:129], v[174:175], v[136:137] op_sel_hi:[1,0,1] neg_lo:[0,0,1] neg_hi:[0,0,1]
	v_pk_fma_f32 v[146:147], v[130:131], v[174:175], v[138:139] op_sel_hi:[1,0,1] neg_lo:[0,0,1] neg_hi:[0,0,1]
	v_cvt_pk_bf16_f32 v148, v140, v141
	v_cvt_pk_bf16_f32 v149, v142, v143
	v_cvt_pk_bf16_f32 v150, v144, v145
	v_cvt_pk_bf16_f32 v151, v146, v147
	global_store_dwordx4 v168, v[148:151], s[54:55]
	v_add_u32_e32 v168, 0x800, v168
	v_lshlrev_b32_e32 v132, 16, v92
	v_and_b32_e32 v133, 0xffff0000, v92
	v_lshlrev_b32_e32 v134, 16, v93
	v_and_b32_e32 v135, 0xffff0000, v93
	v_lshlrev_b32_e32 v136, 16, v94
	v_and_b32_e32 v137, 0xffff0000, v94
	v_lshlrev_b32_e32 v138, 16, v95
	v_and_b32_e32 v139, 0xffff0000, v95
	v_lshlrev_b32_e32 v140, 16, v28
	v_and_b32_e32 v141, 0xffff0000, v28
	v_lshlrev_b32_e32 v142, 16, v29
	v_and_b32_e32 v143, 0xffff0000, v29
	v_lshlrev_b32_e32 v144, 16, v30
	v_and_b32_e32 v145, 0xffff0000, v30
	v_lshlrev_b32_e32 v146, 16, v31
	v_and_b32_e32 v147, 0xffff0000, v31
	v_pk_add_f32 v[124:125], v[124:125], v[132:133]
	v_pk_add_f32 v[126:127], v[126:127], v[134:135]
	v_pk_add_f32 v[128:129], v[128:129], v[136:137]
	v_pk_add_f32 v[130:131], v[130:131], v[138:139]
	v_pk_add_f32 v[124:125], v[124:125], v[140:141] neg_lo:[0,1] neg_hi:[0,1]
	v_pk_add_f32 v[126:127], v[126:127], v[142:143] neg_lo:[0,1] neg_hi:[0,1]
	v_pk_add_f32 v[128:129], v[128:129], v[144:145] neg_lo:[0,1] neg_hi:[0,1]
; __device__ __forceinline__ u32x4 pack8(const f32x4 a, const f32x4 b) { u32x4 w; w.x = cvt_pk_bf16(a[0], a[1]); w.y = cvt_pk_bf16(a[2], a[3]); w.z = cvt_pk_bf16(b[0], b[1]); w.w = cvt_pk_bf16(b[2], b[3]); return w; }
; __global__ void __launch_bounds__(512, 2) fwd_mega(Args a) {
;     ...
;             for (int s = s0; s < s0 + 32; ++s) {
;                 f32x4 u0, u1; pg8::unpack8(*(const u32x4*)(base + (size_t)s * 512), u0, u1);
;                 const int jlo = (s - hw) > 0 ? (s - hw) : 0, jhi = (s + hw) < SEQ ? (s + hw) : SEQ;
;                 const float rc = 1.0f / (float)(jhi - jlo);
;                 *(u32x4*)(obase + (size_t)s * 1024) = pg8::pack8(w0 * rc - u0, w1 * rc - u1);
;                 if (s + hw < SEQ) { f32x4 a0, a1; pg8::unpack8(*(const u32x4*)(base + (size_t)(s + hw) * 512), a0, a1); w0 += a0; w1 += a1; }
;                 if (s - hw >= 0) { f32x4 a0, a1; pg8::unpack8(*(const u32x4*)(base + (size_t)(s - hw) * 512), a0, a1); w0 -= a0; w1 -= a1; }
	v_pk_add_f32 v[130:131], v[130:131], v[146:147] neg_lo:[0,1] neg_hi:[0,1]
	v_add_u32_e32 v170, 16, v169
	v_min_u32_e32 v170, s56, v170
	v_add_u32_e32 v171, 0, v169
	v_max_i32_e32 v171, 0, v171
	v_sub_u32_e32 v170, v170, v171
	v_cvt_f32_u32_e32 v170, v170
	v_rcp_f32_e32 v174, v170
	v_lshlrev_b32_e32 v132, 16, v64
	v_and_b32_e32 v133, 0xffff0000, v64
	v_lshlrev_b32_e32 v134, 16, v65
	v_and_b32_e32 v135, 0xffff0000, v65
	v_lshlrev_b32_e32 v136, 16, v66
	v_and_b32_e32 v137, 0xffff0000, v66
	v_lshlrev_b32_e32 v138, 16, v67
	v_and_b32_e32 v139, 0xffff0000, v67
	v_pk_fma_f32 v[140:141], v[124:125], v[174:175], v[132:133] op_sel_hi:[1,0,1] neg_lo:[0,0,1] neg_hi:[0,0,1]
	v_pk_fma_f32 v[142:143], v[126:127], v[174:175], v[134:135] op_sel_hi:[1,0,1] neg_lo:[0,0,1] neg_hi:[0,0,1]
	v_pk_fma_f32 v[144:145], v[128:129], v[174:175], v[136:137] op_sel_hi:[1,0,1] neg_lo:[0,0,1] neg_hi:[0,0,1]
	v_pk_fma_f32 v[146:147], v[130:131], v[174:175], v[138:139] op_sel_hi:[1,0,1] neg_lo:[0,0,1] neg_hi:[0,0,1]
	v_cvt_pk_bf16_f32 v148, v140, v141
	v_cvt_pk_bf16_f32 v149, v142, v143
	v_cvt_pk_bf16_f32 v150, v144, v145
	v_cvt_pk_bf16_f32 v151, v146, v147
	global_store_dwordx4 v168, v[148:151], s[54:55]
	v_add_u32_e32 v168, 0x800, v168
	v_lshlrev_b32_e32 v132, 16, v96
	v_and_b32_e32 v133, 0xffff0000, v96
	v_lshlrev_b32_e32 v134, 16, v97
	v_and_b32_e32 v135, 0xffff0000, v97
	v_lshlrev_b32_e32 v136, 16, v98
	v_and_b32_e32 v137, 0xffff0000, v98
	v_lshlrev_b32_e32 v138, 16, v99
	v_and_b32_e32 v139, 0xffff0000, v99
	v_lshlrev_b32_e32 v140, 16, v32
	v_and_b32_e32 v141, 0xffff0000, v32
	v_lshlrev_b32_e32 v142, 16, v33
	v_and_b32_e32 v143, 0xffff0000, v33
	v_lshlrev_b32_e32 v144, 16, v34
	v_and_b32_e32 v145, 0xffff0000, v34
	v_lshlrev_b32_e32 v146, 16, v35
	v_and_b32_e32 v147, 0xffff0000, v35
	v_pk_add_f32 v[124:125], v[124:125], v[132:133]
	v_pk_add_f32 v[126:127], v[126:127], v[134:135]
	v_pk_add_f32 v[128:129], v[128:129], v[136:137]
	v_pk_add_f32 v[130:131], v[130:131], v[138:139]
	v_pk_add_f32 v[124:125], v[124:125], v[140:141] neg_lo:[0,1] neg_hi:[0,1]
	v_pk_add_f32 v[126:127], v[126:127], v[142:143] neg_lo:[0,1] neg_hi:[0,1]
	v_pk_add_f32 v[128:129], v[128:129], v[144:145] neg_lo:[0,1] neg_hi:[0,1]
	v_pk_add_f32 v[130:131], v[130:131], v[146:147] neg_lo:[0,1] neg_hi:[0,1]
	v_add_u32_e32 v170, 17, v169
	v_min_u32_e32 v170, s56, v170
	v_add_u32_e32 v171, 1, v169
	v_max_i32_e32 v171, 0, v171
	v_sub_u32_e32 v170, v170, v171
	v_cvt_f32_u32_e32 v170, v170
	v_rcp_f32_e32 v174, v170
	v_lshlrev_b32_e32 v132, 16, v68
	v_and_b32_e32 v133, 0xffff0000, v68
	v_lshlrev_b32_e32 v134, 16, v69
	v_and_b32_e32 v135, 0xffff0000, v69
	v_lshlrev_b32_e32 v136, 16, v70
	v_and_b32_e32 v137, 0xffff0000, v70
	v_lshlrev_b32_e32 v138, 16, v71
	v_and_b32_e32 v139, 0xffff0000, v71
	v_pk_fma_f32 v[140:141], v[124:125], v[174:175], v[132:133] op_sel_hi:[1,0,1] neg_lo:[0,0,1] neg_hi:[0,0,1]
	v_pk_fma_f32 v[142:143], v[126:127], v[174:175], v[134:135] op_sel_hi:[1,0,1] neg_lo:[0,0,1] neg_hi:[0,0,1]
	v_pk_fma_f32 v[144:145], v[128:129], v[174:175], v[136:137] op_sel_hi:[1,0,1] neg_lo:[0,0,1] neg_hi:[0,0,1]
	v_pk_fma_f32 v[146:147], v[130:131], v[174:175], v[138:139] op_sel_hi:[1,0,1] neg_lo:[0,0,1] neg_hi:[0,0,1]
	v_cvt_pk_bf16_f32 v148, v140, v141
	v_cvt_pk_bf16_f32 v149, v142, v143
	v_cvt_pk_bf16_f32 v150, v144, v145
	v_cvt_pk_bf16_f32 v151, v146, v147
	global_store_dwordx4 v168, v[148:151], s[54:55]
	v_add_u32_e32 v168, 0x800, v168
	v_lshlrev_b32_e32 v132, 16, v100
	v_and_b32_e32 v133, 0xffff0000, v100
	v_lshlrev_b32_e32 v134, 16, v101
	v_and_b32_e32 v135, 0xffff0000, v101
	v_lshlrev_b32_e32 v136, 16, v102
	v_and_b32_e32 v137, 0xffff0000, v102
	v_lshlrev_b32_e32 v138, 16, v103
	v_and_b32_e32 v139, 0xffff0000, v103
	v_lshlrev_b32_e32 v140, 16, v36
	v_and_b32_e32 v141, 0xffff0000, v36
	v_lshlrev_b32_e32 v142, 16, v37
	v_and_b32_e32 v143, 0xffff0000, v37
	v_lshlrev_b32_e32 v144, 16, v38
	v_and_b32_e32 v145, 0xffff0000, v38
	v_lshlrev_b32_e32 v146, 16, v39
	v_and_b32_e32 v147, 0xffff0000, v39
	v_pk_add_f32 v[124:125], v[124:125], v[132:133]
	v_pk_add_f32 v[126:127], v[126:127], v[134:135]
	v_pk_add_f32 v[128:129], v[128:129], v[136:137]
	v_pk_add_f32 v[130:131], v[130:131], v[138:139]
	v_pk_add_f32 v[124:125], v[124:125], v[140:141] neg_lo:[0,1] neg_hi:[0,1]
	v_pk_add_f32 v[126:127], v[126:127], v[142:143] neg_lo:[0,1] neg_hi:[0,1]
	v_pk_add_f32 v[128:129], v[128:129], v[144:145] neg_lo:[0,1] neg_hi:[0,1]
	v_pk_add_f32 v[130:131], v[130:131], v[146:147] neg_lo:[0,1] neg_hi:[0,1]
	v_add_u32_e32 v170, 18, v169
	v_min_u32_e32 v170, s56, v170
	v_add_u32_e32 v171, 2, v169
	v_max_i32_e32 v171, 0, v171
	v_sub_u32_e32 v170, v170, v171
	v_cvt_f32_u32_e32 v170, v170
	v_rcp_f32_e32 v174, v170
	v_lshlrev_b32_e32 v132, 16, v72
	v_and_b32_e32 v133, 0xffff0000, v72
	v_lshlrev_b32_e32 v134, 16, v73
	v_and_b32_e32 v135, 0xffff0000, v73
	v_lshlrev_b32_e32 v136, 16, v74
	v_and_b32_e32 v137, 0xffff0000, v74
	v_lshlrev_b32_e32 v138, 16, v75
	v_and_b32_e32 v139, 0xffff0000, v75
	v_pk_fma_f32 v[140:141], v[124:125], v[174:175], v[132:133] op_sel_hi:[1,0,1] neg_lo:[0,0,1] neg_hi:[0,0,1]
	v_pk_fma_f32 v[142:143], v[126:127], v[174:175], v[134:135] op_sel_hi:[1,0,1] neg_lo:[0,0,1] neg_hi:[0,0,1]
	v_pk_fma_f32 v[144:145], v[128:129], v[174:175], v[136:137] op_sel_hi:[1,0,1] neg_lo:[0,0,1] neg_hi:[0,0,1]
	v_pk_fma_f32 v[146:147], v[130:131], v[174:175], v[138:139] op_sel_hi:[1,0,1] neg_lo:[0,0,1] neg_hi:[0,0,1]
	v_cvt_pk_bf16_f32 v148, v140, v141
	v_cvt_pk_bf16_f32 v149, v142, v143
	v_cvt_pk_bf16_f32 v150, v144, v145
	v_cvt_pk_bf16_f32 v151, v146, v147
	global_store_dwordx4 v168, v[148:151], s[54:55]
	v_add_u32_e32 v168, 0x800, v168
; __device__ __forceinline__ u32x4 pack8(const f32x4 a, const f32x4 b) { u32x4 w; w.x = cvt_pk_bf16(a[0], a[1]); w.y = cvt_pk_bf16(a[2], a[3]); w.z = cvt_pk_bf16(b[0], b[1]); w.w = cvt_pk_bf16(b[2], b[3]); return w; }
; __global__ void __launch_bounds__(512, 2) fwd_mega(Args a) {
;     ...
;             for (int s = s0; s < s0 + 32; ++s) {
;                 f32x4 u0, u1; pg8::unpack8(*(const u32x4*)(base + (size_t)s * 512), u0, u1);
;                 const int jlo = (s - hw) > 0 ? (s - hw) : 0, jhi = (s + hw) < SEQ ? (s + hw) : SEQ;
;                 const float rc = 1.0f / (float)(jhi - jlo);
;                 *(u32x4*)(obase + (size_t)s * 1024) = pg8::pack8(w0 * rc - u0, w1 * rc - u1);
;                 if (s + hw < SEQ) { f32x4 a0, a1; pg8::unpack8(*(const u32x4*)(base + (size_t)(s + hw) * 512), a0, a1); w0 += a0; w1 += a1; }
;                 if (s - hw >= 0) { f32x4 a0, a1; pg8::unpack8(*(const u32x4*)(base + (size_t)(s - hw) * 512), a0, a1); w0 -= a0; w1 -= a1; }
	v_lshlrev_b32_e32 v132, 16, v104
	v_and_b32_e32 v133, 0xffff0000, v104
	v_lshlrev_b32_e32 v134, 16, v105
	v_and_b32_e32 v135, 0xffff0000, v105
	v_lshlrev_b32_e32 v136, 16, v106
	v_and_b32_e32 v137, 0xffff0000, v106
	v_lshlrev_b32_e32 v138, 16, v107
	v_and_b32_e32 v139, 0xffff0000, v107
	v_lshlrev_b32_e32 v140, 16, v40
	v_and_b32_e32 v141, 0xffff0000, v40
	v_lshlrev_b32_e32 v142, 16, v41
	v_and_b32_e32 v143, 0xffff0000, v41
	v_lshlrev_b32_e32 v144, 16, v42
	v_and_b32_e32 v145, 0xffff0000, v42
	v_lshlrev_b32_e32 v146, 16, v43
	v_and_b32_e32 v147, 0xffff0000, v43
	v_pk_add_f32 v[124:125], v[124:125], v[132:133]
	v_pk_add_f32 v[126:127], v[126:127], v[134:135]
	v_pk_add_f32 v[128:129], v[128:129], v[136:137]
	v_pk_add_f32 v[130:131], v[130:131], v[138:139]
	v_pk_add_f32 v[124:125], v[124:125], v[140:141] neg_lo:[0,1] neg_hi:[0,1]
	v_pk_add_f32 v[126:127], v[126:127], v[142:143] neg_lo:[0,1] neg_hi:[0,1]
	v_pk_add_f32 v[128:129], v[128:129], v[144:145] neg_lo:[0,1] neg_hi:[0,1]
	v_pk_add_f32 v[130:131], v[130:131], v[146:147] neg_lo:[0,1] neg_hi:[0,1]
	v_add_u32_e32 v170, 19, v169
	v_min_u32_e32 v170, s56, v170
	v_add_u32_e32 v171, 3, v169
	v_max_i32_e32 v171, 0, v171
	v_sub_u32_e32 v170, v170, v171
	v_cvt_f32_u32_e32 v170, v170
	v_rcp_f32_e32 v174, v170
	v_lshlrev_b32_e32 v132, 16, v76
	v_and_b32_e32 v133, 0xffff0000, v76
	v_lshlrev_b32_e32 v134, 16, v77
	v_and_b32_e32 v135, 0xffff0000, v77
	v_lshlrev_b32_e32 v136, 16, v78
	v_and_b32_e32 v137, 0xffff0000, v78
	v_lshlrev_b32_e32 v138, 16, v79
	v_and_b32_e32 v139, 0xffff0000, v79
	v_pk_fma_f32 v[140:141], v[124:125], v[174:175], v[132:133] op_sel_hi:[1,0,1] neg_lo:[0,0,1] neg_hi:[0,0,1]
	v_pk_fma_f32 v[142:143], v[126:127], v[174:175], v[134:135] op_sel_hi:[1,0,1] neg_lo:[0,0,1] neg_hi:[0,0,1]
	v_pk_fma_f32 v[144:145], v[128:129], v[174:175], v[136:137] op_sel_hi:[1,0,1] neg_lo:[0,0,1] neg_hi:[0,0,1]
	v_pk_fma_f32 v[146:147], v[130:131], v[174:175], v[138:139] op_sel_hi:[1,0,1] neg_lo:[0,0,1] neg_hi:[0,0,1]
	v_cvt_pk_bf16_f32 v148, v140, v141
	v_cvt_pk_bf16_f32 v149, v142, v143
	v_cvt_pk_bf16_f32 v150, v144, v145
	v_cvt_pk_bf16_f32 v151, v146, v147
	global_store_dwordx4 v168, v[148:151], s[54:55]
	v_add_u32_e32 v168, 0x800, v168
	v_lshlrev_b32_e32 v132, 16, v108
	v_and_b32_e32 v133, 0xffff0000, v108
	v_lshlrev_b32_e32 v134, 16, v109
	v_and_b32_e32 v135, 0xffff0000, v109
	v_lshlrev_b32_e32 v136, 16, v110
	v_and_b32_e32 v137, 0xffff0000, v110
	v_lshlrev_b32_e32 v138, 16, v111
	v_and_b32_e32 v139, 0xffff0000, v111
	v_lshlrev_b32_e32 v140, 16, v44
	v_and_b32_e32 v141, 0xffff0000, v44
	v_lshlrev_b32_e32 v142, 16, v45
	v_and_b32_e32 v143, 0xffff0000, v45
	v_lshlrev_b32_e32 v144, 16, v46
	v_and_b32_e32 v145, 0xffff0000, v46
	v_lshlrev_b32_e32 v146, 16, v47
	v_and_b32_e32 v147, 0xffff0000, v47
	v_pk_add_f32 v[124:125], v[124:125], v[132:133]
	v_pk_add_f32 v[126:127], v[126:127], v[134:135]
	v_pk_add_f32 v[128:129], v[128:129], v[136:137]
	v_pk_add_f32 v[130:131], v[130:131], v[138:139]
	v_pk_add_f32 v[124:125], v[124:125], v[140:141] neg_lo:[0,1] neg_hi:[0,1]
	v_pk_add_f32 v[126:127], v[126:127], v[142:143] neg_lo:[0,1] neg_hi:[0,1]
	v_pk_add_f32 v[128:129], v[128:129], v[144:145] neg_lo:[0,1] neg_hi:[0,1]
	v_pk_add_f32 v[130:131], v[130:131], v[146:147] neg_lo:[0,1] neg_hi:[0,1]
	v_add_u32_e32 v170, 20, v169
	v_min_u32_e32 v170, s56, v170
	v_add_u32_e32 v171, 4, v169
	v_max_i32_e32 v171, 0, v171
	v_sub_u32_e32 v170, v170, v171
	v_cvt_f32_u32_e32 v170, v170
	v_rcp_f32_e32 v174, v170
	v_lshlrev_b32_e32 v132, 16, v80
	v_and_b32_e32 v133, 0xffff0000, v80
	v_lshlrev_b32_e32 v134, 16, v81
	v_and_b32_e32 v135, 0xffff0000, v81
	v_lshlrev_b32_e32 v136, 16, v82
	v_and_b32_e32 v137, 0xffff0000, v82
	v_lshlrev_b32_e32 v138, 16, v83
	v_and_b32_e32 v139, 0xffff0000, v83
	v_pk_fma_f32 v[140:141], v[124:125], v[174:175], v[132:133] op_sel_hi:[1,0,1] neg_lo:[0,0,1] neg_hi:[0,0,1]
	v_pk_fma_f32 v[142:143], v[126:127], v[174:175], v[134:135] op_sel_hi:[1,0,1] neg_lo:[0,0,1] neg_hi:[0,0,1]
	v_pk_fma_f32 v[144:145], v[128:129], v[174:175], v[136:137] op_sel_hi:[1,0,1] neg_lo:[0,0,1] neg_hi:[0,0,1]
	v_pk_fma_f32 v[146:147], v[130:131], v[174:175], v[138:139] op_sel_hi:[1,0,1] neg_lo:[0,0,1] neg_hi:[0,0,1]
	v_cvt_pk_bf16_f32 v148, v140, v141
	v_cvt_pk_bf16_f32 v149, v142, v143
	v_cvt_pk_bf16_f32 v150, v144, v145
	v_cvt_pk_bf16_f32 v151, v146, v147
	global_store_dwordx4 v168, v[148:151], s[54:55]
	v_add_u32_e32 v168, 0x800, v168
	v_lshlrev_b32_e32 v132, 16, v112
	v_and_b32_e32 v133, 0xffff0000, v112
	v_lshlrev_b32_e32 v134, 16, v113
	v_and_b32_e32 v135, 0xffff0000, v113
	v_lshlrev_b32_e32 v136, 16, v114
	v_and_b32_e32 v137, 0xffff0000, v114
	v_lshlrev_b32_e32 v138, 16, v115
	v_and_b32_e32 v139, 0xffff0000, v115
	v_lshlrev_b32_e32 v140, 16, v48
	v_and_b32_e32 v141, 0xffff0000, v48
	v_lshlrev_b32_e32 v142, 16, v49
	v_and_b32_e32 v143, 0xffff0000, v49
	v_lshlrev_b32_e32 v144, 16, v50
	v_and_b32_e32 v145, 0xffff0000, v50
	v_lshlrev_b32_e32 v146, 16, v51
	v_and_b32_e32 v147, 0xffff0000, v51
	v_pk_add_f32 v[124:125], v[124:125], v[132:133]
	v_pk_add_f32 v[126:127], v[126:127], v[134:135]
	v_pk_add_f32 v[128:129], v[128:129], v[136:137]
	v_pk_add_f32 v[130:131], v[130:131], v[138:139]
	v_pk_add_f32 v[124:125], v[124:125], v[140:141] neg_lo:[0,1] neg_hi:[0,1]
	v_pk_add_f32 v[126:127], v[126:127], v[142:143] neg_lo:[0,1] neg_hi:[0,1]
	v_pk_add_f32 v[128:129], v[128:129], v[144:145] neg_lo:[0,1] neg_hi:[0,1]
	v_pk_add_f32 v[130:131], v[130:131], v[146:147] neg_lo:[0,1] neg_hi:[0,1]
	v_add_u32_e32 v170, 21, v169
	v_min_u32_e32 v170, s56, v170
	v_add_u32_e32 v171, 5, v169
; __device__ __forceinline__ u32x4 pack8(const f32x4 a, const f32x4 b) { u32x4 w; w.x = cvt_pk_bf16(a[0], a[1]); w.y = cvt_pk_bf16(a[2], a[3]); w.z = cvt_pk_bf16(b[0], b[1]); w.w = cvt_pk_bf16(b[2], b[3]); return w; }
; __global__ void __launch_bounds__(512, 2) fwd_mega(Args a) {
;     ...
;         for (int item = bx * 512 + tid; item < NBATCH * 64 * 64; item += G * 512) {
;     ...
;             for (int s = s0; s < s0 + 32; ++s) {
;                 f32x4 u0, u1; pg8::unpack8(*(const u32x4*)(base + (size_t)s * 512), u0, u1);
;                 const int jlo = (s - hw) > 0 ? (s - hw) : 0, jhi = (s + hw) < SEQ ? (s + hw) : SEQ;
;                 const float rc = 1.0f / (float)(jhi - jlo);
;                 *(u32x4*)(obase + (size_t)s * 1024) = pg8::pack8(w0 * rc - u0, w1 * rc - u1);
;                 if (s + hw < SEQ) { f32x4 a0, a1; pg8::unpack8(*(const u32x4*)(base + (size_t)(s + hw) * 512), a0, a1); w0 += a0; w1 += a1; }
;                 if (s - hw >= 0) { f32x4 a0, a1; pg8::unpack8(*(const u32x4*)(base + (size_t)(s - hw) * 512), a0, a1); w0 -= a0; w1 -= a1; }
	v_max_i32_e32 v171, 0, v171
	v_sub_u32_e32 v170, v170, v171
	v_cvt_f32_u32_e32 v170, v170
	v_rcp_f32_e32 v174, v170
	v_lshlrev_b32_e32 v132, 16, v84
	v_and_b32_e32 v133, 0xffff0000, v84
	v_lshlrev_b32_e32 v134, 16, v85
	v_and_b32_e32 v135, 0xffff0000, v85
	v_lshlrev_b32_e32 v136, 16, v86
	v_and_b32_e32 v137, 0xffff0000, v86
	v_lshlrev_b32_e32 v138, 16, v87
	v_and_b32_e32 v139, 0xffff0000, v87
	v_pk_fma_f32 v[140:141], v[124:125], v[174:175], v[132:133] op_sel_hi:[1,0,1] neg_lo:[0,0,1] neg_hi:[0,0,1]
	v_pk_fma_f32 v[142:143], v[126:127], v[174:175], v[134:135] op_sel_hi:[1,0,1] neg_lo:[0,0,1] neg_hi:[0,0,1]
	v_pk_fma_f32 v[144:145], v[128:129], v[174:175], v[136:137] op_sel_hi:[1,0,1] neg_lo:[0,0,1] neg_hi:[0,0,1]
	v_pk_fma_f32 v[146:147], v[130:131], v[174:175], v[138:139] op_sel_hi:[1,0,1] neg_lo:[0,0,1] neg_hi:[0,0,1]
	v_cvt_pk_bf16_f32 v148, v140, v141
	v_cvt_pk_bf16_f32 v149, v142, v143
	v_cvt_pk_bf16_f32 v150, v144, v145
	v_cvt_pk_bf16_f32 v151, v146, v147
	global_store_dwordx4 v168, v[148:151], s[54:55]
	v_add_u32_e32 v168, 0x800, v168
	v_lshlrev_b32_e32 v132, 16, v116
	v_and_b32_e32 v133, 0xffff0000, v116
	v_lshlrev_b32_e32 v134, 16, v117
	v_and_b32_e32 v135, 0xffff0000, v117
	v_lshlrev_b32_e32 v136, 16, v118
	v_and_b32_e32 v137, 0xffff0000, v118
	v_lshlrev_b32_e32 v138, 16, v119
	v_and_b32_e32 v139, 0xffff0000, v119
	v_lshlrev_b32_e32 v140, 16, v52
	v_and_b32_e32 v141, 0xffff0000, v52
	v_lshlrev_b32_e32 v142, 16, v53
	v_and_b32_e32 v143, 0xffff0000, v53
	v_lshlrev_b32_e32 v144, 16, v54
	v_and_b32_e32 v145, 0xffff0000, v54
	v_lshlrev_b32_e32 v146, 16, v55
	v_and_b32_e32 v147, 0xffff0000, v55
	v_pk_add_f32 v[124:125], v[124:125], v[132:133]
	v_pk_add_f32 v[126:127], v[126:127], v[134:135]
	v_pk_add_f32 v[128:129], v[128:129], v[136:137]
	v_pk_add_f32 v[130:131], v[130:131], v[138:139]
	v_pk_add_f32 v[124:125], v[124:125], v[140:141] neg_lo:[0,1] neg_hi:[0,1]
	v_pk_add_f32 v[126:127], v[126:127], v[142:143] neg_lo:[0,1] neg_hi:[0,1]
	v_pk_add_f32 v[128:129], v[128:129], v[144:145] neg_lo:[0,1] neg_hi:[0,1]
	v_pk_add_f32 v[130:131], v[130:131], v[146:147] neg_lo:[0,1] neg_hi:[0,1]
	v_add_u32_e32 v170, 22, v169
	v_min_u32_e32 v170, s56, v170
	v_add_u32_e32 v171, 6, v169
	v_max_i32_e32 v171, 0, v171
	v_sub_u32_e32 v170, v170, v171
	v_cvt_f32_u32_e32 v170, v170
	v_rcp_f32_e32 v174, v170
	v_lshlrev_b32_e32 v132, 16, v88
	v_and_b32_e32 v133, 0xffff0000, v88
	v_lshlrev_b32_e32 v134, 16, v89
	v_and_b32_e32 v135, 0xffff0000, v89
	v_lshlrev_b32_e32 v136, 16, v90
	v_and_b32_e32 v137, 0xffff0000, v90
	v_lshlrev_b32_e32 v138, 16, v91
	v_and_b32_e32 v139, 0xffff0000, v91
	v_pk_fma_f32 v[140:141], v[124:125], v[174:175], v[132:133] op_sel_hi:[1,0,1] neg_lo:[0,0,1] neg_hi:[0,0,1]
	v_pk_fma_f32 v[142:143], v[126:127], v[174:175], v[134:135] op_sel_hi:[1,0,1] neg_lo:[0,0,1] neg_hi:[0,0,1]
	v_pk_fma_f32 v[144:145], v[128:129], v[174:175], v[136:137] op_sel_hi:[1,0,1] neg_lo:[0,0,1] neg_hi:[0,0,1]
	v_pk_fma_f32 v[146:147], v[130:131], v[174:175], v[138:139] op_sel_hi:[1,0,1] neg_lo:[0,0,1] neg_hi:[0,0,1]
	v_cvt_pk_bf16_f32 v148, v140, v141
	v_cvt_pk_bf16_f32 v149, v142, v143
	v_cvt_pk_bf16_f32 v150, v144, v145
	v_cvt_pk_bf16_f32 v151, v146, v147
	global_store_dwordx4 v168, v[148:151], s[54:55]
	v_add_u32_e32 v168, 0x800, v168
	v_lshlrev_b32_e32 v132, 16, v120
	v_and_b32_e32 v133, 0xffff0000, v120
	v_lshlrev_b32_e32 v134, 16, v121
	v_and_b32_e32 v135, 0xffff0000, v121
	v_lshlrev_b32_e32 v136, 16, v122
	v_and_b32_e32 v137, 0xffff0000, v122
	v_lshlrev_b32_e32 v138, 16, v123
	v_and_b32_e32 v139, 0xffff0000, v123
	v_lshlrev_b32_e32 v140, 16, v56
	v_and_b32_e32 v141, 0xffff0000, v56
	v_lshlrev_b32_e32 v142, 16, v57
	v_and_b32_e32 v143, 0xffff0000, v57
	v_lshlrev_b32_e32 v144, 16, v58
	v_and_b32_e32 v145, 0xffff0000, v58
	v_lshlrev_b32_e32 v146, 16, v59
	v_and_b32_e32 v147, 0xffff0000, v59
	v_pk_add_f32 v[124:125], v[124:125], v[132:133]
	v_pk_add_f32 v[126:127], v[126:127], v[134:135]
	v_pk_add_f32 v[128:129], v[128:129], v[136:137]
	v_pk_add_f32 v[130:131], v[130:131], v[138:139]
	v_pk_add_f32 v[124:125], v[124:125], v[140:141] neg_lo:[0,1] neg_hi:[0,1]
	v_pk_add_f32 v[126:127], v[126:127], v[142:143] neg_lo:[0,1] neg_hi:[0,1]
	v_pk_add_f32 v[128:129], v[128:129], v[144:145] neg_lo:[0,1] neg_hi:[0,1]
	v_pk_add_f32 v[130:131], v[130:131], v[146:147] neg_lo:[0,1] neg_hi:[0,1]
	v_add_u32_e32 v170, 23, v169
	v_min_u32_e32 v170, s56, v170
	v_add_u32_e32 v171, 7, v169
	v_max_i32_e32 v171, 0, v171
	v_sub_u32_e32 v170, v170, v171
	v_cvt_f32_u32_e32 v170, v170
	v_rcp_f32_e32 v174, v170
	v_lshlrev_b32_e32 v132, 16, v92
	v_and_b32_e32 v133, 0xffff0000, v92
	v_lshlrev_b32_e32 v134, 16, v93
	v_and_b32_e32 v135, 0xffff0000, v93
	v_lshlrev_b32_e32 v136, 16, v94
	v_and_b32_e32 v137, 0xffff0000, v94
	v_lshlrev_b32_e32 v138, 16, v95
	v_and_b32_e32 v139, 0xffff0000, v95
	v_pk_fma_f32 v[140:141], v[124:125], v[174:175], v[132:133] op_sel_hi:[1,0,1] neg_lo:[0,0,1] neg_hi:[0,0,1]
	v_pk_fma_f32 v[142:143], v[126:127], v[174:175], v[134:135] op_sel_hi:[1,0,1] neg_lo:[0,0,1] neg_hi:[0,0,1]
	v_pk_fma_f32 v[144:145], v[128:129], v[174:175], v[136:137] op_sel_hi:[1,0,1] neg_lo:[0,0,1] neg_hi:[0,0,1]
	v_pk_fma_f32 v[146:147], v[130:131], v[174:175], v[138:139] op_sel_hi:[1,0,1] neg_lo:[0,0,1] neg_hi:[0,0,1]
	v_cvt_pk_bf16_f32 v148, v140, v141
	v_cvt_pk_bf16_f32 v149, v142, v143
	v_cvt_pk_bf16_f32 v150, v144, v145
	v_cvt_pk_bf16_f32 v151, v146, v147
	global_store_dwordx4 v168, v[148:151], s[54:55]
	s_branch .Lpool_next
.Lpool_next:
	s_lshl_b32 s48, s34, 3
	s_add_i32 s46, s46, s48
	s_cmpk_lt_u32 s46, 0x1000
	s_cbranch_scc1 .Lpool_item
